# v46 + segment-closing wait fusion: one s_waitcnt vmcnt(N) lgkmcnt(0) with the priority raise in front, nothing between the last wait and the barrier
# speedup vs baseline: 1.0033x; 1.0009x over previous
.LBB0_393:
	s_ashr_i32 s19, s18, 31
	s_lshl_b64 s[0:1], s[18:19], 20
	s_add_u32 s20, s42, s0
	s_addc_u32 s21, s43, s1
	s_and_b64 s[0:1], s[4:5], exec
	s_cselect_b32 s7, s21, s25
	s_cselect_b32 s19, s20, s24
	s_ashr_i32 s17, s16, 31
	s_lshl_b64 s[0:1], s[16:17], 20
	s_add_u32 s22, s30, s0
	s_addc_u32 s23, s31, s1
	s_and_b64 s[0:1], s[4:5], exec
	s_cselect_b32 s17, s23, s27
	s_cselect_b32 s49, s22, s26
	s_add_u32 s24, s24, 0x80080
	s_addc_u32 s25, s25, 0
	s_add_u32 s58, s26, 0x100
	v_mov_b32_e32 v2, 0
	s_addc_u32 s59, s27, 0
	s_mov_b32 s60, -2
	v_mov_b32_e32 v3, v2
	s_waitcnt lgkmcnt(0)
	v_pk_mov_b32 v[4:5], v[2:3], v[2:3] op_sel:[0,1]
	v_pk_mov_b32 v[6:7], v[2:3], v[2:3] op_sel:[0,1]
	v_pk_mov_b32 v[8:9], v[2:3], v[2:3] op_sel:[0,1]
	v_pk_mov_b32 v[18:19], v[2:3], v[2:3] op_sel:[0,1]
	v_pk_mov_b32 v[20:21], v[2:3], v[2:3] op_sel:[0,1]
	v_pk_mov_b32 v[22:23], v[2:3], v[2:3] op_sel:[0,1]
	v_pk_mov_b32 v[24:25], v[2:3], v[2:3] op_sel:[0,1]
	v_pk_mov_b32 v[34:35], v[2:3], v[2:3] op_sel:[0,1]
	v_pk_mov_b32 v[36:37], v[2:3], v[2:3] op_sel:[0,1]
	v_pk_mov_b32 v[38:39], v[2:3], v[2:3] op_sel:[0,1]
	v_pk_mov_b32 v[40:41], v[2:3], v[2:3] op_sel:[0,1]
	v_pk_mov_b32 v[50:51], v[2:3], v[2:3] op_sel:[0,1]
	v_pk_mov_b32 v[52:53], v[2:3], v[2:3] op_sel:[0,1]
	v_pk_mov_b32 v[54:55], v[2:3], v[2:3] op_sel:[0,1]
	v_pk_mov_b32 v[56:57], v[2:3], v[2:3] op_sel:[0,1]
	v_pk_mov_b32 v[10:11], v[2:3], v[2:3] op_sel:[0,1]
	v_pk_mov_b32 v[12:13], v[2:3], v[2:3] op_sel:[0,1]
	v_pk_mov_b32 v[14:15], v[2:3], v[2:3] op_sel:[0,1]
	v_pk_mov_b32 v[16:17], v[2:3], v[2:3] op_sel:[0,1]
	v_pk_mov_b32 v[26:27], v[2:3], v[2:3] op_sel:[0,1]
	v_pk_mov_b32 v[28:29], v[2:3], v[2:3] op_sel:[0,1]
	v_pk_mov_b32 v[30:31], v[2:3], v[2:3] op_sel:[0,1]
	v_pk_mov_b32 v[32:33], v[2:3], v[2:3] op_sel:[0,1]
	v_pk_mov_b32 v[42:43], v[2:3], v[2:3] op_sel:[0,1]
	v_pk_mov_b32 v[44:45], v[2:3], v[2:3] op_sel:[0,1]
	v_pk_mov_b32 v[46:47], v[2:3], v[2:3] op_sel:[0,1]
	v_pk_mov_b32 v[48:49], v[2:3], v[2:3] op_sel:[0,1]
	v_pk_mov_b32 v[58:59], v[2:3], v[2:3] op_sel:[0,1]
	v_pk_mov_b32 v[60:61], v[2:3], v[2:3] op_sel:[0,1]
	v_pk_mov_b32 v[62:63], v[2:3], v[2:3] op_sel:[0,1]
	v_pk_mov_b32 v[64:65], v[2:3], v[2:3] op_sel:[0,1]
	v_pk_mov_b32 v[66:67], v[2:3], v[2:3] op_sel:[0,1]
	v_pk_mov_b32 v[68:69], v[2:3], v[2:3] op_sel:[0,1]
	v_pk_mov_b32 v[70:71], v[2:3], v[2:3] op_sel:[0,1]
	v_pk_mov_b32 v[72:73], v[2:3], v[2:3] op_sel:[0,1]
	v_pk_mov_b32 v[82:83], v[2:3], v[2:3] op_sel:[0,1]
	v_pk_mov_b32 v[84:85], v[2:3], v[2:3] op_sel:[0,1]
	v_pk_mov_b32 v[86:87], v[2:3], v[2:3] op_sel:[0,1]
	v_pk_mov_b32 v[88:89], v[2:3], v[2:3] op_sel:[0,1]
	v_pk_mov_b32 v[98:99], v[2:3], v[2:3] op_sel:[0,1]
	v_pk_mov_b32 v[100:101], v[2:3], v[2:3] op_sel:[0,1]
	v_pk_mov_b32 v[102:103], v[2:3], v[2:3] op_sel:[0,1]
	v_pk_mov_b32 v[104:105], v[2:3], v[2:3] op_sel:[0,1]
	v_pk_mov_b32 v[114:115], v[2:3], v[2:3] op_sel:[0,1]
	v_pk_mov_b32 v[116:117], v[2:3], v[2:3] op_sel:[0,1]
	v_pk_mov_b32 v[118:119], v[2:3], v[2:3] op_sel:[0,1]
	v_pk_mov_b32 v[120:121], v[2:3], v[2:3] op_sel:[0,1]
	v_pk_mov_b32 v[74:75], v[2:3], v[2:3] op_sel:[0,1]
	v_pk_mov_b32 v[76:77], v[2:3], v[2:3] op_sel:[0,1]
	v_pk_mov_b32 v[78:79], v[2:3], v[2:3] op_sel:[0,1]
	v_pk_mov_b32 v[80:81], v[2:3], v[2:3] op_sel:[0,1]
	v_pk_mov_b32 v[90:91], v[2:3], v[2:3] op_sel:[0,1]
	v_pk_mov_b32 v[92:93], v[2:3], v[2:3] op_sel:[0,1]
	v_pk_mov_b32 v[94:95], v[2:3], v[2:3] op_sel:[0,1]
	v_pk_mov_b32 v[96:97], v[2:3], v[2:3] op_sel:[0,1]
	v_pk_mov_b32 v[106:107], v[2:3], v[2:3] op_sel:[0,1]
	v_pk_mov_b32 v[108:109], v[2:3], v[2:3] op_sel:[0,1]
	v_pk_mov_b32 v[110:111], v[2:3], v[2:3] op_sel:[0,1]
	v_pk_mov_b32 v[112:113], v[2:3], v[2:3] op_sel:[0,1]
	v_pk_mov_b32 v[122:123], v[2:3], v[2:3] op_sel:[0,1]
	v_pk_mov_b32 v[124:125], v[2:3], v[2:3] op_sel:[0,1]
	v_pk_mov_b32 v[126:127], v[2:3], v[2:3] op_sel:[0,1]
	v_pk_mov_b32 v[128:129], v[2:3], v[2:3] op_sel:[0,1]
	s_cmp_eq_u32 s101, 0x80000001
	s_cbranch_scc0 .LBB0_394
	s_add_u32 s0, s24, 0xfff80080
	s_addc_u32 s1, s25, -1
	s_add_i32 s33, 0, 0x10000
	s_cmp_eq_u32 s60, 28
	s_cselect_b32 s29, s7, s1
	s_cselect_b32 s28, s19, s0
	s_cselect_b32 s27, s17, s59
	s_cselect_b32 s26, s49, s58
	s_add_i32 s55, 0, 0x14000
	ds_read_b128 v[142:145], v151
	ds_read_b128 v[146:149], v151 offset:1024
	ds_read_b128 v[154:157], v151 offset:2048
	ds_read_b128 v[158:161], v151 offset:3072
	ds_read_b128 v[162:165], v151 offset:16384
	ds_read_b128 v[166:169], v151 offset:17408
	ds_read_b128 v[170:173], v151 offset:18432
	ds_read_b128 v[174:177], v151 offset:19456
	s_add_i32 m0, s9, 0xc000
	ds_read_b128 v[178:181], v153
	ds_read_b128 v[182:185], v153 offset:1024
	ds_read_b128 v[186:189], v153 offset:2048
	ds_read_b128 v[190:193], v153 offset:3072
	ds_read_b128 v[194:197], v153 offset:4096
	ds_read_b128 v[198:201], v153 offset:5120
	ds_read_b128 v[208:211], v153 offset:6144
	ds_read_b128 v[212:215], v153 offset:7168
	global_load_lds_dwordx4 v138, s[24:25]
	s_add_i32 m0, s9, 0xe000
	s_nop 0
	global_load_lds_dwordx4 v140, s[24:25]
	s_setprio 1
	s_waitcnt vmcnt(24) lgkmcnt(0)
	s_barrier
	v_mfma_f32_16x16x32_bf16 v[126:129], v[142:145], v[178:181], v[126:129]
	v_mfma_f32_16x16x32_bf16 v[122:125], v[154:157], v[178:181], v[122:125]
	v_mfma_f32_16x16x32_bf16 v[110:113], v[142:145], v[186:189], v[110:113]
	v_mfma_f32_16x16x32_bf16 v[106:109], v[154:157], v[186:189], v[106:109]
	v_mfma_f32_16x16x32_bf16 v[94:97], v[142:145], v[194:197], v[94:97]
	v_mfma_f32_16x16x32_bf16 v[90:93], v[154:157], v[194:197], v[90:93]
	v_mfma_f32_16x16x32_bf16 v[78:81], v[142:145], v[208:211], v[78:81]
	v_mfma_f32_16x16x32_bf16 v[74:77], v[154:157], v[208:211], v[74:77]
	v_mfma_f32_16x16x32_bf16 v[126:129], v[146:149], v[182:185], v[126:129]
	v_mfma_f32_16x16x32_bf16 v[122:125], v[158:161], v[182:185], v[122:125]
	v_mfma_f32_16x16x32_bf16 v[110:113], v[146:149], v[190:193], v[110:113]
	v_mfma_f32_16x16x32_bf16 v[106:109], v[158:161], v[190:193], v[106:109]
	v_mfma_f32_16x16x32_bf16 v[94:97], v[146:149], v[198:201], v[94:97]
	v_mfma_f32_16x16x32_bf16 v[90:93], v[158:161], v[198:201], v[90:93]
	v_mfma_f32_16x16x32_bf16 v[78:81], v[146:149], v[212:215], v[78:81]
	v_mfma_f32_16x16x32_bf16 v[74:77], v[158:161], v[212:215], v[74:77]
	v_mfma_f32_16x16x32_bf16 v[118:121], v[162:165], v[178:181], v[118:121]
	v_mfma_f32_16x16x32_bf16 v[114:117], v[170:173], v[178:181], v[114:117]
	v_mfma_f32_16x16x32_bf16 v[102:105], v[162:165], v[186:189], v[102:105]
	v_mfma_f32_16x16x32_bf16 v[98:101], v[170:173], v[186:189], v[98:101]
	v_mfma_f32_16x16x32_bf16 v[86:89], v[162:165], v[194:197], v[86:89]
	v_mfma_f32_16x16x32_bf16 v[82:85], v[170:173], v[194:197], v[82:85]
	v_mfma_f32_16x16x32_bf16 v[70:73], v[162:165], v[208:211], v[70:73]
	v_mfma_f32_16x16x32_bf16 v[66:69], v[170:173], v[208:211], v[66:69]
	v_mfma_f32_16x16x32_bf16 v[118:121], v[166:169], v[182:185], v[118:121]
	v_mfma_f32_16x16x32_bf16 v[114:117], v[174:177], v[182:185], v[114:117]
	v_mfma_f32_16x16x32_bf16 v[102:105], v[166:169], v[190:193], v[102:105]
	v_mfma_f32_16x16x32_bf16 v[98:101], v[174:177], v[190:193], v[98:101]
	v_mfma_f32_16x16x32_bf16 v[86:89], v[166:169], v[198:201], v[86:89]
	v_mfma_f32_16x16x32_bf16 v[82:85], v[174:177], v[198:201], v[82:85]
	v_mfma_f32_16x16x32_bf16 v[70:73], v[166:169], v[212:215], v[70:73]
	v_mfma_f32_16x16x32_bf16 v[66:69], v[174:177], v[212:215], v[66:69]
	s_barrier
	s_setprio 0
	s_add_i32 s0, s33, s34
	s_mov_b32 m0, s0
	ds_read_b128 v[178:181], v153 offset:16384
	ds_read_b128 v[182:185], v153 offset:17408
	ds_read_b128 v[186:189], v153 offset:18432
	ds_read_b128 v[190:193], v153 offset:19456
	ds_read_b128 v[194:197], v153 offset:20480
	ds_read_b128 v[198:201], v153 offset:21504
	ds_read_b128 v[208:211], v153 offset:22528
	ds_read_b128 v[212:215], v153 offset:23552
	global_load_lds_dwordx4 v132, s[26:27]
	s_add_i32 m0, s0, 0x2000
	s_add_u32 s0, s26, 0x80000
	s_addc_u32 s1, s27, 0
	s_add_i32 s33, s55, s34
	global_load_lds_dwordx4 v136, s[26:27]
	s_mov_b32 m0, s33
	s_nop 0
	global_load_lds_dwordx4 v132, s[0:1]
	s_add_i32 m0, s33, 0x2000
	s_nop 0
	global_load_lds_dwordx4 v136, s[0:1]
	s_mov_b32 m0, s9
	s_nop 0
	global_load_lds_dwordx4 v130, s[28:29]
	s_mov_b32 m0, s35
	s_nop 0
	global_load_lds_dwordx4 v134, s[28:29]
	s_setprio 1
	s_waitcnt vmcnt(24) lgkmcnt(0)
	s_barrier
	v_mfma_f32_16x16x32_bf16 v[62:65], v[142:145], v[178:181], v[62:65]
	v_mfma_f32_16x16x32_bf16 v[58:61], v[154:157], v[178:181], v[58:61]
	v_mfma_f32_16x16x32_bf16 v[46:49], v[142:145], v[186:189], v[46:49]
	v_mfma_f32_16x16x32_bf16 v[42:45], v[154:157], v[186:189], v[42:45]
	v_mfma_f32_16x16x32_bf16 v[30:33], v[142:145], v[194:197], v[30:33]
	v_mfma_f32_16x16x32_bf16 v[26:29], v[154:157], v[194:197], v[26:29]
	v_mfma_f32_16x16x32_bf16 v[14:17], v[142:145], v[208:211], v[14:17]
	v_mfma_f32_16x16x32_bf16 v[10:13], v[154:157], v[208:211], v[10:13]
	v_mfma_f32_16x16x32_bf16 v[62:65], v[146:149], v[182:185], v[62:65]
	v_mfma_f32_16x16x32_bf16 v[58:61], v[158:161], v[182:185], v[58:61]
	v_mfma_f32_16x16x32_bf16 v[46:49], v[146:149], v[190:193], v[46:49]
	v_mfma_f32_16x16x32_bf16 v[42:45], v[158:161], v[190:193], v[42:45]
	v_mfma_f32_16x16x32_bf16 v[30:33], v[146:149], v[198:201], v[30:33]
	v_mfma_f32_16x16x32_bf16 v[26:29], v[158:161], v[198:201], v[26:29]
	v_mfma_f32_16x16x32_bf16 v[14:17], v[146:149], v[212:215], v[14:17]
	v_mfma_f32_16x16x32_bf16 v[10:13], v[158:161], v[212:215], v[10:13]
	v_mfma_f32_16x16x32_bf16 v[54:57], v[162:165], v[178:181], v[54:57]
	v_mfma_f32_16x16x32_bf16 v[50:53], v[170:173], v[178:181], v[50:53]
	v_mfma_f32_16x16x32_bf16 v[38:41], v[162:165], v[186:189], v[38:41]
	v_mfma_f32_16x16x32_bf16 v[34:37], v[170:173], v[186:189], v[34:37]
	v_mfma_f32_16x16x32_bf16 v[22:25], v[162:165], v[194:197], v[22:25]
	v_mfma_f32_16x16x32_bf16 v[18:21], v[170:173], v[194:197], v[18:21]
	v_mfma_f32_16x16x32_bf16 v[6:9], v[162:165], v[208:211], v[6:9]
	v_mfma_f32_16x16x32_bf16 v[2:5], v[170:173], v[208:211], v[2:5]
	v_mfma_f32_16x16x32_bf16 v[54:57], v[166:169], v[182:185], v[54:57]
	v_mfma_f32_16x16x32_bf16 v[50:53], v[174:177], v[182:185], v[50:53]
	v_mfma_f32_16x16x32_bf16 v[38:41], v[166:169], v[190:193], v[38:41]
	v_mfma_f32_16x16x32_bf16 v[34:37], v[174:177], v[190:193], v[34:37]
	v_mfma_f32_16x16x32_bf16 v[22:25], v[166:169], v[198:201], v[22:25]
	v_mfma_f32_16x16x32_bf16 v[18:21], v[174:177], v[198:201], v[18:21]
	v_mfma_f32_16x16x32_bf16 v[6:9], v[166:169], v[212:215], v[6:9]
	v_mfma_f32_16x16x32_bf16 v[2:5], v[174:177], v[212:215], v[2:5]
	s_barrier
	s_setprio 0
	s_branch .Lpeel_mid_0
.LBB0_394:
	s_add_u32 s0, s24, 0xfff80080
	s_addc_u32 s1, s25, -1
	s_add_i32 s33, 0, 0x10000
	s_cmp_eq_u32 s60, 28
	s_cselect_b32 s29, s7, s1
	s_cselect_b32 s28, s19, s0
	s_cselect_b32 s27, s17, s59
	s_cselect_b32 s26, s49, s58
	s_add_i32 s55, 0, 0x14000
	ds_read_b128 v[142:145], v151
	ds_read_b128 v[146:149], v151 offset:1024
	ds_read_b128 v[154:157], v151 offset:2048
	ds_read_b128 v[158:161], v151 offset:3072
	ds_read_b128 v[162:165], v151 offset:16384
	ds_read_b128 v[166:169], v151 offset:17408
	ds_read_b128 v[170:173], v151 offset:18432
	ds_read_b128 v[174:177], v151 offset:19456
	s_add_i32 m0, s9, 0xc000
	ds_read_b128 v[178:181], v153
	ds_read_b128 v[182:185], v153 offset:1024
	ds_read_b128 v[186:189], v153 offset:2048
	ds_read_b128 v[190:193], v153 offset:3072
	ds_read_b128 v[194:197], v153 offset:4096
	ds_read_b128 v[198:201], v153 offset:5120
	ds_read_b128 v[208:211], v153 offset:6144
	ds_read_b128 v[212:215], v153 offset:7168
	global_load_lds_dwordx4 v138, s[24:25]
	s_add_i32 m0, s9, 0xe000
	s_nop 0
	global_load_lds_dwordx4 v140, s[24:25]
	s_setprio 1
	s_waitcnt vmcnt(8) lgkmcnt(0)
	s_barrier
	v_mfma_f32_16x16x32_bf16 v[126:129], v[142:145], v[178:181], v[126:129]
	v_mfma_f32_16x16x32_bf16 v[122:125], v[154:157], v[178:181], v[122:125]
	v_mfma_f32_16x16x32_bf16 v[110:113], v[142:145], v[186:189], v[110:113]
	v_mfma_f32_16x16x32_bf16 v[106:109], v[154:157], v[186:189], v[106:109]
	v_mfma_f32_16x16x32_bf16 v[94:97], v[142:145], v[194:197], v[94:97]
	v_mfma_f32_16x16x32_bf16 v[90:93], v[154:157], v[194:197], v[90:93]
	v_mfma_f32_16x16x32_bf16 v[78:81], v[142:145], v[208:211], v[78:81]
	v_mfma_f32_16x16x32_bf16 v[74:77], v[154:157], v[208:211], v[74:77]
	v_mfma_f32_16x16x32_bf16 v[126:129], v[146:149], v[182:185], v[126:129]
	v_mfma_f32_16x16x32_bf16 v[122:125], v[158:161], v[182:185], v[122:125]
	v_mfma_f32_16x16x32_bf16 v[110:113], v[146:149], v[190:193], v[110:113]
	v_mfma_f32_16x16x32_bf16 v[106:109], v[158:161], v[190:193], v[106:109]
	v_mfma_f32_16x16x32_bf16 v[94:97], v[146:149], v[198:201], v[94:97]
	v_mfma_f32_16x16x32_bf16 v[90:93], v[158:161], v[198:201], v[90:93]
	v_mfma_f32_16x16x32_bf16 v[78:81], v[146:149], v[212:215], v[78:81]
	v_mfma_f32_16x16x32_bf16 v[74:77], v[158:161], v[212:215], v[74:77]
	v_mfma_f32_16x16x32_bf16 v[118:121], v[162:165], v[178:181], v[118:121]
	v_mfma_f32_16x16x32_bf16 v[114:117], v[170:173], v[178:181], v[114:117]
	v_mfma_f32_16x16x32_bf16 v[102:105], v[162:165], v[186:189], v[102:105]
	v_mfma_f32_16x16x32_bf16 v[98:101], v[170:173], v[186:189], v[98:101]
	v_mfma_f32_16x16x32_bf16 v[86:89], v[162:165], v[194:197], v[86:89]
	v_mfma_f32_16x16x32_bf16 v[82:85], v[170:173], v[194:197], v[82:85]
	v_mfma_f32_16x16x32_bf16 v[70:73], v[162:165], v[208:211], v[70:73]
	v_mfma_f32_16x16x32_bf16 v[66:69], v[170:173], v[208:211], v[66:69]
	v_mfma_f32_16x16x32_bf16 v[118:121], v[166:169], v[182:185], v[118:121]
	v_mfma_f32_16x16x32_bf16 v[114:117], v[174:177], v[182:185], v[114:117]
	v_mfma_f32_16x16x32_bf16 v[102:105], v[166:169], v[190:193], v[102:105]
	v_mfma_f32_16x16x32_bf16 v[98:101], v[174:177], v[190:193], v[98:101]
	v_mfma_f32_16x16x32_bf16 v[86:89], v[166:169], v[198:201], v[86:89]
	v_mfma_f32_16x16x32_bf16 v[82:85], v[174:177], v[198:201], v[82:85]
	v_mfma_f32_16x16x32_bf16 v[70:73], v[166:169], v[212:215], v[70:73]
	v_mfma_f32_16x16x32_bf16 v[66:69], v[174:177], v[212:215], v[66:69]
	s_barrier
	s_setprio 0
	s_add_i32 s0, s33, s34
	s_mov_b32 m0, s0
	ds_read_b128 v[178:181], v153 offset:16384
	ds_read_b128 v[182:185], v153 offset:17408
	ds_read_b128 v[186:189], v153 offset:18432
	ds_read_b128 v[190:193], v153 offset:19456
	ds_read_b128 v[194:197], v153 offset:20480
	ds_read_b128 v[198:201], v153 offset:21504
	ds_read_b128 v[208:211], v153 offset:22528
	ds_read_b128 v[212:215], v153 offset:23552
	global_load_lds_dwordx4 v132, s[26:27]
	s_add_i32 m0, s0, 0x2000
	s_add_u32 s0, s26, 0x80000
	s_addc_u32 s1, s27, 0
	s_add_i32 s33, s55, s34
	global_load_lds_dwordx4 v136, s[26:27]
	s_mov_b32 m0, s33
	s_nop 0
	global_load_lds_dwordx4 v132, s[0:1]
	s_add_i32 m0, s33, 0x2000
	s_nop 0
	global_load_lds_dwordx4 v136, s[0:1]
	s_mov_b32 m0, s9
	s_nop 0
	global_load_lds_dwordx4 v130, s[28:29]
	s_mov_b32 m0, s35
	s_nop 0
	global_load_lds_dwordx4 v134, s[28:29]
	s_setprio 1
	s_waitcnt vmcnt(8) lgkmcnt(0)
	s_barrier
	v_mfma_f32_16x16x32_bf16 v[62:65], v[142:145], v[178:181], v[62:65]
	v_mfma_f32_16x16x32_bf16 v[58:61], v[154:157], v[178:181], v[58:61]
	v_mfma_f32_16x16x32_bf16 v[46:49], v[142:145], v[186:189], v[46:49]
	v_mfma_f32_16x16x32_bf16 v[42:45], v[154:157], v[186:189], v[42:45]
	v_mfma_f32_16x16x32_bf16 v[30:33], v[142:145], v[194:197], v[30:33]
	v_mfma_f32_16x16x32_bf16 v[26:29], v[154:157], v[194:197], v[26:29]
	v_mfma_f32_16x16x32_bf16 v[14:17], v[142:145], v[208:211], v[14:17]
	v_mfma_f32_16x16x32_bf16 v[10:13], v[154:157], v[208:211], v[10:13]
	v_mfma_f32_16x16x32_bf16 v[62:65], v[146:149], v[182:185], v[62:65]
	v_mfma_f32_16x16x32_bf16 v[58:61], v[158:161], v[182:185], v[58:61]
	v_mfma_f32_16x16x32_bf16 v[46:49], v[146:149], v[190:193], v[46:49]
	v_mfma_f32_16x16x32_bf16 v[42:45], v[158:161], v[190:193], v[42:45]
	v_mfma_f32_16x16x32_bf16 v[30:33], v[146:149], v[198:201], v[30:33]
	v_mfma_f32_16x16x32_bf16 v[26:29], v[158:161], v[198:201], v[26:29]
	v_mfma_f32_16x16x32_bf16 v[14:17], v[146:149], v[212:215], v[14:17]
	v_mfma_f32_16x16x32_bf16 v[10:13], v[158:161], v[212:215], v[10:13]
	v_mfma_f32_16x16x32_bf16 v[54:57], v[162:165], v[178:181], v[54:57]
	v_mfma_f32_16x16x32_bf16 v[50:53], v[170:173], v[178:181], v[50:53]
	v_mfma_f32_16x16x32_bf16 v[38:41], v[162:165], v[186:189], v[38:41]
	v_mfma_f32_16x16x32_bf16 v[34:37], v[170:173], v[186:189], v[34:37]
	v_mfma_f32_16x16x32_bf16 v[22:25], v[162:165], v[194:197], v[22:25]
	v_mfma_f32_16x16x32_bf16 v[18:21], v[170:173], v[194:197], v[18:21]
	v_mfma_f32_16x16x32_bf16 v[6:9], v[162:165], v[208:211], v[6:9]
	v_mfma_f32_16x16x32_bf16 v[2:5], v[170:173], v[208:211], v[2:5]
	v_mfma_f32_16x16x32_bf16 v[54:57], v[166:169], v[182:185], v[54:57]
	v_mfma_f32_16x16x32_bf16 v[50:53], v[174:177], v[182:185], v[50:53]
	v_mfma_f32_16x16x32_bf16 v[38:41], v[166:169], v[190:193], v[38:41]
	v_mfma_f32_16x16x32_bf16 v[34:37], v[174:177], v[190:193], v[34:37]
	v_mfma_f32_16x16x32_bf16 v[22:25], v[166:169], v[198:201], v[22:25]
	v_mfma_f32_16x16x32_bf16 v[18:21], v[174:177], v[198:201], v[18:21]
	v_mfma_f32_16x16x32_bf16 v[6:9], v[166:169], v[212:215], v[6:9]
	v_mfma_f32_16x16x32_bf16 v[2:5], v[174:177], v[212:215], v[2:5]
	s_barrier
	s_setprio 0
.Lpeel_mid_0:
	s_add_i32 s33, 0, 0x18000
	s_add_i32 s55, 0, 0x1c000
	ds_read_b128 v[142:145], v151 offset:32768
	ds_read_b128 v[146:149], v151 offset:33792
	ds_read_b128 v[154:157], v151 offset:34816
	ds_read_b128 v[158:161], v151 offset:35840
	ds_read_b128 v[162:165], v151 offset:49152
	ds_read_b128 v[166:169], v151 offset:50176
	ds_read_b128 v[170:173], v151 offset:51200
	ds_read_b128 v[174:177], v151 offset:52224
	s_add_u32 s0, s28, 0x80000
	s_addc_u32 s1, s29, 0
	s_mov_b32 m0, s36
	ds_read_b128 v[178:181], v153 offset:32768
	ds_read_b128 v[182:185], v153 offset:33792
	ds_read_b128 v[186:189], v153 offset:34816
	ds_read_b128 v[190:193], v153 offset:35840
	ds_read_b128 v[194:197], v153 offset:36864
	ds_read_b128 v[198:201], v153 offset:37888
	ds_read_b128 v[208:211], v153 offset:38912
	ds_read_b128 v[212:215], v153 offset:39936
	global_load_lds_dwordx4 v130, s[0:1]
	s_mov_b32 m0, s37
	s_nop 0
	global_load_lds_dwordx4 v134, s[0:1]
	s_setprio 1
	s_waitcnt vmcnt(8) lgkmcnt(0)
	s_barrier
	v_mfma_f32_16x16x32_bf16 v[126:129], v[142:145], v[178:181], v[126:129]
	v_mfma_f32_16x16x32_bf16 v[122:125], v[154:157], v[178:181], v[122:125]
	v_mfma_f32_16x16x32_bf16 v[110:113], v[142:145], v[186:189], v[110:113]
	v_mfma_f32_16x16x32_bf16 v[106:109], v[154:157], v[186:189], v[106:109]
	v_mfma_f32_16x16x32_bf16 v[94:97], v[142:145], v[194:197], v[94:97]
	v_mfma_f32_16x16x32_bf16 v[90:93], v[154:157], v[194:197], v[90:93]
	v_mfma_f32_16x16x32_bf16 v[78:81], v[142:145], v[208:211], v[78:81]
	v_mfma_f32_16x16x32_bf16 v[74:77], v[154:157], v[208:211], v[74:77]
	v_mfma_f32_16x16x32_bf16 v[126:129], v[146:149], v[182:185], v[126:129]
	v_mfma_f32_16x16x32_bf16 v[122:125], v[158:161], v[182:185], v[122:125]
	v_mfma_f32_16x16x32_bf16 v[110:113], v[146:149], v[190:193], v[110:113]
	v_mfma_f32_16x16x32_bf16 v[106:109], v[158:161], v[190:193], v[106:109]
	v_mfma_f32_16x16x32_bf16 v[94:97], v[146:149], v[198:201], v[94:97]
	v_mfma_f32_16x16x32_bf16 v[90:93], v[158:161], v[198:201], v[90:93]
	v_mfma_f32_16x16x32_bf16 v[78:81], v[146:149], v[212:215], v[78:81]
	v_mfma_f32_16x16x32_bf16 v[74:77], v[158:161], v[212:215], v[74:77]
	v_mfma_f32_16x16x32_bf16 v[118:121], v[162:165], v[178:181], v[118:121]
	v_mfma_f32_16x16x32_bf16 v[114:117], v[170:173], v[178:181], v[114:117]
	v_mfma_f32_16x16x32_bf16 v[102:105], v[162:165], v[186:189], v[102:105]
	v_mfma_f32_16x16x32_bf16 v[98:101], v[170:173], v[186:189], v[98:101]
	v_mfma_f32_16x16x32_bf16 v[86:89], v[162:165], v[194:197], v[86:89]
	v_mfma_f32_16x16x32_bf16 v[82:85], v[170:173], v[194:197], v[82:85]
	v_mfma_f32_16x16x32_bf16 v[70:73], v[162:165], v[208:211], v[70:73]
	v_mfma_f32_16x16x32_bf16 v[66:69], v[170:173], v[208:211], v[66:69]
	v_mfma_f32_16x16x32_bf16 v[118:121], v[166:169], v[182:185], v[118:121]
	v_mfma_f32_16x16x32_bf16 v[114:117], v[174:177], v[182:185], v[114:117]
	v_mfma_f32_16x16x32_bf16 v[102:105], v[166:169], v[190:193], v[102:105]
	v_mfma_f32_16x16x32_bf16 v[98:101], v[174:177], v[190:193], v[98:101]
	v_mfma_f32_16x16x32_bf16 v[86:89], v[166:169], v[198:201], v[86:89]
	v_mfma_f32_16x16x32_bf16 v[82:85], v[174:177], v[198:201], v[82:85]
	v_mfma_f32_16x16x32_bf16 v[70:73], v[166:169], v[212:215], v[70:73]
	v_mfma_f32_16x16x32_bf16 v[66:69], v[174:177], v[212:215], v[66:69]
	s_barrier
	s_setprio 0
	s_add_i32 s0, s33, s34
	s_add_u32 s100, s26, 0x80
	s_addc_u32 s101, s27, 0
	s_mov_b32 m0, s0
	ds_read_b128 v[178:181], v153 offset:49152
	ds_read_b128 v[182:185], v153 offset:50176
	ds_read_b128 v[186:189], v153 offset:51200
	ds_read_b128 v[190:193], v153 offset:52224
	ds_read_b128 v[194:197], v153 offset:53248
	ds_read_b128 v[198:201], v153 offset:54272
	ds_read_b128 v[208:211], v153 offset:55296
	ds_read_b128 v[212:215], v153 offset:56320
	global_load_lds_dwordx4 v132, s[100:101]
	s_add_i32 m0, s0, 0x2000
	s_add_u32 s100, s26, 0x80
	s_addc_u32 s101, s27, 0
	s_add_u32 s0, s26, 0x80080
	s_addc_u32 s1, s27, 0
	s_add_i32 s26, s55, s34
	global_load_lds_dwordx4 v136, s[100:101]
	s_mov_b32 m0, s26
	s_nop 0
	global_load_lds_dwordx4 v132, s[0:1]
	s_add_i32 m0, s26, 0x2000
	s_nop 0
	global_load_lds_dwordx4 v136, s[0:1]
	s_add_u32 s100, s28, 0x80
	s_addc_u32 s101, s29, 0
	s_mov_b32 m0, s39
	s_nop 0
	global_load_lds_dwordx4 v130, s[100:101]
	s_add_u32 s100, s28, 0x80
	s_addc_u32 s101, s29, 0
	s_mov_b32 m0, s40
	s_nop 0
	global_load_lds_dwordx4 v134, s[100:101]
	s_setprio 1
	s_waitcnt vmcnt(8) lgkmcnt(0)
	s_barrier
	v_mfma_f32_16x16x32_bf16 v[62:65], v[142:145], v[178:181], v[62:65]
	v_mfma_f32_16x16x32_bf16 v[58:61], v[154:157], v[178:181], v[58:61]
	v_mfma_f32_16x16x32_bf16 v[46:49], v[142:145], v[186:189], v[46:49]
	v_mfma_f32_16x16x32_bf16 v[42:45], v[154:157], v[186:189], v[42:45]
	v_mfma_f32_16x16x32_bf16 v[30:33], v[142:145], v[194:197], v[30:33]
	v_mfma_f32_16x16x32_bf16 v[26:29], v[154:157], v[194:197], v[26:29]
	v_mfma_f32_16x16x32_bf16 v[14:17], v[142:145], v[208:211], v[14:17]
	v_mfma_f32_16x16x32_bf16 v[10:13], v[154:157], v[208:211], v[10:13]
	v_mfma_f32_16x16x32_bf16 v[62:65], v[146:149], v[182:185], v[62:65]
	v_mfma_f32_16x16x32_bf16 v[58:61], v[158:161], v[182:185], v[58:61]
	v_mfma_f32_16x16x32_bf16 v[46:49], v[146:149], v[190:193], v[46:49]
	v_mfma_f32_16x16x32_bf16 v[42:45], v[158:161], v[190:193], v[42:45]
	v_mfma_f32_16x16x32_bf16 v[30:33], v[146:149], v[198:201], v[30:33]
	v_mfma_f32_16x16x32_bf16 v[26:29], v[158:161], v[198:201], v[26:29]
	v_mfma_f32_16x16x32_bf16 v[14:17], v[146:149], v[212:215], v[14:17]
	v_mfma_f32_16x16x32_bf16 v[10:13], v[158:161], v[212:215], v[10:13]
	v_mfma_f32_16x16x32_bf16 v[54:57], v[162:165], v[178:181], v[54:57]
	v_mfma_f32_16x16x32_bf16 v[50:53], v[170:173], v[178:181], v[50:53]
	v_mfma_f32_16x16x32_bf16 v[38:41], v[162:165], v[186:189], v[38:41]
	v_mfma_f32_16x16x32_bf16 v[34:37], v[170:173], v[186:189], v[34:37]
	v_mfma_f32_16x16x32_bf16 v[22:25], v[162:165], v[194:197], v[22:25]
	v_mfma_f32_16x16x32_bf16 v[18:21], v[170:173], v[194:197], v[18:21]
	v_mfma_f32_16x16x32_bf16 v[6:9], v[162:165], v[208:211], v[6:9]
	v_mfma_f32_16x16x32_bf16 v[2:5], v[170:173], v[208:211], v[2:5]
	v_mfma_f32_16x16x32_bf16 v[54:57], v[166:169], v[182:185], v[54:57]
	v_mfma_f32_16x16x32_bf16 v[50:53], v[174:177], v[182:185], v[50:53]
	v_mfma_f32_16x16x32_bf16 v[38:41], v[166:169], v[190:193], v[38:41]
	v_mfma_f32_16x16x32_bf16 v[34:37], v[174:177], v[190:193], v[34:37]
	v_mfma_f32_16x16x32_bf16 v[22:25], v[166:169], v[198:201], v[22:25]
	v_mfma_f32_16x16x32_bf16 v[18:21], v[174:177], v[198:201], v[18:21]
	v_mfma_f32_16x16x32_bf16 v[6:9], v[166:169], v[212:215], v[6:9]
	v_mfma_f32_16x16x32_bf16 v[2:5], v[174:177], v[212:215], v[2:5]
	s_barrier
	s_setprio 0
	s_add_i32 s60, s60, 2
	s_add_u32 s24, s24, 0x100
	s_addc_u32 s25, s25, 0
	s_add_u32 s58, s58, 0x100
	s_addc_u32 s59, s59, 0
	s_cmp_gt_u32 s60, 29
	s_cbranch_scc0 .LBB0_394
	s_mov_b32 s101, 0x80000001
	s_and_b64 vcc, exec, s[14:15]
	s_cbranch_vccz .LBB0_397
	s_barrier

.LBB0_692:
	s_add_u32 s0, s18, 0xfff00080
	s_addc_u32 s1, s19, -1
	s_add_i32 s33, 0, 0x10000
	s_cmp_eq_u32 s61, 60
	s_cselect_b32 s23, s11, s1
	s_cselect_b32 s22, s49, s0
	s_cselect_b32 s21, s9, s60
	s_cselect_b32 s20, s58, s59
	s_add_i32 s55, 0, 0x14000
	ds_read_b128 v[78:81], v205
	ds_read_b128 v[86:89], v205 offset:1024
	ds_read_b128 v[94:97], v205 offset:2048
	ds_read_b128 v[98:101], v205 offset:3072
	ds_read_b128 v[106:109], v205 offset:16384
	ds_read_b128 v[110:113], v205 offset:17408
	ds_read_b128 v[126:129], v205 offset:18432
	ds_read_b128 v[134:137], v205 offset:19456
	s_add_i32 m0, s27, 0xc000
	ds_read_b128 v[146:149], v239
	ds_read_b128 v[158:161], v239 offset:1024
	ds_read_b128 v[166:169], v239 offset:2048
	ds_read_b128 v[174:177], v239 offset:3072
	ds_read_b128 v[178:181], v239 offset:4096
	ds_read_b128 v[182:185], v239 offset:5120
	ds_read_b128 v[186:189], v239 offset:6144
	ds_read_b128 v[190:193], v239 offset:7168
	global_load_lds_dwordx4 v214, s[18:19]
	s_add_i32 m0, s27, 0xe000
	s_nop 0
	global_load_lds_dwordx4 v216, s[18:19]
	s_setprio 1
	s_waitcnt vmcnt(8) lgkmcnt(0)
	s_barrier
	v_mfma_f32_16x16x32_bf16 v[170:173], v[78:81], v[146:149], v[170:173]
	v_mfma_f32_16x16x32_bf16 v[162:165], v[94:97], v[146:149], v[162:165]
	v_mfma_f32_16x16x32_bf16 v[142:145], v[78:81], v[166:169], v[142:145]
	v_mfma_f32_16x16x32_bf16 v[138:141], v[94:97], v[166:169], v[138:141]
	v_mfma_f32_16x16x32_bf16 v[118:121], v[78:81], v[178:181], v[118:121]
	v_mfma_f32_16x16x32_bf16 v[114:117], v[94:97], v[178:181], v[114:117]
	v_mfma_f32_16x16x32_bf16 v[82:85], v[78:81], v[186:189], v[82:85]
	v_mfma_f32_16x16x32_bf16 v[74:77], v[94:97], v[186:189], v[74:77]
	v_mfma_f32_16x16x32_bf16 v[170:173], v[86:89], v[158:161], v[170:173]
	v_mfma_f32_16x16x32_bf16 v[162:165], v[98:101], v[158:161], v[162:165]
	v_mfma_f32_16x16x32_bf16 v[142:145], v[86:89], v[174:177], v[142:145]
	v_mfma_f32_16x16x32_bf16 v[138:141], v[98:101], v[174:177], v[138:141]
	v_mfma_f32_16x16x32_bf16 v[118:121], v[86:89], v[182:185], v[118:121]
	v_mfma_f32_16x16x32_bf16 v[114:117], v[98:101], v[182:185], v[114:117]
	v_mfma_f32_16x16x32_bf16 v[82:85], v[86:89], v[190:193], v[82:85]
	v_mfma_f32_16x16x32_bf16 v[74:77], v[98:101], v[190:193], v[74:77]
	v_mfma_f32_16x16x32_bf16 v[154:157], v[106:109], v[146:149], v[154:157]
	v_mfma_f32_16x16x32_bf16 v[130:133], v[106:109], v[166:169], v[130:133]
	v_mfma_f32_16x16x32_bf16 v[122:125], v[126:129], v[166:169], v[122:125]
	v_mfma_f32_16x16x32_bf16 v[102:105], v[106:109], v[178:181], v[102:105]
	v_mfma_f32_16x16x32_bf16 v[90:93], v[126:129], v[178:181], v[90:93]
	v_mfma_f32_16x16x32_bf16 v[70:73], v[106:109], v[186:189], v[70:73]
	v_mfma_f32_16x16x32_bf16 v[66:69], v[126:129], v[186:189], v[66:69]
	v_mfma_f32_16x16x32_bf16 v[154:157], v[110:113], v[158:161], v[154:157]
	v_mfma_f32_16x16x32_bf16 v[146:149], v[126:129], v[146:149], v[150:153]
	v_mfma_f32_16x16x32_bf16 v[130:133], v[110:113], v[174:177], v[130:133]
	v_mfma_f32_16x16x32_bf16 v[122:125], v[134:137], v[174:177], v[122:125]
	v_mfma_f32_16x16x32_bf16 v[102:105], v[110:113], v[182:185], v[102:105]
	v_mfma_f32_16x16x32_bf16 v[90:93], v[134:137], v[182:185], v[90:93]
	v_mfma_f32_16x16x32_bf16 v[70:73], v[110:113], v[190:193], v[70:73]
	v_mfma_f32_16x16x32_bf16 v[66:69], v[134:137], v[190:193], v[66:69]
	v_mfma_f32_16x16x32_bf16 v[146:149], v[134:137], v[158:161], v[146:149]
	s_barrier
	s_setprio 0
	s_add_i32 s0, s33, s26
	s_mov_b32 m0, s0
	ds_read_b128 v[150:153], v239 offset:16384
	ds_read_b128 v[158:161], v239 offset:17408
	ds_read_b128 v[166:169], v239 offset:18432
	ds_read_b128 v[174:177], v239 offset:19456
	ds_read_b128 v[178:181], v239 offset:20480
	ds_read_b128 v[182:185], v239 offset:21504
	ds_read_b128 v[186:189], v239 offset:22528
	ds_read_b128 v[190:193], v239 offset:23552
	global_load_lds_dwordx4 v202, s[20:21]
	s_add_i32 m0, s0, 0x2000
	s_add_u32 s0, s20, 0x100000
	s_addc_u32 s1, s21, 0
	s_add_i32 s33, s55, s26
	global_load_lds_dwordx4 v208, s[20:21]
	s_mov_b32 m0, s33
	s_nop 0
	global_load_lds_dwordx4 v202, s[0:1]
	s_add_i32 m0, s33, 0x2000
	s_nop 0
	global_load_lds_dwordx4 v208, s[0:1]
	s_mov_b32 m0, s27
	s_nop 0
	global_load_lds_dwordx4 v212, s[22:23]
	s_mov_b32 m0, s28
	s_nop 0
	global_load_lds_dwordx4 v210, s[22:23]
	s_setprio 1
	s_waitcnt vmcnt(8) lgkmcnt(0)
	s_barrier
	v_mfma_f32_16x16x32_bf16 v[62:65], v[78:81], v[150:153], v[62:65]
	v_mfma_f32_16x16x32_bf16 v[58:61], v[94:97], v[150:153], v[58:61]
	v_mfma_f32_16x16x32_bf16 v[46:49], v[78:81], v[166:169], v[46:49]
	v_mfma_f32_16x16x32_bf16 v[42:45], v[94:97], v[166:169], v[42:45]
	v_mfma_f32_16x16x32_bf16 v[30:33], v[78:81], v[178:181], v[30:33]
	v_mfma_f32_16x16x32_bf16 v[26:29], v[94:97], v[178:181], v[26:29]
	v_mfma_f32_16x16x32_bf16 v[14:17], v[78:81], v[186:189], v[14:17]
	v_mfma_f32_16x16x32_bf16 v[10:13], v[94:97], v[186:189], v[10:13]
	v_mfma_f32_16x16x32_bf16 v[62:65], v[86:89], v[158:161], v[62:65]
	v_mfma_f32_16x16x32_bf16 v[58:61], v[98:101], v[158:161], v[58:61]
	v_mfma_f32_16x16x32_bf16 v[46:49], v[86:89], v[174:177], v[46:49]
	v_mfma_f32_16x16x32_bf16 v[42:45], v[98:101], v[174:177], v[42:45]
	v_mfma_f32_16x16x32_bf16 v[30:33], v[86:89], v[182:185], v[30:33]
	v_mfma_f32_16x16x32_bf16 v[26:29], v[98:101], v[182:185], v[26:29]
	v_mfma_f32_16x16x32_bf16 v[14:17], v[86:89], v[190:193], v[14:17]
	v_mfma_f32_16x16x32_bf16 v[10:13], v[98:101], v[190:193], v[10:13]
	v_mfma_f32_16x16x32_bf16 v[54:57], v[106:109], v[150:153], v[54:57]
	v_mfma_f32_16x16x32_bf16 v[50:53], v[126:129], v[150:153], v[50:53]
	v_mfma_f32_16x16x32_bf16 v[38:41], v[106:109], v[166:169], v[38:41]
	v_mfma_f32_16x16x32_bf16 v[34:37], v[126:129], v[166:169], v[34:37]
	v_mfma_f32_16x16x32_bf16 v[22:25], v[106:109], v[178:181], v[22:25]
	v_mfma_f32_16x16x32_bf16 v[18:21], v[126:129], v[178:181], v[18:21]
	v_mfma_f32_16x16x32_bf16 v[6:9], v[106:109], v[186:189], v[6:9]
	v_mfma_f32_16x16x32_bf16 v[2:5], v[126:129], v[186:189], v[2:5]
	v_mfma_f32_16x16x32_bf16 v[54:57], v[110:113], v[158:161], v[54:57]
	v_mfma_f32_16x16x32_bf16 v[50:53], v[134:137], v[158:161], v[50:53]
	v_mfma_f32_16x16x32_bf16 v[38:41], v[110:113], v[174:177], v[38:41]
	v_mfma_f32_16x16x32_bf16 v[34:37], v[134:137], v[174:177], v[34:37]
	v_mfma_f32_16x16x32_bf16 v[22:25], v[110:113], v[182:185], v[22:25]
	v_mfma_f32_16x16x32_bf16 v[18:21], v[134:137], v[182:185], v[18:21]
	v_mfma_f32_16x16x32_bf16 v[6:9], v[110:113], v[190:193], v[6:9]
	v_mfma_f32_16x16x32_bf16 v[2:5], v[134:137], v[190:193], v[2:5]
	s_barrier
	s_setprio 0
	s_add_i32 s33, 0, 0x18000
	s_add_i32 s55, 0, 0x1c000
	ds_read_b128 v[78:81], v205 offset:32768
	ds_read_b128 v[86:89], v205 offset:33792
	ds_read_b128 v[94:97], v205 offset:34816
	ds_read_b128 v[98:101], v205 offset:35840
	ds_read_b128 v[106:109], v205 offset:49152
	ds_read_b128 v[110:113], v205 offset:50176
	ds_read_b128 v[126:129], v205 offset:51200
	ds_read_b128 v[134:137], v205 offset:52224
	s_add_u32 s0, s22, 0x100000
	s_addc_u32 s1, s23, 0
	s_mov_b32 m0, s29
	ds_read_b128 v[150:153], v239 offset:32768
	ds_read_b128 v[158:161], v239 offset:33792
	ds_read_b128 v[166:169], v239 offset:34816
	ds_read_b128 v[174:177], v239 offset:35840
	ds_read_b128 v[178:181], v239 offset:36864
	ds_read_b128 v[182:185], v239 offset:37888
	ds_read_b128 v[186:189], v239 offset:38912
	ds_read_b128 v[190:193], v239 offset:39936
	global_load_lds_dwordx4 v212, s[0:1]
	s_mov_b32 m0, s30
	s_nop 0
	global_load_lds_dwordx4 v210, s[0:1]
	s_setprio 1
	s_waitcnt vmcnt(8) lgkmcnt(0)
	s_barrier
	v_mfma_f32_16x16x32_bf16 v[170:173], v[78:81], v[150:153], v[170:173]
	v_mfma_f32_16x16x32_bf16 v[162:165], v[94:97], v[150:153], v[162:165]
	v_mfma_f32_16x16x32_bf16 v[142:145], v[78:81], v[166:169], v[142:145]
	v_mfma_f32_16x16x32_bf16 v[138:141], v[94:97], v[166:169], v[138:141]
	v_mfma_f32_16x16x32_bf16 v[118:121], v[78:81], v[178:181], v[118:121]
	v_mfma_f32_16x16x32_bf16 v[114:117], v[94:97], v[178:181], v[114:117]
	v_mfma_f32_16x16x32_bf16 v[82:85], v[78:81], v[186:189], v[82:85]
	v_mfma_f32_16x16x32_bf16 v[74:77], v[94:97], v[186:189], v[74:77]
	v_mfma_f32_16x16x32_bf16 v[170:173], v[86:89], v[158:161], v[170:173]
	v_mfma_f32_16x16x32_bf16 v[162:165], v[98:101], v[158:161], v[162:165]
	v_mfma_f32_16x16x32_bf16 v[142:145], v[86:89], v[174:177], v[142:145]
	v_mfma_f32_16x16x32_bf16 v[138:141], v[98:101], v[174:177], v[138:141]
	v_mfma_f32_16x16x32_bf16 v[118:121], v[86:89], v[182:185], v[118:121]
	v_mfma_f32_16x16x32_bf16 v[114:117], v[98:101], v[182:185], v[114:117]
	v_mfma_f32_16x16x32_bf16 v[82:85], v[86:89], v[190:193], v[82:85]
	v_mfma_f32_16x16x32_bf16 v[74:77], v[98:101], v[190:193], v[74:77]
	v_mfma_f32_16x16x32_bf16 v[154:157], v[106:109], v[150:153], v[154:157]
	v_mfma_f32_16x16x32_bf16 v[146:149], v[126:129], v[150:153], v[146:149]
	v_mfma_f32_16x16x32_bf16 v[130:133], v[106:109], v[166:169], v[130:133]
	v_mfma_f32_16x16x32_bf16 v[122:125], v[126:129], v[166:169], v[122:125]
	v_mfma_f32_16x16x32_bf16 v[102:105], v[106:109], v[178:181], v[102:105]
	v_mfma_f32_16x16x32_bf16 v[90:93], v[126:129], v[178:181], v[90:93]
	v_mfma_f32_16x16x32_bf16 v[70:73], v[106:109], v[186:189], v[70:73]
	v_mfma_f32_16x16x32_bf16 v[66:69], v[126:129], v[186:189], v[66:69]
	v_mfma_f32_16x16x32_bf16 v[154:157], v[110:113], v[158:161], v[154:157]
	v_mfma_f32_16x16x32_bf16 v[150:153], v[134:137], v[158:161], v[146:149]
	v_mfma_f32_16x16x32_bf16 v[130:133], v[110:113], v[174:177], v[130:133]
	v_mfma_f32_16x16x32_bf16 v[122:125], v[134:137], v[174:177], v[122:125]
	v_mfma_f32_16x16x32_bf16 v[102:105], v[110:113], v[182:185], v[102:105]
	v_mfma_f32_16x16x32_bf16 v[90:93], v[134:137], v[182:185], v[90:93]
	v_mfma_f32_16x16x32_bf16 v[70:73], v[110:113], v[190:193], v[70:73]
	v_mfma_f32_16x16x32_bf16 v[66:69], v[134:137], v[190:193], v[66:69]
	s_barrier
	s_setprio 0
	s_add_i32 s0, s33, s26
	s_add_u32 s100, s20, 0x80
	s_addc_u32 s101, s21, 0
	s_mov_b32 m0, s0
	ds_read_b128 v[146:149], v239 offset:49152
	ds_read_b128 v[158:161], v239 offset:50176
	ds_read_b128 v[166:169], v239 offset:51200
	ds_read_b128 v[174:177], v239 offset:52224
	ds_read_b128 v[178:181], v239 offset:53248
	ds_read_b128 v[182:185], v239 offset:54272
	ds_read_b128 v[186:189], v239 offset:55296
	ds_read_b128 v[190:193], v239 offset:56320
	global_load_lds_dwordx4 v202, s[100:101]
	s_add_i32 m0, s0, 0x2000
	s_add_u32 s100, s20, 0x80
	s_addc_u32 s101, s21, 0
	s_add_u32 s0, s20, 0x100080
	s_addc_u32 s1, s21, 0
	s_add_i32 s20, s55, s26
	global_load_lds_dwordx4 v208, s[100:101]
	s_mov_b32 m0, s20
	s_nop 0
	global_load_lds_dwordx4 v202, s[0:1]
	s_add_i32 m0, s20, 0x2000
	s_nop 0
	global_load_lds_dwordx4 v208, s[0:1]
	s_add_u32 s100, s22, 0x80
	s_addc_u32 s101, s23, 0
	s_mov_b32 m0, s35
	s_nop 0
	global_load_lds_dwordx4 v212, s[100:101]
	s_add_u32 s100, s22, 0x80
	s_addc_u32 s101, s23, 0
	s_mov_b32 m0, s36
	s_nop 0
	global_load_lds_dwordx4 v210, s[100:101]
	s_setprio 1
	s_waitcnt vmcnt(8) lgkmcnt(0)
	s_barrier
	v_mfma_f32_16x16x32_bf16 v[62:65], v[78:81], v[146:149], v[62:65]
	v_mfma_f32_16x16x32_bf16 v[58:61], v[94:97], v[146:149], v[58:61]
	v_mfma_f32_16x16x32_bf16 v[46:49], v[78:81], v[166:169], v[46:49]
	v_mfma_f32_16x16x32_bf16 v[42:45], v[94:97], v[166:169], v[42:45]
	v_mfma_f32_16x16x32_bf16 v[30:33], v[78:81], v[178:181], v[30:33]
	v_mfma_f32_16x16x32_bf16 v[26:29], v[94:97], v[178:181], v[26:29]
	v_mfma_f32_16x16x32_bf16 v[14:17], v[78:81], v[186:189], v[14:17]
	v_mfma_f32_16x16x32_bf16 v[10:13], v[94:97], v[186:189], v[10:13]
	v_mfma_f32_16x16x32_bf16 v[62:65], v[86:89], v[158:161], v[62:65]
	v_mfma_f32_16x16x32_bf16 v[58:61], v[98:101], v[158:161], v[58:61]
	v_mfma_f32_16x16x32_bf16 v[46:49], v[86:89], v[174:177], v[46:49]
	v_mfma_f32_16x16x32_bf16 v[42:45], v[98:101], v[174:177], v[42:45]
	v_mfma_f32_16x16x32_bf16 v[30:33], v[86:89], v[182:185], v[30:33]
	v_mfma_f32_16x16x32_bf16 v[26:29], v[98:101], v[182:185], v[26:29]
	v_mfma_f32_16x16x32_bf16 v[14:17], v[86:89], v[190:193], v[14:17]
	v_mfma_f32_16x16x32_bf16 v[10:13], v[98:101], v[190:193], v[10:13]
	v_mfma_f32_16x16x32_bf16 v[54:57], v[106:109], v[146:149], v[54:57]
	v_mfma_f32_16x16x32_bf16 v[50:53], v[126:129], v[146:149], v[50:53]
	v_mfma_f32_16x16x32_bf16 v[38:41], v[106:109], v[166:169], v[38:41]
	v_mfma_f32_16x16x32_bf16 v[34:37], v[126:129], v[166:169], v[34:37]
	v_mfma_f32_16x16x32_bf16 v[22:25], v[106:109], v[178:181], v[22:25]
	v_mfma_f32_16x16x32_bf16 v[18:21], v[126:129], v[178:181], v[18:21]
	v_mfma_f32_16x16x32_bf16 v[6:9], v[106:109], v[186:189], v[6:9]
	v_mfma_f32_16x16x32_bf16 v[2:5], v[126:129], v[186:189], v[2:5]
	v_mfma_f32_16x16x32_bf16 v[54:57], v[110:113], v[158:161], v[54:57]
	v_mfma_f32_16x16x32_bf16 v[50:53], v[134:137], v[158:161], v[50:53]
	v_mfma_f32_16x16x32_bf16 v[38:41], v[110:113], v[174:177], v[38:41]
	v_mfma_f32_16x16x32_bf16 v[34:37], v[134:137], v[174:177], v[34:37]
	v_mfma_f32_16x16x32_bf16 v[22:25], v[110:113], v[182:185], v[22:25]
	v_mfma_f32_16x16x32_bf16 v[18:21], v[134:137], v[182:185], v[18:21]
	v_mfma_f32_16x16x32_bf16 v[6:9], v[110:113], v[190:193], v[6:9]
	v_mfma_f32_16x16x32_bf16 v[2:5], v[134:137], v[190:193], v[2:5]
	s_barrier
	s_setprio 0
	s_add_i32 s61, s61, 2
	s_add_u32 s18, s18, 0x100
	s_addc_u32 s19, s19, 0
	s_add_u32 s59, s59, 0x100
	s_addc_u32 s60, s60, 0
	s_cmp_gt_u32 s61, 61
	s_cbranch_scc0 .LBB0_692
	s_and_b64 vcc, exec, s[6:7]
	s_cbranch_vccz .LBB0_695
	s_barrier

.LBB0_712:
	s_add_u32 s0, s18, 0xfff00080
	s_addc_u32 s1, s19, -1
	s_add_i32 s33, 0, 0x10000
	s_cmp_eq_u32 s49, 4
	s_cselect_b32 s23, s15, s1
	s_cselect_b32 s22, s14, s0
	s_cselect_b32 s21, s17, s11
	s_cselect_b32 s20, s16, s9
	s_add_i32 s55, 0, 0x14000
	ds_read_b128 v[140:143], v136
	ds_read_b128 v[144:147], v136 offset:1024
	ds_read_b128 v[148:151], v136 offset:2048
	ds_read_b128 v[152:155], v136 offset:3072
	ds_read_b128 v[156:159], v136 offset:16384
	ds_read_b128 v[160:163], v136 offset:17408
	ds_read_b128 v[164:167], v136 offset:18432
	ds_read_b128 v[168:171], v136 offset:19456
	s_add_i32 m0, s27, 0xc000
	ds_read_b128 v[172:175], v139
	ds_read_b128 v[176:179], v139 offset:1024
	ds_read_b128 v[180:183], v139 offset:2048
	ds_read_b128 v[184:187], v139 offset:3072
	ds_read_b128 v[188:191], v139 offset:4096
	ds_read_b128 v[192:195], v139 offset:5120
	ds_read_b128 v[196:199], v139 offset:6144
	ds_read_b128 v[208:211], v139 offset:7168
	global_load_lds_dwordx4 v132, s[18:19]
	s_add_i32 m0, s27, 0xe000
	s_nop 0
	global_load_lds_dwordx4 v134, s[18:19]
	s_setprio 1
	s_waitcnt vmcnt(8) lgkmcnt(0)
	s_barrier
	v_mfma_f32_16x16x32_bf16 v[126:129], v[140:143], v[172:175], v[126:129]
	v_mfma_f32_16x16x32_bf16 v[122:125], v[148:151], v[172:175], v[122:125]
	v_mfma_f32_16x16x32_bf16 v[118:121], v[140:143], v[180:183], v[118:121]
	v_mfma_f32_16x16x32_bf16 v[114:117], v[148:151], v[180:183], v[114:117]
	v_mfma_f32_16x16x32_bf16 v[106:109], v[140:143], v[188:191], v[106:109]
	v_mfma_f32_16x16x32_bf16 v[98:101], v[148:151], v[188:191], v[98:101]
	v_mfma_f32_16x16x32_bf16 v[90:93], v[140:143], v[196:199], v[90:93]
	v_mfma_f32_16x16x32_bf16 v[82:85], v[148:151], v[196:199], v[82:85]
	v_mfma_f32_16x16x32_bf16 v[126:129], v[144:147], v[176:179], v[126:129]
	v_mfma_f32_16x16x32_bf16 v[122:125], v[152:155], v[176:179], v[122:125]
	v_mfma_f32_16x16x32_bf16 v[118:121], v[144:147], v[184:187], v[118:121]
	v_mfma_f32_16x16x32_bf16 v[114:117], v[152:155], v[184:187], v[114:117]
	v_mfma_f32_16x16x32_bf16 v[106:109], v[144:147], v[192:195], v[106:109]
	v_mfma_f32_16x16x32_bf16 v[98:101], v[152:155], v[192:195], v[98:101]
	v_mfma_f32_16x16x32_bf16 v[90:93], v[144:147], v[208:211], v[90:93]
	v_mfma_f32_16x16x32_bf16 v[82:85], v[152:155], v[208:211], v[82:85]
	v_mfma_f32_16x16x32_bf16 v[110:113], v[156:159], v[172:175], v[110:113]
	v_mfma_f32_16x16x32_bf16 v[102:105], v[164:167], v[172:175], v[102:105]
	v_mfma_f32_16x16x32_bf16 v[94:97], v[156:159], v[180:183], v[94:97]
	v_mfma_f32_16x16x32_bf16 v[86:89], v[164:167], v[180:183], v[86:89]
	v_mfma_f32_16x16x32_bf16 v[78:81], v[156:159], v[188:191], v[78:81]
	v_mfma_f32_16x16x32_bf16 v[74:77], v[164:167], v[188:191], v[74:77]
	v_mfma_f32_16x16x32_bf16 v[70:73], v[156:159], v[196:199], v[70:73]
	v_mfma_f32_16x16x32_bf16 v[66:69], v[164:167], v[196:199], v[66:69]
	v_mfma_f32_16x16x32_bf16 v[110:113], v[160:163], v[176:179], v[110:113]
	v_mfma_f32_16x16x32_bf16 v[102:105], v[168:171], v[176:179], v[102:105]
	v_mfma_f32_16x16x32_bf16 v[94:97], v[160:163], v[184:187], v[94:97]
	v_mfma_f32_16x16x32_bf16 v[86:89], v[168:171], v[184:187], v[86:89]
	v_mfma_f32_16x16x32_bf16 v[78:81], v[160:163], v[192:195], v[78:81]
	v_mfma_f32_16x16x32_bf16 v[74:77], v[168:171], v[192:195], v[74:77]
	v_mfma_f32_16x16x32_bf16 v[70:73], v[160:163], v[208:211], v[70:73]
	v_mfma_f32_16x16x32_bf16 v[66:69], v[168:171], v[208:211], v[66:69]
	s_barrier
	s_setprio 0
	s_add_i32 s0, s33, s26
	s_mov_b32 m0, s0
	ds_read_b128 v[172:175], v139 offset:16384
	ds_read_b128 v[176:179], v139 offset:17408
	ds_read_b128 v[180:183], v139 offset:18432
	ds_read_b128 v[184:187], v139 offset:19456
	ds_read_b128 v[188:191], v139 offset:20480
	ds_read_b128 v[192:195], v139 offset:21504
	ds_read_b128 v[196:199], v139 offset:22528
	ds_read_b128 v[208:211], v139 offset:23552
	global_load_lds_dwordx4 v202, s[20:21]
	s_add_i32 m0, s0, 0x2000
	s_add_u32 s0, s20, 0x100000
	s_addc_u32 s1, s21, 0
	s_add_i32 s33, s55, s26
	global_load_lds_dwordx4 v130, s[20:21]
	s_mov_b32 m0, s33
	s_nop 0
	global_load_lds_dwordx4 v202, s[0:1]
	s_add_i32 m0, s33, 0x2000
	s_nop 0
	global_load_lds_dwordx4 v130, s[0:1]
	s_mov_b32 m0, s27
	s_nop 0
	global_load_lds_dwordx4 v202, s[22:23]
	s_mov_b32 m0, s28
	s_nop 0
	global_load_lds_dwordx4 v130, s[22:23]
	s_setprio 1
	s_waitcnt vmcnt(8) lgkmcnt(0)
	s_barrier
	v_mfma_f32_16x16x32_bf16 v[62:65], v[140:143], v[172:175], v[62:65]
	v_mfma_f32_16x16x32_bf16 v[58:61], v[148:151], v[172:175], v[58:61]
	v_mfma_f32_16x16x32_bf16 v[54:57], v[140:143], v[180:183], v[54:57]
	v_mfma_f32_16x16x32_bf16 v[50:53], v[148:151], v[180:183], v[50:53]
	v_mfma_f32_16x16x32_bf16 v[38:41], v[140:143], v[188:191], v[38:41]
	v_mfma_f32_16x16x32_bf16 v[34:37], v[148:151], v[188:191], v[34:37]
	v_mfma_f32_16x16x32_bf16 v[22:25], v[140:143], v[196:199], v[22:25]
	v_mfma_f32_16x16x32_bf16 v[18:21], v[148:151], v[196:199], v[18:21]
	v_mfma_f32_16x16x32_bf16 v[62:65], v[144:147], v[176:179], v[62:65]
	v_mfma_f32_16x16x32_bf16 v[58:61], v[152:155], v[176:179], v[58:61]
	v_mfma_f32_16x16x32_bf16 v[54:57], v[144:147], v[184:187], v[54:57]
	v_mfma_f32_16x16x32_bf16 v[50:53], v[152:155], v[184:187], v[50:53]
	v_mfma_f32_16x16x32_bf16 v[38:41], v[144:147], v[192:195], v[38:41]
	v_mfma_f32_16x16x32_bf16 v[34:37], v[152:155], v[192:195], v[34:37]
	v_mfma_f32_16x16x32_bf16 v[22:25], v[144:147], v[208:211], v[22:25]
	v_mfma_f32_16x16x32_bf16 v[18:21], v[152:155], v[208:211], v[18:21]
	v_mfma_f32_16x16x32_bf16 v[46:49], v[156:159], v[172:175], v[46:49]
	v_mfma_f32_16x16x32_bf16 v[42:45], v[164:167], v[172:175], v[42:45]
	v_mfma_f32_16x16x32_bf16 v[30:33], v[156:159], v[180:183], v[30:33]
	v_mfma_f32_16x16x32_bf16 v[26:29], v[164:167], v[180:183], v[26:29]
	v_mfma_f32_16x16x32_bf16 v[14:17], v[156:159], v[188:191], v[14:17]
	v_mfma_f32_16x16x32_bf16 v[10:13], v[164:167], v[188:191], v[10:13]
	v_mfma_f32_16x16x32_bf16 v[6:9], v[156:159], v[196:199], v[6:9]
	v_mfma_f32_16x16x32_bf16 v[2:5], v[164:167], v[196:199], v[2:5]
	v_mfma_f32_16x16x32_bf16 v[46:49], v[160:163], v[176:179], v[46:49]
	v_mfma_f32_16x16x32_bf16 v[42:45], v[168:171], v[176:179], v[42:45]
	v_mfma_f32_16x16x32_bf16 v[30:33], v[160:163], v[184:187], v[30:33]
	v_mfma_f32_16x16x32_bf16 v[26:29], v[168:171], v[184:187], v[26:29]
	v_mfma_f32_16x16x32_bf16 v[14:17], v[160:163], v[192:195], v[14:17]
	v_mfma_f32_16x16x32_bf16 v[10:13], v[168:171], v[192:195], v[10:13]
	v_mfma_f32_16x16x32_bf16 v[6:9], v[160:163], v[208:211], v[6:9]
	v_mfma_f32_16x16x32_bf16 v[2:5], v[168:171], v[208:211], v[2:5]
	s_barrier
	s_setprio 0
	s_add_i32 s33, 0, 0x18000
	s_add_i32 s55, 0, 0x1c000
	ds_read_b128 v[140:143], v136 offset:32768
	ds_read_b128 v[144:147], v136 offset:33792
	ds_read_b128 v[148:151], v136 offset:34816
	ds_read_b128 v[152:155], v136 offset:35840
	ds_read_b128 v[156:159], v136 offset:49152
	ds_read_b128 v[160:163], v136 offset:50176
	ds_read_b128 v[164:167], v136 offset:51200
	ds_read_b128 v[168:171], v136 offset:52224
	s_add_u32 s0, s22, 0x100000
	s_addc_u32 s1, s23, 0
	s_mov_b32 m0, s29
	ds_read_b128 v[172:175], v139 offset:32768
	ds_read_b128 v[176:179], v139 offset:33792
	ds_read_b128 v[180:183], v139 offset:34816
	ds_read_b128 v[184:187], v139 offset:35840
	ds_read_b128 v[188:191], v139 offset:36864
	ds_read_b128 v[192:195], v139 offset:37888
	ds_read_b128 v[196:199], v139 offset:38912
	ds_read_b128 v[208:211], v139 offset:39936
	global_load_lds_dwordx4 v202, s[0:1]
	s_mov_b32 m0, s30
	s_nop 0
	global_load_lds_dwordx4 v130, s[0:1]
	s_setprio 1
	s_waitcnt vmcnt(8) lgkmcnt(0)
	s_barrier
	v_mfma_f32_16x16x32_bf16 v[126:129], v[140:143], v[172:175], v[126:129]
	v_mfma_f32_16x16x32_bf16 v[122:125], v[148:151], v[172:175], v[122:125]
	v_mfma_f32_16x16x32_bf16 v[118:121], v[140:143], v[180:183], v[118:121]
	v_mfma_f32_16x16x32_bf16 v[114:117], v[148:151], v[180:183], v[114:117]
	v_mfma_f32_16x16x32_bf16 v[106:109], v[140:143], v[188:191], v[106:109]
	v_mfma_f32_16x16x32_bf16 v[98:101], v[148:151], v[188:191], v[98:101]
	v_mfma_f32_16x16x32_bf16 v[90:93], v[140:143], v[196:199], v[90:93]
	v_mfma_f32_16x16x32_bf16 v[82:85], v[148:151], v[196:199], v[82:85]
	v_mfma_f32_16x16x32_bf16 v[126:129], v[144:147], v[176:179], v[126:129]
	v_mfma_f32_16x16x32_bf16 v[122:125], v[152:155], v[176:179], v[122:125]
	v_mfma_f32_16x16x32_bf16 v[118:121], v[144:147], v[184:187], v[118:121]
	v_mfma_f32_16x16x32_bf16 v[114:117], v[152:155], v[184:187], v[114:117]
	v_mfma_f32_16x16x32_bf16 v[106:109], v[144:147], v[192:195], v[106:109]
	v_mfma_f32_16x16x32_bf16 v[98:101], v[152:155], v[192:195], v[98:101]
	v_mfma_f32_16x16x32_bf16 v[90:93], v[144:147], v[208:211], v[90:93]
	v_mfma_f32_16x16x32_bf16 v[82:85], v[152:155], v[208:211], v[82:85]
	v_mfma_f32_16x16x32_bf16 v[110:113], v[156:159], v[172:175], v[110:113]
	v_mfma_f32_16x16x32_bf16 v[102:105], v[164:167], v[172:175], v[102:105]
	v_mfma_f32_16x16x32_bf16 v[94:97], v[156:159], v[180:183], v[94:97]
	v_mfma_f32_16x16x32_bf16 v[86:89], v[164:167], v[180:183], v[86:89]
	v_mfma_f32_16x16x32_bf16 v[78:81], v[156:159], v[188:191], v[78:81]
	v_mfma_f32_16x16x32_bf16 v[74:77], v[164:167], v[188:191], v[74:77]
	v_mfma_f32_16x16x32_bf16 v[70:73], v[156:159], v[196:199], v[70:73]
	v_mfma_f32_16x16x32_bf16 v[66:69], v[164:167], v[196:199], v[66:69]
	v_mfma_f32_16x16x32_bf16 v[110:113], v[160:163], v[176:179], v[110:113]
	v_mfma_f32_16x16x32_bf16 v[102:105], v[168:171], v[176:179], v[102:105]
	v_mfma_f32_16x16x32_bf16 v[94:97], v[160:163], v[184:187], v[94:97]
	v_mfma_f32_16x16x32_bf16 v[86:89], v[168:171], v[184:187], v[86:89]
	v_mfma_f32_16x16x32_bf16 v[78:81], v[160:163], v[192:195], v[78:81]
	v_mfma_f32_16x16x32_bf16 v[74:77], v[168:171], v[192:195], v[74:77]
	v_mfma_f32_16x16x32_bf16 v[70:73], v[160:163], v[208:211], v[70:73]
	v_mfma_f32_16x16x32_bf16 v[66:69], v[168:171], v[208:211], v[66:69]
	s_barrier
	s_setprio 0
	s_add_i32 s0, s33, s26
	s_add_u32 s100, s20, 0x80
	s_addc_u32 s101, s21, 0
	s_mov_b32 m0, s0
	ds_read_b128 v[172:175], v139 offset:49152
	ds_read_b128 v[176:179], v139 offset:50176
	ds_read_b128 v[180:183], v139 offset:51200
	ds_read_b128 v[184:187], v139 offset:52224
	ds_read_b128 v[188:191], v139 offset:53248
	ds_read_b128 v[192:195], v139 offset:54272
	ds_read_b128 v[196:199], v139 offset:55296
	ds_read_b128 v[208:211], v139 offset:56320
	global_load_lds_dwordx4 v202, s[100:101]
	s_add_i32 m0, s0, 0x2000
	s_add_u32 s100, s20, 0x80
	s_addc_u32 s101, s21, 0
	s_add_u32 s0, s20, 0x100080
	s_addc_u32 s1, s21, 0
	s_add_i32 s20, s55, s26
	global_load_lds_dwordx4 v130, s[100:101]
	s_mov_b32 m0, s20
	s_nop 0
	global_load_lds_dwordx4 v202, s[0:1]
	s_add_i32 m0, s20, 0x2000
	s_nop 0
	global_load_lds_dwordx4 v130, s[0:1]
	s_add_u32 s100, s22, 0x80
	s_addc_u32 s101, s23, 0
	s_mov_b32 m0, s31
	s_nop 0
	global_load_lds_dwordx4 v202, s[100:101]
	s_add_u32 s100, s22, 0x80
	s_addc_u32 s101, s23, 0
	s_mov_b32 m0, s34
	s_nop 0
	global_load_lds_dwordx4 v130, s[100:101]
	s_setprio 1
	s_waitcnt vmcnt(8) lgkmcnt(0)
	s_barrier
	v_mfma_f32_16x16x32_bf16 v[62:65], v[140:143], v[172:175], v[62:65]
	v_mfma_f32_16x16x32_bf16 v[58:61], v[148:151], v[172:175], v[58:61]
	v_mfma_f32_16x16x32_bf16 v[54:57], v[140:143], v[180:183], v[54:57]
	v_mfma_f32_16x16x32_bf16 v[50:53], v[148:151], v[180:183], v[50:53]
	v_mfma_f32_16x16x32_bf16 v[38:41], v[140:143], v[188:191], v[38:41]
	v_mfma_f32_16x16x32_bf16 v[34:37], v[148:151], v[188:191], v[34:37]
	v_mfma_f32_16x16x32_bf16 v[22:25], v[140:143], v[196:199], v[22:25]
	v_mfma_f32_16x16x32_bf16 v[18:21], v[148:151], v[196:199], v[18:21]
	v_mfma_f32_16x16x32_bf16 v[62:65], v[144:147], v[176:179], v[62:65]
	v_mfma_f32_16x16x32_bf16 v[58:61], v[152:155], v[176:179], v[58:61]
	v_mfma_f32_16x16x32_bf16 v[54:57], v[144:147], v[184:187], v[54:57]
	v_mfma_f32_16x16x32_bf16 v[50:53], v[152:155], v[184:187], v[50:53]
	v_mfma_f32_16x16x32_bf16 v[38:41], v[144:147], v[192:195], v[38:41]
	v_mfma_f32_16x16x32_bf16 v[34:37], v[152:155], v[192:195], v[34:37]
	v_mfma_f32_16x16x32_bf16 v[22:25], v[144:147], v[208:211], v[22:25]
	v_mfma_f32_16x16x32_bf16 v[18:21], v[152:155], v[208:211], v[18:21]
	v_mfma_f32_16x16x32_bf16 v[46:49], v[156:159], v[172:175], v[46:49]
	v_mfma_f32_16x16x32_bf16 v[42:45], v[164:167], v[172:175], v[42:45]
	v_mfma_f32_16x16x32_bf16 v[30:33], v[156:159], v[180:183], v[30:33]
	v_mfma_f32_16x16x32_bf16 v[26:29], v[164:167], v[180:183], v[26:29]
	v_mfma_f32_16x16x32_bf16 v[14:17], v[156:159], v[188:191], v[14:17]
	v_mfma_f32_16x16x32_bf16 v[10:13], v[164:167], v[188:191], v[10:13]
	v_mfma_f32_16x16x32_bf16 v[6:9], v[156:159], v[196:199], v[6:9]
	v_mfma_f32_16x16x32_bf16 v[2:5], v[164:167], v[196:199], v[2:5]
	v_mfma_f32_16x16x32_bf16 v[46:49], v[160:163], v[176:179], v[46:49]
	v_mfma_f32_16x16x32_bf16 v[42:45], v[168:171], v[176:179], v[42:45]
	v_mfma_f32_16x16x32_bf16 v[30:33], v[160:163], v[184:187], v[30:33]
	v_mfma_f32_16x16x32_bf16 v[26:29], v[168:171], v[184:187], v[26:29]
	v_mfma_f32_16x16x32_bf16 v[14:17], v[160:163], v[192:195], v[14:17]
	v_mfma_f32_16x16x32_bf16 v[10:13], v[168:171], v[192:195], v[10:13]
	v_mfma_f32_16x16x32_bf16 v[6:9], v[160:163], v[208:211], v[6:9]
	v_mfma_f32_16x16x32_bf16 v[2:5], v[168:171], v[208:211], v[2:5]
	s_barrier
	s_setprio 0
	s_add_i32 s49, s49, 2
	s_add_u32 s18, s18, 0x100
	s_addc_u32 s19, s19, 0
	s_add_u32 s9, s9, 0x100
	s_addc_u32 s11, s11, 0
	s_cmp_gt_u32 s49, 5
	s_cbranch_scc0 .LBB0_712
	s_and_b64 vcc, exec, s[6:7]
	s_cbranch_vccz .LBB0_715
	s_barrier

.LBB0_836:
	s_ashr_i32 s11, s10, 31
	s_lshl_b64 s[0:1], s[10:11], 20
	s_add_u32 s14, s42, s0
	s_addc_u32 s15, s43, s1
	s_and_b64 s[0:1], s[2:3], exec
	s_cselect_b32 s11, s15, s19
	s_cselect_b32 s38, s14, s18
	s_ashr_i32 s9, s8, 31
	s_lshl_b64 s[0:1], s[8:9], 20
	s_add_u32 s16, s24, s0
	s_addc_u32 s17, s25, s1
	s_and_b64 s[0:1], s[2:3], exec
	s_cselect_b32 s9, s17, s21
	s_cselect_b32 s39, s16, s20
	s_add_u32 s18, s18, 0x80080
	s_addc_u32 s19, s19, 0
	s_add_u32 s49, s20, 0x100
	v_mov_b32_e32 v2, 0
	s_addc_u32 s58, s21, 0
	s_mov_b32 s59, -2
	v_mov_b32_e32 v3, v2
	v_pk_mov_b32 v[4:5], v[2:3], v[2:3] op_sel:[0,1]
	v_pk_mov_b32 v[10:11], v[2:3], v[2:3] op_sel:[0,1]
	v_pk_mov_b32 v[12:13], v[2:3], v[2:3] op_sel:[0,1]
	v_pk_mov_b32 v[18:19], v[2:3], v[2:3] op_sel:[0,1]
	v_pk_mov_b32 v[20:21], v[2:3], v[2:3] op_sel:[0,1]
	v_pk_mov_b32 v[26:27], v[2:3], v[2:3] op_sel:[0,1]
	v_pk_mov_b32 v[28:29], v[2:3], v[2:3] op_sel:[0,1]
	v_pk_mov_b32 v[34:35], v[2:3], v[2:3] op_sel:[0,1]
	v_pk_mov_b32 v[36:37], v[2:3], v[2:3] op_sel:[0,1]
	v_pk_mov_b32 v[42:43], v[2:3], v[2:3] op_sel:[0,1]
	v_pk_mov_b32 v[44:45], v[2:3], v[2:3] op_sel:[0,1]
	v_pk_mov_b32 v[50:51], v[2:3], v[2:3] op_sel:[0,1]
	v_pk_mov_b32 v[52:53], v[2:3], v[2:3] op_sel:[0,1]
	v_pk_mov_b32 v[58:59], v[2:3], v[2:3] op_sel:[0,1]
	v_pk_mov_b32 v[60:61], v[2:3], v[2:3] op_sel:[0,1]
	v_pk_mov_b32 v[6:7], v[2:3], v[2:3] op_sel:[0,1]
	v_pk_mov_b32 v[8:9], v[2:3], v[2:3] op_sel:[0,1]
	v_pk_mov_b32 v[14:15], v[2:3], v[2:3] op_sel:[0,1]
	v_pk_mov_b32 v[16:17], v[2:3], v[2:3] op_sel:[0,1]
	v_pk_mov_b32 v[22:23], v[2:3], v[2:3] op_sel:[0,1]
	v_pk_mov_b32 v[24:25], v[2:3], v[2:3] op_sel:[0,1]
	v_pk_mov_b32 v[30:31], v[2:3], v[2:3] op_sel:[0,1]
	v_pk_mov_b32 v[32:33], v[2:3], v[2:3] op_sel:[0,1]
	v_pk_mov_b32 v[38:39], v[2:3], v[2:3] op_sel:[0,1]
	v_pk_mov_b32 v[40:41], v[2:3], v[2:3] op_sel:[0,1]
	v_pk_mov_b32 v[46:47], v[2:3], v[2:3] op_sel:[0,1]
	v_pk_mov_b32 v[48:49], v[2:3], v[2:3] op_sel:[0,1]
	v_pk_mov_b32 v[54:55], v[2:3], v[2:3] op_sel:[0,1]
	v_pk_mov_b32 v[56:57], v[2:3], v[2:3] op_sel:[0,1]
	v_pk_mov_b32 v[62:63], v[2:3], v[2:3] op_sel:[0,1]
	v_pk_mov_b32 v[64:65], v[2:3], v[2:3] op_sel:[0,1]
	v_pk_mov_b32 v[66:67], v[2:3], v[2:3] op_sel:[0,1]
	v_pk_mov_b32 v[68:69], v[2:3], v[2:3] op_sel:[0,1]
	v_pk_mov_b32 v[74:75], v[2:3], v[2:3] op_sel:[0,1]
	v_pk_mov_b32 v[76:77], v[2:3], v[2:3] op_sel:[0,1]
	v_pk_mov_b32 v[82:83], v[2:3], v[2:3] op_sel:[0,1]
	v_pk_mov_b32 v[84:85], v[2:3], v[2:3] op_sel:[0,1]
	v_pk_mov_b32 v[90:91], v[2:3], v[2:3] op_sel:[0,1]
	v_pk_mov_b32 v[92:93], v[2:3], v[2:3] op_sel:[0,1]
	v_pk_mov_b32 v[98:99], v[2:3], v[2:3] op_sel:[0,1]
	v_pk_mov_b32 v[100:101], v[2:3], v[2:3] op_sel:[0,1]
	v_pk_mov_b32 v[106:107], v[2:3], v[2:3] op_sel:[0,1]
	v_pk_mov_b32 v[108:109], v[2:3], v[2:3] op_sel:[0,1]
	v_pk_mov_b32 v[114:115], v[2:3], v[2:3] op_sel:[0,1]
	v_pk_mov_b32 v[116:117], v[2:3], v[2:3] op_sel:[0,1]
	v_pk_mov_b32 v[122:123], v[2:3], v[2:3] op_sel:[0,1]
	v_pk_mov_b32 v[124:125], v[2:3], v[2:3] op_sel:[0,1]
	v_pk_mov_b32 v[70:71], v[2:3], v[2:3] op_sel:[0,1]
	v_pk_mov_b32 v[72:73], v[2:3], v[2:3] op_sel:[0,1]
	v_pk_mov_b32 v[78:79], v[2:3], v[2:3] op_sel:[0,1]
	v_pk_mov_b32 v[80:81], v[2:3], v[2:3] op_sel:[0,1]
	v_pk_mov_b32 v[86:87], v[2:3], v[2:3] op_sel:[0,1]
	v_pk_mov_b32 v[88:89], v[2:3], v[2:3] op_sel:[0,1]
	v_pk_mov_b32 v[94:95], v[2:3], v[2:3] op_sel:[0,1]
	v_pk_mov_b32 v[96:97], v[2:3], v[2:3] op_sel:[0,1]
	v_pk_mov_b32 v[102:103], v[2:3], v[2:3] op_sel:[0,1]
	v_pk_mov_b32 v[104:105], v[2:3], v[2:3] op_sel:[0,1]
	v_pk_mov_b32 v[110:111], v[2:3], v[2:3] op_sel:[0,1]
	v_pk_mov_b32 v[112:113], v[2:3], v[2:3] op_sel:[0,1]
	v_pk_mov_b32 v[118:119], v[2:3], v[2:3] op_sel:[0,1]
	v_pk_mov_b32 v[120:121], v[2:3], v[2:3] op_sel:[0,1]
	v_pk_mov_b32 v[126:127], v[2:3], v[2:3] op_sel:[0,1]
	v_pk_mov_b32 v[128:129], v[2:3], v[2:3] op_sel:[0,1]
	s_cmp_eq_u32 s101, 0x80000001
	s_cbranch_scc0 .LBB0_837
	s_add_u32 s0, s18, 0xfff80080
	s_addc_u32 s1, s19, -1
	s_add_i32 s33, 0, 0x10000
	s_cmp_eq_u32 s59, 28
	s_cselect_b32 s23, s11, s1
	s_cselect_b32 s22, s38, s0
	s_cselect_b32 s21, s9, s58
	s_cselect_b32 s20, s39, s49
	s_add_i32 s55, 0, 0x14000
	ds_read_b128 v[146:149], v143
	ds_read_b128 v[150:153], v143 offset:1024
	ds_read_b128 v[154:157], v143 offset:2048
	ds_read_b128 v[158:161], v143 offset:3072
	ds_read_b128 v[162:165], v143 offset:16384
	ds_read_b128 v[166:169], v143 offset:17408
	ds_read_b128 v[170:173], v143 offset:18432
	ds_read_b128 v[174:177], v143 offset:19456
	s_add_i32 m0, s27, 0xc000
	ds_read_b128 v[178:181], v145
	ds_read_b128 v[182:185], v145 offset:1024
	ds_read_b128 v[186:189], v145 offset:2048
	ds_read_b128 v[190:193], v145 offset:3072
	ds_read_b128 v[194:197], v145 offset:4096
	ds_read_b128 v[198:201], v145 offset:5120
	ds_read_b128 v[208:211], v145 offset:6144
	ds_read_b128 v[212:215], v145 offset:7168
	global_load_lds_dwordx4 v136, s[18:19]
	s_add_i32 m0, s27, 0xe000
	s_nop 0
	global_load_lds_dwordx4 v138, s[18:19]
	s_setprio 1
	s_waitcnt vmcnt(16) lgkmcnt(0)
	s_barrier
	v_mfma_f32_16x16x32_bf16 v[126:129], v[146:149], v[178:181], v[126:129]
	v_mfma_f32_16x16x32_bf16 v[118:121], v[154:157], v[178:181], v[118:121]
	v_mfma_f32_16x16x32_bf16 v[110:113], v[146:149], v[186:189], v[110:113]
	v_mfma_f32_16x16x32_bf16 v[102:105], v[154:157], v[186:189], v[102:105]
	v_mfma_f32_16x16x32_bf16 v[94:97], v[146:149], v[194:197], v[94:97]
	v_mfma_f32_16x16x32_bf16 v[86:89], v[154:157], v[194:197], v[86:89]
	v_mfma_f32_16x16x32_bf16 v[78:81], v[146:149], v[208:211], v[78:81]
	v_mfma_f32_16x16x32_bf16 v[70:73], v[154:157], v[208:211], v[70:73]
	v_mfma_f32_16x16x32_bf16 v[126:129], v[150:153], v[182:185], v[126:129]
	v_mfma_f32_16x16x32_bf16 v[118:121], v[158:161], v[182:185], v[118:121]
	v_mfma_f32_16x16x32_bf16 v[110:113], v[150:153], v[190:193], v[110:113]
	v_mfma_f32_16x16x32_bf16 v[102:105], v[158:161], v[190:193], v[102:105]
	v_mfma_f32_16x16x32_bf16 v[94:97], v[150:153], v[198:201], v[94:97]
	v_mfma_f32_16x16x32_bf16 v[86:89], v[158:161], v[198:201], v[86:89]
	v_mfma_f32_16x16x32_bf16 v[78:81], v[150:153], v[212:215], v[78:81]
	v_mfma_f32_16x16x32_bf16 v[70:73], v[158:161], v[212:215], v[70:73]
	v_mfma_f32_16x16x32_bf16 v[122:125], v[162:165], v[178:181], v[122:125]
	v_mfma_f32_16x16x32_bf16 v[114:117], v[170:173], v[178:181], v[114:117]
	v_mfma_f32_16x16x32_bf16 v[106:109], v[162:165], v[186:189], v[106:109]
	v_mfma_f32_16x16x32_bf16 v[98:101], v[170:173], v[186:189], v[98:101]
	v_mfma_f32_16x16x32_bf16 v[90:93], v[162:165], v[194:197], v[90:93]
	v_mfma_f32_16x16x32_bf16 v[82:85], v[170:173], v[194:197], v[82:85]
	v_mfma_f32_16x16x32_bf16 v[74:77], v[162:165], v[208:211], v[74:77]
	v_mfma_f32_16x16x32_bf16 v[66:69], v[170:173], v[208:211], v[66:69]
	v_mfma_f32_16x16x32_bf16 v[122:125], v[166:169], v[182:185], v[122:125]
	v_mfma_f32_16x16x32_bf16 v[114:117], v[174:177], v[182:185], v[114:117]
	v_mfma_f32_16x16x32_bf16 v[106:109], v[166:169], v[190:193], v[106:109]
	v_mfma_f32_16x16x32_bf16 v[98:101], v[174:177], v[190:193], v[98:101]
	v_mfma_f32_16x16x32_bf16 v[90:93], v[166:169], v[198:201], v[90:93]
	v_mfma_f32_16x16x32_bf16 v[82:85], v[174:177], v[198:201], v[82:85]
	v_mfma_f32_16x16x32_bf16 v[74:77], v[166:169], v[212:215], v[74:77]
	v_mfma_f32_16x16x32_bf16 v[66:69], v[174:177], v[212:215], v[66:69]
	s_barrier
	s_setprio 0
	s_add_i32 s0, s33, s26
	s_mov_b32 m0, s0
	ds_read_b128 v[178:181], v145 offset:16384
	ds_read_b128 v[182:185], v145 offset:17408
	ds_read_b128 v[186:189], v145 offset:18432
	ds_read_b128 v[190:193], v145 offset:19456
	ds_read_b128 v[194:197], v145 offset:20480
	ds_read_b128 v[198:201], v145 offset:21504
	ds_read_b128 v[208:211], v145 offset:22528
	ds_read_b128 v[212:215], v145 offset:23552
	global_load_lds_dwordx4 v202, s[20:21]
	s_add_i32 m0, s0, 0x2000
	s_add_u32 s0, s20, 0x80000
	s_addc_u32 s1, s21, 0
	s_add_i32 s33, s55, s26
	global_load_lds_dwordx4 v130, s[20:21]
	s_mov_b32 m0, s33
	s_nop 0
	global_load_lds_dwordx4 v202, s[0:1]
	s_add_i32 m0, s33, 0x2000
	s_nop 0
	global_load_lds_dwordx4 v130, s[0:1]
	s_mov_b32 m0, s27
	s_nop 0
	global_load_lds_dwordx4 v134, s[22:23]
	s_mov_b32 m0, s28
	s_nop 0
	global_load_lds_dwordx4 v132, s[22:23]
	s_setprio 1
	s_waitcnt vmcnt(16) lgkmcnt(0)
	s_barrier
	v_mfma_f32_16x16x32_bf16 v[62:65], v[146:149], v[178:181], v[62:65]
	v_mfma_f32_16x16x32_bf16 v[54:57], v[154:157], v[178:181], v[54:57]
	v_mfma_f32_16x16x32_bf16 v[46:49], v[146:149], v[186:189], v[46:49]
	v_mfma_f32_16x16x32_bf16 v[38:41], v[154:157], v[186:189], v[38:41]
	v_mfma_f32_16x16x32_bf16 v[30:33], v[146:149], v[194:197], v[30:33]
	v_mfma_f32_16x16x32_bf16 v[22:25], v[154:157], v[194:197], v[22:25]
	v_mfma_f32_16x16x32_bf16 v[14:17], v[146:149], v[208:211], v[14:17]
	v_mfma_f32_16x16x32_bf16 v[6:9], v[154:157], v[208:211], v[6:9]
	v_mfma_f32_16x16x32_bf16 v[62:65], v[150:153], v[182:185], v[62:65]
	v_mfma_f32_16x16x32_bf16 v[54:57], v[158:161], v[182:185], v[54:57]
	v_mfma_f32_16x16x32_bf16 v[46:49], v[150:153], v[190:193], v[46:49]
	v_mfma_f32_16x16x32_bf16 v[38:41], v[158:161], v[190:193], v[38:41]
	v_mfma_f32_16x16x32_bf16 v[30:33], v[150:153], v[198:201], v[30:33]
	v_mfma_f32_16x16x32_bf16 v[22:25], v[158:161], v[198:201], v[22:25]
	v_mfma_f32_16x16x32_bf16 v[14:17], v[150:153], v[212:215], v[14:17]
	v_mfma_f32_16x16x32_bf16 v[6:9], v[158:161], v[212:215], v[6:9]
	v_mfma_f32_16x16x32_bf16 v[58:61], v[162:165], v[178:181], v[58:61]
	v_mfma_f32_16x16x32_bf16 v[50:53], v[170:173], v[178:181], v[50:53]
	v_mfma_f32_16x16x32_bf16 v[42:45], v[162:165], v[186:189], v[42:45]
	v_mfma_f32_16x16x32_bf16 v[34:37], v[170:173], v[186:189], v[34:37]
	v_mfma_f32_16x16x32_bf16 v[26:29], v[162:165], v[194:197], v[26:29]
	v_mfma_f32_16x16x32_bf16 v[18:21], v[170:173], v[194:197], v[18:21]
	v_mfma_f32_16x16x32_bf16 v[10:13], v[162:165], v[208:211], v[10:13]
	v_mfma_f32_16x16x32_bf16 v[2:5], v[170:173], v[208:211], v[2:5]
	v_mfma_f32_16x16x32_bf16 v[58:61], v[166:169], v[182:185], v[58:61]
	v_mfma_f32_16x16x32_bf16 v[50:53], v[174:177], v[182:185], v[50:53]
	v_mfma_f32_16x16x32_bf16 v[42:45], v[166:169], v[190:193], v[42:45]
	v_mfma_f32_16x16x32_bf16 v[34:37], v[174:177], v[190:193], v[34:37]
	v_mfma_f32_16x16x32_bf16 v[26:29], v[166:169], v[198:201], v[26:29]
	v_mfma_f32_16x16x32_bf16 v[18:21], v[174:177], v[198:201], v[18:21]
	v_mfma_f32_16x16x32_bf16 v[10:13], v[166:169], v[212:215], v[10:13]
	v_mfma_f32_16x16x32_bf16 v[2:5], v[174:177], v[212:215], v[2:5]
	s_barrier
	s_setprio 0
	s_branch .Lpeel_mid_3
.LBB0_837:
	s_add_u32 s0, s18, 0xfff80080
	s_addc_u32 s1, s19, -1
	s_add_i32 s33, 0, 0x10000
	s_cmp_eq_u32 s59, 28
	s_cselect_b32 s23, s11, s1
	s_cselect_b32 s22, s38, s0
	s_cselect_b32 s21, s9, s58
	s_cselect_b32 s20, s39, s49
	s_add_i32 s55, 0, 0x14000
	ds_read_b128 v[146:149], v143
	ds_read_b128 v[150:153], v143 offset:1024
	ds_read_b128 v[154:157], v143 offset:2048
	ds_read_b128 v[158:161], v143 offset:3072
	ds_read_b128 v[162:165], v143 offset:16384
	ds_read_b128 v[166:169], v143 offset:17408
	ds_read_b128 v[170:173], v143 offset:18432
	ds_read_b128 v[174:177], v143 offset:19456
	s_add_i32 m0, s27, 0xc000
	ds_read_b128 v[178:181], v145
	ds_read_b128 v[182:185], v145 offset:1024
	ds_read_b128 v[186:189], v145 offset:2048
	ds_read_b128 v[190:193], v145 offset:3072
	ds_read_b128 v[194:197], v145 offset:4096
	ds_read_b128 v[198:201], v145 offset:5120
	ds_read_b128 v[208:211], v145 offset:6144
	ds_read_b128 v[212:215], v145 offset:7168
	global_load_lds_dwordx4 v136, s[18:19]
	s_add_i32 m0, s27, 0xe000
	s_nop 0
	global_load_lds_dwordx4 v138, s[18:19]
	s_setprio 1
	s_waitcnt vmcnt(8) lgkmcnt(0)
	s_barrier
	v_mfma_f32_16x16x32_bf16 v[126:129], v[146:149], v[178:181], v[126:129]
	v_mfma_f32_16x16x32_bf16 v[118:121], v[154:157], v[178:181], v[118:121]
	v_mfma_f32_16x16x32_bf16 v[110:113], v[146:149], v[186:189], v[110:113]
	v_mfma_f32_16x16x32_bf16 v[102:105], v[154:157], v[186:189], v[102:105]
	v_mfma_f32_16x16x32_bf16 v[94:97], v[146:149], v[194:197], v[94:97]
	v_mfma_f32_16x16x32_bf16 v[86:89], v[154:157], v[194:197], v[86:89]
	v_mfma_f32_16x16x32_bf16 v[78:81], v[146:149], v[208:211], v[78:81]
	v_mfma_f32_16x16x32_bf16 v[70:73], v[154:157], v[208:211], v[70:73]
	v_mfma_f32_16x16x32_bf16 v[126:129], v[150:153], v[182:185], v[126:129]
	v_mfma_f32_16x16x32_bf16 v[118:121], v[158:161], v[182:185], v[118:121]
	v_mfma_f32_16x16x32_bf16 v[110:113], v[150:153], v[190:193], v[110:113]
	v_mfma_f32_16x16x32_bf16 v[102:105], v[158:161], v[190:193], v[102:105]
	v_mfma_f32_16x16x32_bf16 v[94:97], v[150:153], v[198:201], v[94:97]
	v_mfma_f32_16x16x32_bf16 v[86:89], v[158:161], v[198:201], v[86:89]
	v_mfma_f32_16x16x32_bf16 v[78:81], v[150:153], v[212:215], v[78:81]
	v_mfma_f32_16x16x32_bf16 v[70:73], v[158:161], v[212:215], v[70:73]
	v_mfma_f32_16x16x32_bf16 v[122:125], v[162:165], v[178:181], v[122:125]
	v_mfma_f32_16x16x32_bf16 v[114:117], v[170:173], v[178:181], v[114:117]
	v_mfma_f32_16x16x32_bf16 v[106:109], v[162:165], v[186:189], v[106:109]
	v_mfma_f32_16x16x32_bf16 v[98:101], v[170:173], v[186:189], v[98:101]
	v_mfma_f32_16x16x32_bf16 v[90:93], v[162:165], v[194:197], v[90:93]
	v_mfma_f32_16x16x32_bf16 v[82:85], v[170:173], v[194:197], v[82:85]
	v_mfma_f32_16x16x32_bf16 v[74:77], v[162:165], v[208:211], v[74:77]
	v_mfma_f32_16x16x32_bf16 v[66:69], v[170:173], v[208:211], v[66:69]
	v_mfma_f32_16x16x32_bf16 v[122:125], v[166:169], v[182:185], v[122:125]
	v_mfma_f32_16x16x32_bf16 v[114:117], v[174:177], v[182:185], v[114:117]
	v_mfma_f32_16x16x32_bf16 v[106:109], v[166:169], v[190:193], v[106:109]
	v_mfma_f32_16x16x32_bf16 v[98:101], v[174:177], v[190:193], v[98:101]
	v_mfma_f32_16x16x32_bf16 v[90:93], v[166:169], v[198:201], v[90:93]
	v_mfma_f32_16x16x32_bf16 v[82:85], v[174:177], v[198:201], v[82:85]
	v_mfma_f32_16x16x32_bf16 v[74:77], v[166:169], v[212:215], v[74:77]
	v_mfma_f32_16x16x32_bf16 v[66:69], v[174:177], v[212:215], v[66:69]
	s_barrier
	s_setprio 0
	s_add_i32 s0, s33, s26
	s_mov_b32 m0, s0
	ds_read_b128 v[178:181], v145 offset:16384
	ds_read_b128 v[182:185], v145 offset:17408
	ds_read_b128 v[186:189], v145 offset:18432
	ds_read_b128 v[190:193], v145 offset:19456
	ds_read_b128 v[194:197], v145 offset:20480
	ds_read_b128 v[198:201], v145 offset:21504
	ds_read_b128 v[208:211], v145 offset:22528
	ds_read_b128 v[212:215], v145 offset:23552
	global_load_lds_dwordx4 v202, s[20:21]
	s_add_i32 m0, s0, 0x2000
	s_add_u32 s0, s20, 0x80000
	s_addc_u32 s1, s21, 0
	s_add_i32 s33, s55, s26
	global_load_lds_dwordx4 v130, s[20:21]
	s_mov_b32 m0, s33
	s_nop 0
	global_load_lds_dwordx4 v202, s[0:1]
	s_add_i32 m0, s33, 0x2000
	s_nop 0
	global_load_lds_dwordx4 v130, s[0:1]
	s_mov_b32 m0, s27
	s_nop 0
	global_load_lds_dwordx4 v134, s[22:23]
	s_mov_b32 m0, s28
	s_nop 0
	global_load_lds_dwordx4 v132, s[22:23]
	s_setprio 1
	s_waitcnt vmcnt(8) lgkmcnt(0)
	s_barrier
	v_mfma_f32_16x16x32_bf16 v[62:65], v[146:149], v[178:181], v[62:65]
	v_mfma_f32_16x16x32_bf16 v[54:57], v[154:157], v[178:181], v[54:57]
	v_mfma_f32_16x16x32_bf16 v[46:49], v[146:149], v[186:189], v[46:49]
	v_mfma_f32_16x16x32_bf16 v[38:41], v[154:157], v[186:189], v[38:41]
	v_mfma_f32_16x16x32_bf16 v[30:33], v[146:149], v[194:197], v[30:33]
	v_mfma_f32_16x16x32_bf16 v[22:25], v[154:157], v[194:197], v[22:25]
	v_mfma_f32_16x16x32_bf16 v[14:17], v[146:149], v[208:211], v[14:17]
	v_mfma_f32_16x16x32_bf16 v[6:9], v[154:157], v[208:211], v[6:9]
	v_mfma_f32_16x16x32_bf16 v[62:65], v[150:153], v[182:185], v[62:65]
	v_mfma_f32_16x16x32_bf16 v[54:57], v[158:161], v[182:185], v[54:57]
	v_mfma_f32_16x16x32_bf16 v[46:49], v[150:153], v[190:193], v[46:49]
	v_mfma_f32_16x16x32_bf16 v[38:41], v[158:161], v[190:193], v[38:41]
	v_mfma_f32_16x16x32_bf16 v[30:33], v[150:153], v[198:201], v[30:33]
	v_mfma_f32_16x16x32_bf16 v[22:25], v[158:161], v[198:201], v[22:25]
	v_mfma_f32_16x16x32_bf16 v[14:17], v[150:153], v[212:215], v[14:17]
	v_mfma_f32_16x16x32_bf16 v[6:9], v[158:161], v[212:215], v[6:9]
	v_mfma_f32_16x16x32_bf16 v[58:61], v[162:165], v[178:181], v[58:61]
	v_mfma_f32_16x16x32_bf16 v[50:53], v[170:173], v[178:181], v[50:53]
	v_mfma_f32_16x16x32_bf16 v[42:45], v[162:165], v[186:189], v[42:45]
	v_mfma_f32_16x16x32_bf16 v[34:37], v[170:173], v[186:189], v[34:37]
	v_mfma_f32_16x16x32_bf16 v[26:29], v[162:165], v[194:197], v[26:29]
	v_mfma_f32_16x16x32_bf16 v[18:21], v[170:173], v[194:197], v[18:21]
	v_mfma_f32_16x16x32_bf16 v[10:13], v[162:165], v[208:211], v[10:13]
	v_mfma_f32_16x16x32_bf16 v[2:5], v[170:173], v[208:211], v[2:5]
	v_mfma_f32_16x16x32_bf16 v[58:61], v[166:169], v[182:185], v[58:61]
	v_mfma_f32_16x16x32_bf16 v[50:53], v[174:177], v[182:185], v[50:53]
	v_mfma_f32_16x16x32_bf16 v[42:45], v[166:169], v[190:193], v[42:45]
	v_mfma_f32_16x16x32_bf16 v[34:37], v[174:177], v[190:193], v[34:37]
	v_mfma_f32_16x16x32_bf16 v[26:29], v[166:169], v[198:201], v[26:29]
	v_mfma_f32_16x16x32_bf16 v[18:21], v[174:177], v[198:201], v[18:21]
	v_mfma_f32_16x16x32_bf16 v[10:13], v[166:169], v[212:215], v[10:13]
	v_mfma_f32_16x16x32_bf16 v[2:5], v[174:177], v[212:215], v[2:5]
	s_barrier
	s_setprio 0
.Lpeel_mid_3:
	s_add_i32 s33, 0, 0x18000
	s_add_i32 s55, 0, 0x1c000
	ds_read_b128 v[146:149], v143 offset:32768
	ds_read_b128 v[150:153], v143 offset:33792
	ds_read_b128 v[154:157], v143 offset:34816
	ds_read_b128 v[158:161], v143 offset:35840
	ds_read_b128 v[162:165], v143 offset:49152
	ds_read_b128 v[166:169], v143 offset:50176
	ds_read_b128 v[170:173], v143 offset:51200
	ds_read_b128 v[174:177], v143 offset:52224
	s_add_u32 s0, s22, 0x80000
	s_addc_u32 s1, s23, 0
	s_mov_b32 m0, s29
	ds_read_b128 v[178:181], v145 offset:32768
	ds_read_b128 v[182:185], v145 offset:33792
	ds_read_b128 v[186:189], v145 offset:34816
	ds_read_b128 v[190:193], v145 offset:35840
	ds_read_b128 v[194:197], v145 offset:36864
	ds_read_b128 v[198:201], v145 offset:37888
	ds_read_b128 v[208:211], v145 offset:38912
	ds_read_b128 v[212:215], v145 offset:39936
	global_load_lds_dwordx4 v134, s[0:1]
	s_mov_b32 m0, s30
	s_nop 0
	global_load_lds_dwordx4 v132, s[0:1]
	s_setprio 1
	s_waitcnt vmcnt(8) lgkmcnt(0)
	s_barrier
	v_mfma_f32_16x16x32_bf16 v[126:129], v[146:149], v[178:181], v[126:129]
	v_mfma_f32_16x16x32_bf16 v[118:121], v[154:157], v[178:181], v[118:121]
	v_mfma_f32_16x16x32_bf16 v[110:113], v[146:149], v[186:189], v[110:113]
	v_mfma_f32_16x16x32_bf16 v[102:105], v[154:157], v[186:189], v[102:105]
	v_mfma_f32_16x16x32_bf16 v[94:97], v[146:149], v[194:197], v[94:97]
	v_mfma_f32_16x16x32_bf16 v[86:89], v[154:157], v[194:197], v[86:89]
	v_mfma_f32_16x16x32_bf16 v[78:81], v[146:149], v[208:211], v[78:81]
	v_mfma_f32_16x16x32_bf16 v[70:73], v[154:157], v[208:211], v[70:73]
	v_mfma_f32_16x16x32_bf16 v[126:129], v[150:153], v[182:185], v[126:129]
	v_mfma_f32_16x16x32_bf16 v[118:121], v[158:161], v[182:185], v[118:121]
	v_mfma_f32_16x16x32_bf16 v[110:113], v[150:153], v[190:193], v[110:113]
	v_mfma_f32_16x16x32_bf16 v[102:105], v[158:161], v[190:193], v[102:105]
	v_mfma_f32_16x16x32_bf16 v[94:97], v[150:153], v[198:201], v[94:97]
	v_mfma_f32_16x16x32_bf16 v[86:89], v[158:161], v[198:201], v[86:89]
	v_mfma_f32_16x16x32_bf16 v[78:81], v[150:153], v[212:215], v[78:81]
	v_mfma_f32_16x16x32_bf16 v[70:73], v[158:161], v[212:215], v[70:73]
	v_mfma_f32_16x16x32_bf16 v[122:125], v[162:165], v[178:181], v[122:125]
	v_mfma_f32_16x16x32_bf16 v[114:117], v[170:173], v[178:181], v[114:117]
	v_mfma_f32_16x16x32_bf16 v[106:109], v[162:165], v[186:189], v[106:109]
	v_mfma_f32_16x16x32_bf16 v[98:101], v[170:173], v[186:189], v[98:101]
	v_mfma_f32_16x16x32_bf16 v[90:93], v[162:165], v[194:197], v[90:93]
	v_mfma_f32_16x16x32_bf16 v[82:85], v[170:173], v[194:197], v[82:85]
	v_mfma_f32_16x16x32_bf16 v[74:77], v[162:165], v[208:211], v[74:77]
	v_mfma_f32_16x16x32_bf16 v[66:69], v[170:173], v[208:211], v[66:69]
	v_mfma_f32_16x16x32_bf16 v[122:125], v[166:169], v[182:185], v[122:125]
	v_mfma_f32_16x16x32_bf16 v[114:117], v[174:177], v[182:185], v[114:117]
	v_mfma_f32_16x16x32_bf16 v[106:109], v[166:169], v[190:193], v[106:109]
	v_mfma_f32_16x16x32_bf16 v[98:101], v[174:177], v[190:193], v[98:101]
	v_mfma_f32_16x16x32_bf16 v[90:93], v[166:169], v[198:201], v[90:93]
	v_mfma_f32_16x16x32_bf16 v[82:85], v[174:177], v[198:201], v[82:85]
	v_mfma_f32_16x16x32_bf16 v[74:77], v[166:169], v[212:215], v[74:77]
	v_mfma_f32_16x16x32_bf16 v[66:69], v[174:177], v[212:215], v[66:69]
	s_barrier
	s_setprio 0
	s_add_i32 s0, s33, s26
	s_add_u32 s100, s20, 0x80
	s_addc_u32 s101, s21, 0
	s_mov_b32 m0, s0
	ds_read_b128 v[178:181], v145 offset:49152
	ds_read_b128 v[182:185], v145 offset:50176
	ds_read_b128 v[186:189], v145 offset:51200
	ds_read_b128 v[190:193], v145 offset:52224
	ds_read_b128 v[194:197], v145 offset:53248
	ds_read_b128 v[198:201], v145 offset:54272
	ds_read_b128 v[208:211], v145 offset:55296
	ds_read_b128 v[212:215], v145 offset:56320
	global_load_lds_dwordx4 v202, s[100:101]
	s_add_i32 m0, s0, 0x2000
	s_add_u32 s100, s20, 0x80
	s_addc_u32 s101, s21, 0
	s_add_u32 s0, s20, 0x80080
	s_addc_u32 s1, s21, 0
	s_add_i32 s20, s55, s26
	global_load_lds_dwordx4 v130, s[100:101]
	s_mov_b32 m0, s20
	s_nop 0
	global_load_lds_dwordx4 v202, s[0:1]
	s_add_i32 m0, s20, 0x2000
	s_nop 0
	global_load_lds_dwordx4 v130, s[0:1]
	s_add_u32 s100, s22, 0x80
	s_addc_u32 s101, s23, 0
	s_mov_b32 m0, s31
	s_nop 0
	global_load_lds_dwordx4 v134, s[100:101]
	s_add_u32 s100, s22, 0x80
	s_addc_u32 s101, s23, 0
	s_mov_b32 m0, s34
	s_nop 0
	global_load_lds_dwordx4 v132, s[100:101]
	s_setprio 1
	s_waitcnt vmcnt(8) lgkmcnt(0)
	s_barrier
	v_mfma_f32_16x16x32_bf16 v[62:65], v[146:149], v[178:181], v[62:65]
	v_mfma_f32_16x16x32_bf16 v[54:57], v[154:157], v[178:181], v[54:57]
	v_mfma_f32_16x16x32_bf16 v[46:49], v[146:149], v[186:189], v[46:49]
	v_mfma_f32_16x16x32_bf16 v[38:41], v[154:157], v[186:189], v[38:41]
	v_mfma_f32_16x16x32_bf16 v[30:33], v[146:149], v[194:197], v[30:33]
	v_mfma_f32_16x16x32_bf16 v[22:25], v[154:157], v[194:197], v[22:25]
	v_mfma_f32_16x16x32_bf16 v[14:17], v[146:149], v[208:211], v[14:17]
	v_mfma_f32_16x16x32_bf16 v[6:9], v[154:157], v[208:211], v[6:9]
	v_mfma_f32_16x16x32_bf16 v[62:65], v[150:153], v[182:185], v[62:65]
	v_mfma_f32_16x16x32_bf16 v[54:57], v[158:161], v[182:185], v[54:57]
	v_mfma_f32_16x16x32_bf16 v[46:49], v[150:153], v[190:193], v[46:49]
	v_mfma_f32_16x16x32_bf16 v[38:41], v[158:161], v[190:193], v[38:41]
	v_mfma_f32_16x16x32_bf16 v[30:33], v[150:153], v[198:201], v[30:33]
	v_mfma_f32_16x16x32_bf16 v[22:25], v[158:161], v[198:201], v[22:25]
	v_mfma_f32_16x16x32_bf16 v[14:17], v[150:153], v[212:215], v[14:17]
	v_mfma_f32_16x16x32_bf16 v[6:9], v[158:161], v[212:215], v[6:9]
	v_mfma_f32_16x16x32_bf16 v[58:61], v[162:165], v[178:181], v[58:61]
	v_mfma_f32_16x16x32_bf16 v[50:53], v[170:173], v[178:181], v[50:53]
	v_mfma_f32_16x16x32_bf16 v[42:45], v[162:165], v[186:189], v[42:45]
	v_mfma_f32_16x16x32_bf16 v[34:37], v[170:173], v[186:189], v[34:37]
	v_mfma_f32_16x16x32_bf16 v[26:29], v[162:165], v[194:197], v[26:29]
	v_mfma_f32_16x16x32_bf16 v[18:21], v[170:173], v[194:197], v[18:21]
	v_mfma_f32_16x16x32_bf16 v[10:13], v[162:165], v[208:211], v[10:13]
	v_mfma_f32_16x16x32_bf16 v[2:5], v[170:173], v[208:211], v[2:5]
	v_mfma_f32_16x16x32_bf16 v[58:61], v[166:169], v[182:185], v[58:61]
	v_mfma_f32_16x16x32_bf16 v[50:53], v[174:177], v[182:185], v[50:53]
	v_mfma_f32_16x16x32_bf16 v[42:45], v[166:169], v[190:193], v[42:45]
	v_mfma_f32_16x16x32_bf16 v[34:37], v[174:177], v[190:193], v[34:37]
	v_mfma_f32_16x16x32_bf16 v[26:29], v[166:169], v[198:201], v[26:29]
	v_mfma_f32_16x16x32_bf16 v[18:21], v[174:177], v[198:201], v[18:21]
	v_mfma_f32_16x16x32_bf16 v[10:13], v[166:169], v[212:215], v[10:13]
	v_mfma_f32_16x16x32_bf16 v[2:5], v[174:177], v[212:215], v[2:5]
	s_barrier
	s_setprio 0
	s_add_i32 s59, s59, 2
	s_add_u32 s18, s18, 0x100
	s_addc_u32 s19, s19, 0
	s_add_u32 s49, s49, 0x100
	s_addc_u32 s58, s58, 0
	s_cmp_gt_u32 s59, 29
	s_cbranch_scc0 .LBB0_837
	s_mov_b32 s101, 0x80000001
	s_and_b64 vcc, exec, s[6:7]
	s_cbranch_vccz .LBB0_840
	s_barrier

.LBB0_970:
	s_add_u32 s16, s2, 0x100
	s_addc_u32 s17, s3, 0
	s_add_i32 s0, 0, 0x10000
	s_cmpk_eq_i32 s59, 0x54
	s_cselect_b32 s21, s7, s17
	s_cselect_b32 s20, s6, s16
	s_cselect_b32 s19, s15, s58
	s_cselect_b32 s18, s14, s49
	s_add_i32 s33, 0, 0x14000
	ds_read_b128 v[78:81], v205
	ds_read_b128 v[82:85], v205 offset:1024
	ds_read_b128 v[94:97], v205 offset:2048
	ds_read_b128 v[98:101], v205 offset:3072
	ds_read_b128 v[106:109], v205 offset:16384
	ds_read_b128 v[110:113], v205 offset:17408
	ds_read_b128 v[126:129], v205 offset:18432
	ds_read_b128 v[134:137], v205 offset:19456
	s_add_i32 m0, s25, 0xc000
	ds_read_b128 v[146:149], v239
	ds_read_b128 v[158:161], v239 offset:1024
	ds_read_b128 v[166:169], v239 offset:2048
	ds_read_b128 v[174:177], v239 offset:3072
	ds_read_b128 v[178:181], v239 offset:4096
	ds_read_b128 v[182:185], v239 offset:5120
	ds_read_b128 v[186:189], v239 offset:6144
	ds_read_b128 v[190:193], v239 offset:7168
	global_load_lds_dwordx4 v214, s[2:3]
	s_add_i32 m0, s25, 0xe000
	s_nop 0
	global_load_lds_dwordx4 v216, s[2:3]
	s_setprio 1
	s_waitcnt vmcnt(8) lgkmcnt(0)
	s_barrier
	v_mfma_f32_16x16x32_bf16 v[170:173], v[78:81], v[146:149], v[170:173]
	v_mfma_f32_16x16x32_bf16 v[162:165], v[94:97], v[146:149], v[162:165]
	v_mfma_f32_16x16x32_bf16 v[142:145], v[78:81], v[166:169], v[142:145]
	v_mfma_f32_16x16x32_bf16 v[138:141], v[94:97], v[166:169], v[138:141]
	v_mfma_f32_16x16x32_bf16 v[118:121], v[78:81], v[178:181], v[118:121]
	v_mfma_f32_16x16x32_bf16 v[114:117], v[94:97], v[178:181], v[114:117]
	v_mfma_f32_16x16x32_bf16 v[86:89], v[78:81], v[186:189], v[86:89]
	v_mfma_f32_16x16x32_bf16 v[74:77], v[94:97], v[186:189], v[74:77]
	v_mfma_f32_16x16x32_bf16 v[170:173], v[82:85], v[158:161], v[170:173]
	v_mfma_f32_16x16x32_bf16 v[162:165], v[98:101], v[158:161], v[162:165]
	v_mfma_f32_16x16x32_bf16 v[142:145], v[82:85], v[174:177], v[142:145]
	v_mfma_f32_16x16x32_bf16 v[138:141], v[98:101], v[174:177], v[138:141]
	v_mfma_f32_16x16x32_bf16 v[118:121], v[82:85], v[182:185], v[118:121]
	v_mfma_f32_16x16x32_bf16 v[114:117], v[98:101], v[182:185], v[114:117]
	v_mfma_f32_16x16x32_bf16 v[86:89], v[82:85], v[190:193], v[86:89]
	v_mfma_f32_16x16x32_bf16 v[74:77], v[98:101], v[190:193], v[74:77]
	v_mfma_f32_16x16x32_bf16 v[154:157], v[106:109], v[146:149], v[154:157]
	v_mfma_f32_16x16x32_bf16 v[130:133], v[106:109], v[166:169], v[130:133]
	v_mfma_f32_16x16x32_bf16 v[122:125], v[126:129], v[166:169], v[122:125]
	v_mfma_f32_16x16x32_bf16 v[102:105], v[106:109], v[178:181], v[102:105]
	v_mfma_f32_16x16x32_bf16 v[90:93], v[126:129], v[178:181], v[90:93]
	v_mfma_f32_16x16x32_bf16 v[70:73], v[106:109], v[186:189], v[70:73]
	v_mfma_f32_16x16x32_bf16 v[66:69], v[126:129], v[186:189], v[66:69]
	v_mfma_f32_16x16x32_bf16 v[154:157], v[110:113], v[158:161], v[154:157]
	v_mfma_f32_16x16x32_bf16 v[146:149], v[126:129], v[146:149], v[150:153]
	v_mfma_f32_16x16x32_bf16 v[130:133], v[110:113], v[174:177], v[130:133]
	v_mfma_f32_16x16x32_bf16 v[122:125], v[134:137], v[174:177], v[122:125]
	v_mfma_f32_16x16x32_bf16 v[102:105], v[110:113], v[182:185], v[102:105]
	v_mfma_f32_16x16x32_bf16 v[90:93], v[134:137], v[182:185], v[90:93]
	v_mfma_f32_16x16x32_bf16 v[70:73], v[110:113], v[190:193], v[70:73]
	v_mfma_f32_16x16x32_bf16 v[66:69], v[134:137], v[190:193], v[66:69]
	v_mfma_f32_16x16x32_bf16 v[146:149], v[134:137], v[158:161], v[146:149]
	s_barrier
	s_setprio 0
	s_add_i32 s0, s0, s24
	s_mov_b32 m0, s0
	ds_read_b128 v[150:153], v239 offset:16384
	ds_read_b128 v[158:161], v239 offset:17408
	ds_read_b128 v[166:169], v239 offset:18432
	ds_read_b128 v[174:177], v239 offset:19456
	ds_read_b128 v[178:181], v239 offset:20480
	ds_read_b128 v[182:185], v239 offset:21504
	ds_read_b128 v[186:189], v239 offset:22528
	ds_read_b128 v[190:193], v239 offset:23552
	global_load_lds_dwordx4 v202, s[18:19]
	s_add_i32 m0, s0, 0x2000
	s_add_u32 s0, s18, 0x160000
	s_addc_u32 s1, s19, 0
	s_add_i32 s2, s33, s24
	global_load_lds_dwordx4 v208, s[18:19]
	s_mov_b32 m0, s2
	s_nop 0
	global_load_lds_dwordx4 v202, s[0:1]
	s_add_i32 m0, s2, 0x2000
	s_nop 0
	global_load_lds_dwordx4 v208, s[0:1]
	s_mov_b32 m0, s25
	s_nop 0
	global_load_lds_dwordx4 v212, s[20:21]
	s_mov_b32 m0, s26
	s_nop 0
	global_load_lds_dwordx4 v210, s[20:21]
	s_setprio 1
	s_waitcnt vmcnt(8) lgkmcnt(0)
	s_barrier
	v_mfma_f32_16x16x32_bf16 v[62:65], v[78:81], v[150:153], v[62:65]
	v_mfma_f32_16x16x32_bf16 v[58:61], v[94:97], v[150:153], v[58:61]
	v_mfma_f32_16x16x32_bf16 v[46:49], v[78:81], v[166:169], v[46:49]
	v_mfma_f32_16x16x32_bf16 v[42:45], v[94:97], v[166:169], v[42:45]
	v_mfma_f32_16x16x32_bf16 v[30:33], v[78:81], v[178:181], v[30:33]
	v_mfma_f32_16x16x32_bf16 v[26:29], v[94:97], v[178:181], v[26:29]
	v_mfma_f32_16x16x32_bf16 v[14:17], v[78:81], v[186:189], v[14:17]
	v_mfma_f32_16x16x32_bf16 v[10:13], v[94:97], v[186:189], v[10:13]
	v_mfma_f32_16x16x32_bf16 v[62:65], v[82:85], v[158:161], v[62:65]
	v_mfma_f32_16x16x32_bf16 v[58:61], v[98:101], v[158:161], v[58:61]
	v_mfma_f32_16x16x32_bf16 v[46:49], v[82:85], v[174:177], v[46:49]
	v_mfma_f32_16x16x32_bf16 v[42:45], v[98:101], v[174:177], v[42:45]
	v_mfma_f32_16x16x32_bf16 v[30:33], v[82:85], v[182:185], v[30:33]
	v_mfma_f32_16x16x32_bf16 v[26:29], v[98:101], v[182:185], v[26:29]
	v_mfma_f32_16x16x32_bf16 v[14:17], v[82:85], v[190:193], v[14:17]
	v_mfma_f32_16x16x32_bf16 v[10:13], v[98:101], v[190:193], v[10:13]
	v_mfma_f32_16x16x32_bf16 v[54:57], v[106:109], v[150:153], v[54:57]
	v_mfma_f32_16x16x32_bf16 v[50:53], v[126:129], v[150:153], v[50:53]
	v_mfma_f32_16x16x32_bf16 v[38:41], v[106:109], v[166:169], v[38:41]
	v_mfma_f32_16x16x32_bf16 v[34:37], v[126:129], v[166:169], v[34:37]
	v_mfma_f32_16x16x32_bf16 v[22:25], v[106:109], v[178:181], v[22:25]
	v_mfma_f32_16x16x32_bf16 v[18:21], v[126:129], v[178:181], v[18:21]
	v_mfma_f32_16x16x32_bf16 v[6:9], v[106:109], v[186:189], v[6:9]
	v_mfma_f32_16x16x32_bf16 v[2:5], v[126:129], v[186:189], v[2:5]
	v_mfma_f32_16x16x32_bf16 v[54:57], v[110:113], v[158:161], v[54:57]
	v_mfma_f32_16x16x32_bf16 v[50:53], v[134:137], v[158:161], v[50:53]
	v_mfma_f32_16x16x32_bf16 v[38:41], v[110:113], v[174:177], v[38:41]
	v_mfma_f32_16x16x32_bf16 v[34:37], v[134:137], v[174:177], v[34:37]
	v_mfma_f32_16x16x32_bf16 v[22:25], v[110:113], v[182:185], v[22:25]
	v_mfma_f32_16x16x32_bf16 v[18:21], v[134:137], v[182:185], v[18:21]
	v_mfma_f32_16x16x32_bf16 v[6:9], v[110:113], v[190:193], v[6:9]
	v_mfma_f32_16x16x32_bf16 v[2:5], v[134:137], v[190:193], v[2:5]
	s_barrier
	s_setprio 0
	s_add_i32 s2, 0, 0x18000
	s_add_i32 s3, 0, 0x1c000
	ds_read_b128 v[78:81], v205 offset:32768
	ds_read_b128 v[82:85], v205 offset:33792
	ds_read_b128 v[94:97], v205 offset:34816
	ds_read_b128 v[98:101], v205 offset:35840
	ds_read_b128 v[106:109], v205 offset:49152
	ds_read_b128 v[110:113], v205 offset:50176
	ds_read_b128 v[126:129], v205 offset:51200
	ds_read_b128 v[134:137], v205 offset:52224
	s_add_u32 s0, s20, 0x160000
	s_addc_u32 s1, s21, 0
	s_mov_b32 m0, s27
	ds_read_b128 v[150:153], v239 offset:32768
	ds_read_b128 v[158:161], v239 offset:33792
	ds_read_b128 v[166:169], v239 offset:34816
	ds_read_b128 v[174:177], v239 offset:35840
	ds_read_b128 v[178:181], v239 offset:36864
	ds_read_b128 v[182:185], v239 offset:37888
	ds_read_b128 v[186:189], v239 offset:38912
	ds_read_b128 v[190:193], v239 offset:39936
	global_load_lds_dwordx4 v212, s[0:1]
	s_mov_b32 m0, s28
	s_nop 0
	global_load_lds_dwordx4 v210, s[0:1]
	s_setprio 1
	s_waitcnt vmcnt(8) lgkmcnt(0)
	s_barrier
	v_mfma_f32_16x16x32_bf16 v[170:173], v[78:81], v[150:153], v[170:173]
	v_mfma_f32_16x16x32_bf16 v[162:165], v[94:97], v[150:153], v[162:165]
	v_mfma_f32_16x16x32_bf16 v[142:145], v[78:81], v[166:169], v[142:145]
	v_mfma_f32_16x16x32_bf16 v[138:141], v[94:97], v[166:169], v[138:141]
	v_mfma_f32_16x16x32_bf16 v[118:121], v[78:81], v[178:181], v[118:121]
	v_mfma_f32_16x16x32_bf16 v[114:117], v[94:97], v[178:181], v[114:117]
	v_mfma_f32_16x16x32_bf16 v[86:89], v[78:81], v[186:189], v[86:89]
	v_mfma_f32_16x16x32_bf16 v[74:77], v[94:97], v[186:189], v[74:77]
	v_mfma_f32_16x16x32_bf16 v[170:173], v[82:85], v[158:161], v[170:173]
	v_mfma_f32_16x16x32_bf16 v[162:165], v[98:101], v[158:161], v[162:165]
	v_mfma_f32_16x16x32_bf16 v[142:145], v[82:85], v[174:177], v[142:145]
	v_mfma_f32_16x16x32_bf16 v[138:141], v[98:101], v[174:177], v[138:141]
	v_mfma_f32_16x16x32_bf16 v[118:121], v[82:85], v[182:185], v[118:121]
	v_mfma_f32_16x16x32_bf16 v[114:117], v[98:101], v[182:185], v[114:117]
	v_mfma_f32_16x16x32_bf16 v[86:89], v[82:85], v[190:193], v[86:89]
	v_mfma_f32_16x16x32_bf16 v[74:77], v[98:101], v[190:193], v[74:77]
	v_mfma_f32_16x16x32_bf16 v[154:157], v[106:109], v[150:153], v[154:157]
	v_mfma_f32_16x16x32_bf16 v[146:149], v[126:129], v[150:153], v[146:149]
	v_mfma_f32_16x16x32_bf16 v[130:133], v[106:109], v[166:169], v[130:133]
	v_mfma_f32_16x16x32_bf16 v[122:125], v[126:129], v[166:169], v[122:125]
	v_mfma_f32_16x16x32_bf16 v[102:105], v[106:109], v[178:181], v[102:105]
	v_mfma_f32_16x16x32_bf16 v[90:93], v[126:129], v[178:181], v[90:93]
	v_mfma_f32_16x16x32_bf16 v[70:73], v[106:109], v[186:189], v[70:73]
	v_mfma_f32_16x16x32_bf16 v[66:69], v[126:129], v[186:189], v[66:69]
	v_mfma_f32_16x16x32_bf16 v[154:157], v[110:113], v[158:161], v[154:157]
	v_mfma_f32_16x16x32_bf16 v[150:153], v[134:137], v[158:161], v[146:149]
	v_mfma_f32_16x16x32_bf16 v[130:133], v[110:113], v[174:177], v[130:133]
	v_mfma_f32_16x16x32_bf16 v[122:125], v[134:137], v[174:177], v[122:125]
	v_mfma_f32_16x16x32_bf16 v[102:105], v[110:113], v[182:185], v[102:105]
	v_mfma_f32_16x16x32_bf16 v[90:93], v[134:137], v[182:185], v[90:93]
	v_mfma_f32_16x16x32_bf16 v[70:73], v[110:113], v[190:193], v[70:73]
	v_mfma_f32_16x16x32_bf16 v[66:69], v[134:137], v[190:193], v[66:69]
	s_barrier
	s_setprio 0
	s_add_i32 s0, s2, s24
	s_add_u32 s100, s18, 0x80
	s_addc_u32 s101, s19, 0
	s_mov_b32 m0, s0
	ds_read_b128 v[146:149], v239 offset:49152
	ds_read_b128 v[158:161], v239 offset:50176
	ds_read_b128 v[166:169], v239 offset:51200
	ds_read_b128 v[174:177], v239 offset:52224
	ds_read_b128 v[178:181], v239 offset:53248
	ds_read_b128 v[182:185], v239 offset:54272
	ds_read_b128 v[186:189], v239 offset:55296
	ds_read_b128 v[190:193], v239 offset:56320
	global_load_lds_dwordx4 v202, s[100:101]
	s_add_i32 m0, s0, 0x2000
	s_add_u32 s100, s18, 0x80
	s_addc_u32 s101, s19, 0
	s_add_u32 s0, s18, 0x160080
	s_addc_u32 s1, s19, 0
	s_add_i32 s2, s3, s24
	global_load_lds_dwordx4 v208, s[100:101]
	s_mov_b32 m0, s2
	s_nop 0
	global_load_lds_dwordx4 v202, s[0:1]
	s_add_i32 m0, s2, 0x2000
	s_nop 0
	global_load_lds_dwordx4 v208, s[0:1]
	s_add_u32 s100, s20, 0x80
	s_addc_u32 s101, s21, 0
	s_mov_b32 m0, s31
	s_nop 0
	global_load_lds_dwordx4 v212, s[100:101]
	s_add_u32 s100, s20, 0x80
	s_addc_u32 s101, s21, 0
	s_mov_b32 m0, s34
	s_nop 0
	global_load_lds_dwordx4 v210, s[100:101]
	s_setprio 1
	s_waitcnt vmcnt(8) lgkmcnt(0)
	s_barrier
	v_mfma_f32_16x16x32_bf16 v[62:65], v[78:81], v[146:149], v[62:65]
	v_mfma_f32_16x16x32_bf16 v[58:61], v[94:97], v[146:149], v[58:61]
	v_mfma_f32_16x16x32_bf16 v[46:49], v[78:81], v[166:169], v[46:49]
	v_mfma_f32_16x16x32_bf16 v[42:45], v[94:97], v[166:169], v[42:45]
	v_mfma_f32_16x16x32_bf16 v[30:33], v[78:81], v[178:181], v[30:33]
	v_mfma_f32_16x16x32_bf16 v[26:29], v[94:97], v[178:181], v[26:29]
	v_mfma_f32_16x16x32_bf16 v[14:17], v[78:81], v[186:189], v[14:17]
	v_mfma_f32_16x16x32_bf16 v[10:13], v[94:97], v[186:189], v[10:13]
	v_mfma_f32_16x16x32_bf16 v[62:65], v[82:85], v[158:161], v[62:65]
	v_mfma_f32_16x16x32_bf16 v[58:61], v[98:101], v[158:161], v[58:61]
	v_mfma_f32_16x16x32_bf16 v[46:49], v[82:85], v[174:177], v[46:49]
	v_mfma_f32_16x16x32_bf16 v[42:45], v[98:101], v[174:177], v[42:45]
	v_mfma_f32_16x16x32_bf16 v[30:33], v[82:85], v[182:185], v[30:33]
	v_mfma_f32_16x16x32_bf16 v[26:29], v[98:101], v[182:185], v[26:29]
	v_mfma_f32_16x16x32_bf16 v[14:17], v[82:85], v[190:193], v[14:17]
	v_mfma_f32_16x16x32_bf16 v[10:13], v[98:101], v[190:193], v[10:13]
	v_mfma_f32_16x16x32_bf16 v[54:57], v[106:109], v[146:149], v[54:57]
	v_mfma_f32_16x16x32_bf16 v[50:53], v[126:129], v[146:149], v[50:53]
	v_mfma_f32_16x16x32_bf16 v[38:41], v[106:109], v[166:169], v[38:41]
	v_mfma_f32_16x16x32_bf16 v[34:37], v[126:129], v[166:169], v[34:37]
	v_mfma_f32_16x16x32_bf16 v[22:25], v[106:109], v[178:181], v[22:25]
	v_mfma_f32_16x16x32_bf16 v[18:21], v[126:129], v[178:181], v[18:21]
	v_mfma_f32_16x16x32_bf16 v[6:9], v[106:109], v[186:189], v[6:9]
	v_mfma_f32_16x16x32_bf16 v[2:5], v[126:129], v[186:189], v[2:5]
	v_mfma_f32_16x16x32_bf16 v[54:57], v[110:113], v[158:161], v[54:57]
	v_mfma_f32_16x16x32_bf16 v[50:53], v[134:137], v[158:161], v[50:53]
	v_mfma_f32_16x16x32_bf16 v[38:41], v[110:113], v[174:177], v[38:41]
	v_mfma_f32_16x16x32_bf16 v[34:37], v[134:137], v[174:177], v[34:37]
	v_mfma_f32_16x16x32_bf16 v[22:25], v[110:113], v[182:185], v[22:25]
	v_mfma_f32_16x16x32_bf16 v[18:21], v[134:137], v[182:185], v[18:21]
	v_mfma_f32_16x16x32_bf16 v[6:9], v[110:113], v[190:193], v[6:9]
	v_mfma_f32_16x16x32_bf16 v[2:5], v[134:137], v[190:193], v[2:5]
	s_barrier
	s_setprio 0
	s_add_i32 s59, s59, 2
	s_add_u32 s49, s49, 0x100
	s_addc_u32 s58, s58, 0
	s_cmpk_gt_u32 s59, 0x55
	s_mov_b64 s[2:3], s[16:17]
	s_cbranch_scc0 .LBB0_970
	s_and_b64 vcc, exec, s[10:11]
	s_cbranch_vccz .LBB0_973
	s_barrier

.LBB0_990:
	s_add_u32 s4, s2, 0x100
	s_addc_u32 s5, s3, 0
	s_add_i32 s0, 0, 0x10000
	s_cmp_eq_u32 s59, 4
	s_cselect_b32 s21, s15, s5
	s_cselect_b32 s20, s14, s4
	s_cselect_b32 s19, s17, s58
	s_cselect_b32 s18, s16, s49
	s_add_i32 s33, 0, 0x14000
	ds_read_b128 v[140:143], v136
	ds_read_b128 v[144:147], v136 offset:1024
	ds_read_b128 v[148:151], v136 offset:2048
	ds_read_b128 v[152:155], v136 offset:3072
	ds_read_b128 v[156:159], v136 offset:16384
	ds_read_b128 v[160:163], v136 offset:17408
	ds_read_b128 v[164:167], v136 offset:18432
	ds_read_b128 v[168:171], v136 offset:19456
	s_add_i32 m0, s25, 0xc000
	ds_read_b128 v[172:175], v139
	ds_read_b128 v[176:179], v139 offset:1024
	ds_read_b128 v[180:183], v139 offset:2048
	ds_read_b128 v[184:187], v139 offset:3072
	ds_read_b128 v[188:191], v139 offset:4096
	ds_read_b128 v[192:195], v139 offset:5120
	ds_read_b128 v[196:199], v139 offset:6144
	ds_read_b128 v[208:211], v139 offset:7168
	global_load_lds_dwordx4 v132, s[2:3]
	s_add_i32 m0, s25, 0xe000
	s_nop 0
	global_load_lds_dwordx4 v134, s[2:3]
	s_setprio 1
	s_waitcnt vmcnt(8) lgkmcnt(0)
	s_barrier
	v_mfma_f32_16x16x32_bf16 v[126:129], v[140:143], v[172:175], v[126:129]
	v_mfma_f32_16x16x32_bf16 v[122:125], v[148:151], v[172:175], v[122:125]
	v_mfma_f32_16x16x32_bf16 v[118:121], v[140:143], v[180:183], v[118:121]
	v_mfma_f32_16x16x32_bf16 v[114:117], v[148:151], v[180:183], v[114:117]
	v_mfma_f32_16x16x32_bf16 v[106:109], v[140:143], v[188:191], v[106:109]
	v_mfma_f32_16x16x32_bf16 v[98:101], v[148:151], v[188:191], v[98:101]
	v_mfma_f32_16x16x32_bf16 v[90:93], v[140:143], v[196:199], v[90:93]
	v_mfma_f32_16x16x32_bf16 v[82:85], v[148:151], v[196:199], v[82:85]
	v_mfma_f32_16x16x32_bf16 v[126:129], v[144:147], v[176:179], v[126:129]
	v_mfma_f32_16x16x32_bf16 v[122:125], v[152:155], v[176:179], v[122:125]
	v_mfma_f32_16x16x32_bf16 v[118:121], v[144:147], v[184:187], v[118:121]
	v_mfma_f32_16x16x32_bf16 v[114:117], v[152:155], v[184:187], v[114:117]
	v_mfma_f32_16x16x32_bf16 v[106:109], v[144:147], v[192:195], v[106:109]
	v_mfma_f32_16x16x32_bf16 v[98:101], v[152:155], v[192:195], v[98:101]
	v_mfma_f32_16x16x32_bf16 v[90:93], v[144:147], v[208:211], v[90:93]
	v_mfma_f32_16x16x32_bf16 v[82:85], v[152:155], v[208:211], v[82:85]
	v_mfma_f32_16x16x32_bf16 v[110:113], v[156:159], v[172:175], v[110:113]
	v_mfma_f32_16x16x32_bf16 v[102:105], v[164:167], v[172:175], v[102:105]
	v_mfma_f32_16x16x32_bf16 v[94:97], v[156:159], v[180:183], v[94:97]
	v_mfma_f32_16x16x32_bf16 v[86:89], v[164:167], v[180:183], v[86:89]
	v_mfma_f32_16x16x32_bf16 v[78:81], v[156:159], v[188:191], v[78:81]
	v_mfma_f32_16x16x32_bf16 v[74:77], v[164:167], v[188:191], v[74:77]
	v_mfma_f32_16x16x32_bf16 v[70:73], v[156:159], v[196:199], v[70:73]
	v_mfma_f32_16x16x32_bf16 v[66:69], v[164:167], v[196:199], v[66:69]
	v_mfma_f32_16x16x32_bf16 v[110:113], v[160:163], v[176:179], v[110:113]
	v_mfma_f32_16x16x32_bf16 v[102:105], v[168:171], v[176:179], v[102:105]
	v_mfma_f32_16x16x32_bf16 v[94:97], v[160:163], v[184:187], v[94:97]
	v_mfma_f32_16x16x32_bf16 v[86:89], v[168:171], v[184:187], v[86:89]
	v_mfma_f32_16x16x32_bf16 v[78:81], v[160:163], v[192:195], v[78:81]
	v_mfma_f32_16x16x32_bf16 v[74:77], v[168:171], v[192:195], v[74:77]
	v_mfma_f32_16x16x32_bf16 v[70:73], v[160:163], v[208:211], v[70:73]
	v_mfma_f32_16x16x32_bf16 v[66:69], v[168:171], v[208:211], v[66:69]
	s_barrier
	s_setprio 0
	s_add_i32 s0, s0, s24
	s_mov_b32 m0, s0
	ds_read_b128 v[172:175], v139 offset:16384
	ds_read_b128 v[176:179], v139 offset:17408
	ds_read_b128 v[180:183], v139 offset:18432
	ds_read_b128 v[184:187], v139 offset:19456
	ds_read_b128 v[188:191], v139 offset:20480
	ds_read_b128 v[192:195], v139 offset:21504
	ds_read_b128 v[196:199], v139 offset:22528
	ds_read_b128 v[208:211], v139 offset:23552
	global_load_lds_dwordx4 v202, s[18:19]
	s_add_i32 m0, s0, 0x2000
	s_add_u32 s0, s18, 0x160000
	s_addc_u32 s1, s19, 0
	s_add_i32 s2, s33, s24
	global_load_lds_dwordx4 v130, s[18:19]
	s_mov_b32 m0, s2
	s_nop 0
	global_load_lds_dwordx4 v202, s[0:1]
	s_add_i32 m0, s2, 0x2000
	s_nop 0
	global_load_lds_dwordx4 v130, s[0:1]
	s_mov_b32 m0, s25
	s_nop 0
	global_load_lds_dwordx4 v202, s[20:21]
	s_mov_b32 m0, s26
	s_nop 0
	global_load_lds_dwordx4 v130, s[20:21]
	s_setprio 1
	s_waitcnt vmcnt(8) lgkmcnt(0)
	s_barrier
	v_mfma_f32_16x16x32_bf16 v[62:65], v[140:143], v[172:175], v[62:65]
	v_mfma_f32_16x16x32_bf16 v[58:61], v[148:151], v[172:175], v[58:61]
	v_mfma_f32_16x16x32_bf16 v[54:57], v[140:143], v[180:183], v[54:57]
	v_mfma_f32_16x16x32_bf16 v[50:53], v[148:151], v[180:183], v[50:53]
	v_mfma_f32_16x16x32_bf16 v[38:41], v[140:143], v[188:191], v[38:41]
	v_mfma_f32_16x16x32_bf16 v[34:37], v[148:151], v[188:191], v[34:37]
	v_mfma_f32_16x16x32_bf16 v[22:25], v[140:143], v[196:199], v[22:25]
	v_mfma_f32_16x16x32_bf16 v[18:21], v[148:151], v[196:199], v[18:21]
	v_mfma_f32_16x16x32_bf16 v[62:65], v[144:147], v[176:179], v[62:65]
	v_mfma_f32_16x16x32_bf16 v[58:61], v[152:155], v[176:179], v[58:61]
	v_mfma_f32_16x16x32_bf16 v[54:57], v[144:147], v[184:187], v[54:57]
	v_mfma_f32_16x16x32_bf16 v[50:53], v[152:155], v[184:187], v[50:53]
	v_mfma_f32_16x16x32_bf16 v[38:41], v[144:147], v[192:195], v[38:41]
	v_mfma_f32_16x16x32_bf16 v[34:37], v[152:155], v[192:195], v[34:37]
	v_mfma_f32_16x16x32_bf16 v[22:25], v[144:147], v[208:211], v[22:25]
	v_mfma_f32_16x16x32_bf16 v[18:21], v[152:155], v[208:211], v[18:21]
	v_mfma_f32_16x16x32_bf16 v[46:49], v[156:159], v[172:175], v[46:49]
	v_mfma_f32_16x16x32_bf16 v[42:45], v[164:167], v[172:175], v[42:45]
	v_mfma_f32_16x16x32_bf16 v[30:33], v[156:159], v[180:183], v[30:33]
	v_mfma_f32_16x16x32_bf16 v[26:29], v[164:167], v[180:183], v[26:29]
	v_mfma_f32_16x16x32_bf16 v[14:17], v[156:159], v[188:191], v[14:17]
	v_mfma_f32_16x16x32_bf16 v[10:13], v[164:167], v[188:191], v[10:13]
	v_mfma_f32_16x16x32_bf16 v[6:9], v[156:159], v[196:199], v[6:9]
	v_mfma_f32_16x16x32_bf16 v[2:5], v[164:167], v[196:199], v[2:5]
	v_mfma_f32_16x16x32_bf16 v[46:49], v[160:163], v[176:179], v[46:49]
	v_mfma_f32_16x16x32_bf16 v[42:45], v[168:171], v[176:179], v[42:45]
	v_mfma_f32_16x16x32_bf16 v[30:33], v[160:163], v[184:187], v[30:33]
	v_mfma_f32_16x16x32_bf16 v[26:29], v[168:171], v[184:187], v[26:29]
	v_mfma_f32_16x16x32_bf16 v[14:17], v[160:163], v[192:195], v[14:17]
	v_mfma_f32_16x16x32_bf16 v[10:13], v[168:171], v[192:195], v[10:13]
	v_mfma_f32_16x16x32_bf16 v[6:9], v[160:163], v[208:211], v[6:9]
	v_mfma_f32_16x16x32_bf16 v[2:5], v[168:171], v[208:211], v[2:5]
	s_barrier
	s_setprio 0
	s_add_i32 s2, 0, 0x18000
	s_add_i32 s3, 0, 0x1c000
	ds_read_b128 v[140:143], v136 offset:32768
	ds_read_b128 v[144:147], v136 offset:33792
	ds_read_b128 v[148:151], v136 offset:34816
	ds_read_b128 v[152:155], v136 offset:35840
	ds_read_b128 v[156:159], v136 offset:49152
	ds_read_b128 v[160:163], v136 offset:50176
	ds_read_b128 v[164:167], v136 offset:51200
	ds_read_b128 v[168:171], v136 offset:52224
	s_add_u32 s0, s20, 0x160000
	s_addc_u32 s1, s21, 0
	s_mov_b32 m0, s27
	ds_read_b128 v[172:175], v139 offset:32768
	ds_read_b128 v[176:179], v139 offset:33792
	ds_read_b128 v[180:183], v139 offset:34816
	ds_read_b128 v[184:187], v139 offset:35840
	ds_read_b128 v[188:191], v139 offset:36864
	ds_read_b128 v[192:195], v139 offset:37888
	ds_read_b128 v[196:199], v139 offset:38912
	ds_read_b128 v[208:211], v139 offset:39936
	global_load_lds_dwordx4 v202, s[0:1]
	s_mov_b32 m0, s28
	s_nop 0
	global_load_lds_dwordx4 v130, s[0:1]
	s_setprio 1
	s_waitcnt vmcnt(8) lgkmcnt(0)
	s_barrier
	v_mfma_f32_16x16x32_bf16 v[126:129], v[140:143], v[172:175], v[126:129]
	v_mfma_f32_16x16x32_bf16 v[122:125], v[148:151], v[172:175], v[122:125]
	v_mfma_f32_16x16x32_bf16 v[118:121], v[140:143], v[180:183], v[118:121]
	v_mfma_f32_16x16x32_bf16 v[114:117], v[148:151], v[180:183], v[114:117]
	v_mfma_f32_16x16x32_bf16 v[106:109], v[140:143], v[188:191], v[106:109]
	v_mfma_f32_16x16x32_bf16 v[98:101], v[148:151], v[188:191], v[98:101]
	v_mfma_f32_16x16x32_bf16 v[90:93], v[140:143], v[196:199], v[90:93]
	v_mfma_f32_16x16x32_bf16 v[82:85], v[148:151], v[196:199], v[82:85]
	v_mfma_f32_16x16x32_bf16 v[126:129], v[144:147], v[176:179], v[126:129]
	v_mfma_f32_16x16x32_bf16 v[122:125], v[152:155], v[176:179], v[122:125]
	v_mfma_f32_16x16x32_bf16 v[118:121], v[144:147], v[184:187], v[118:121]
	v_mfma_f32_16x16x32_bf16 v[114:117], v[152:155], v[184:187], v[114:117]
	v_mfma_f32_16x16x32_bf16 v[106:109], v[144:147], v[192:195], v[106:109]
	v_mfma_f32_16x16x32_bf16 v[98:101], v[152:155], v[192:195], v[98:101]
	v_mfma_f32_16x16x32_bf16 v[90:93], v[144:147], v[208:211], v[90:93]
	v_mfma_f32_16x16x32_bf16 v[82:85], v[152:155], v[208:211], v[82:85]
	v_mfma_f32_16x16x32_bf16 v[110:113], v[156:159], v[172:175], v[110:113]
	v_mfma_f32_16x16x32_bf16 v[102:105], v[164:167], v[172:175], v[102:105]
	v_mfma_f32_16x16x32_bf16 v[94:97], v[156:159], v[180:183], v[94:97]
	v_mfma_f32_16x16x32_bf16 v[86:89], v[164:167], v[180:183], v[86:89]
	v_mfma_f32_16x16x32_bf16 v[78:81], v[156:159], v[188:191], v[78:81]
	v_mfma_f32_16x16x32_bf16 v[74:77], v[164:167], v[188:191], v[74:77]
	v_mfma_f32_16x16x32_bf16 v[70:73], v[156:159], v[196:199], v[70:73]
	v_mfma_f32_16x16x32_bf16 v[66:69], v[164:167], v[196:199], v[66:69]
	v_mfma_f32_16x16x32_bf16 v[110:113], v[160:163], v[176:179], v[110:113]
	v_mfma_f32_16x16x32_bf16 v[102:105], v[168:171], v[176:179], v[102:105]
	v_mfma_f32_16x16x32_bf16 v[94:97], v[160:163], v[184:187], v[94:97]
	v_mfma_f32_16x16x32_bf16 v[86:89], v[168:171], v[184:187], v[86:89]
	v_mfma_f32_16x16x32_bf16 v[78:81], v[160:163], v[192:195], v[78:81]
	v_mfma_f32_16x16x32_bf16 v[74:77], v[168:171], v[192:195], v[74:77]
	v_mfma_f32_16x16x32_bf16 v[70:73], v[160:163], v[208:211], v[70:73]
	v_mfma_f32_16x16x32_bf16 v[66:69], v[168:171], v[208:211], v[66:69]
	s_barrier
	s_setprio 0
	s_add_i32 s0, s2, s24
	s_add_u32 s100, s18, 0x80
	s_addc_u32 s101, s19, 0
	s_mov_b32 m0, s0
	ds_read_b128 v[172:175], v139 offset:49152
	ds_read_b128 v[176:179], v139 offset:50176
	ds_read_b128 v[180:183], v139 offset:51200
	ds_read_b128 v[184:187], v139 offset:52224
	ds_read_b128 v[188:191], v139 offset:53248
	ds_read_b128 v[192:195], v139 offset:54272
	ds_read_b128 v[196:199], v139 offset:55296
	ds_read_b128 v[208:211], v139 offset:56320
	global_load_lds_dwordx4 v202, s[100:101]
	s_add_i32 m0, s0, 0x2000
	s_add_u32 s100, s18, 0x80
	s_addc_u32 s101, s19, 0
	s_add_u32 s0, s18, 0x160080
	s_addc_u32 s1, s19, 0
	s_add_i32 s2, s3, s24
	global_load_lds_dwordx4 v130, s[100:101]
	s_mov_b32 m0, s2
	s_nop 0
	global_load_lds_dwordx4 v202, s[0:1]
	s_add_i32 m0, s2, 0x2000
	s_nop 0
	global_load_lds_dwordx4 v130, s[0:1]
	s_add_u32 s100, s20, 0x80
	s_addc_u32 s101, s21, 0
	s_mov_b32 m0, s29
	s_nop 0
	global_load_lds_dwordx4 v202, s[100:101]
	s_add_u32 s100, s20, 0x80
	s_addc_u32 s101, s21, 0
	s_mov_b32 m0, s30
	s_nop 0
	global_load_lds_dwordx4 v130, s[100:101]
	s_setprio 1
	s_waitcnt vmcnt(8) lgkmcnt(0)
	s_barrier
	v_mfma_f32_16x16x32_bf16 v[62:65], v[140:143], v[172:175], v[62:65]
	v_mfma_f32_16x16x32_bf16 v[58:61], v[148:151], v[172:175], v[58:61]
	v_mfma_f32_16x16x32_bf16 v[54:57], v[140:143], v[180:183], v[54:57]
	v_mfma_f32_16x16x32_bf16 v[50:53], v[148:151], v[180:183], v[50:53]
	v_mfma_f32_16x16x32_bf16 v[38:41], v[140:143], v[188:191], v[38:41]
	v_mfma_f32_16x16x32_bf16 v[34:37], v[148:151], v[188:191], v[34:37]
	v_mfma_f32_16x16x32_bf16 v[22:25], v[140:143], v[196:199], v[22:25]
	v_mfma_f32_16x16x32_bf16 v[18:21], v[148:151], v[196:199], v[18:21]
	v_mfma_f32_16x16x32_bf16 v[62:65], v[144:147], v[176:179], v[62:65]
	v_mfma_f32_16x16x32_bf16 v[58:61], v[152:155], v[176:179], v[58:61]
	v_mfma_f32_16x16x32_bf16 v[54:57], v[144:147], v[184:187], v[54:57]
	v_mfma_f32_16x16x32_bf16 v[50:53], v[152:155], v[184:187], v[50:53]
	v_mfma_f32_16x16x32_bf16 v[38:41], v[144:147], v[192:195], v[38:41]
	v_mfma_f32_16x16x32_bf16 v[34:37], v[152:155], v[192:195], v[34:37]
	v_mfma_f32_16x16x32_bf16 v[22:25], v[144:147], v[208:211], v[22:25]
	v_mfma_f32_16x16x32_bf16 v[18:21], v[152:155], v[208:211], v[18:21]
	v_mfma_f32_16x16x32_bf16 v[46:49], v[156:159], v[172:175], v[46:49]
	v_mfma_f32_16x16x32_bf16 v[42:45], v[164:167], v[172:175], v[42:45]
	v_mfma_f32_16x16x32_bf16 v[30:33], v[156:159], v[180:183], v[30:33]
	v_mfma_f32_16x16x32_bf16 v[26:29], v[164:167], v[180:183], v[26:29]
	v_mfma_f32_16x16x32_bf16 v[14:17], v[156:159], v[188:191], v[14:17]
	v_mfma_f32_16x16x32_bf16 v[10:13], v[164:167], v[188:191], v[10:13]
	v_mfma_f32_16x16x32_bf16 v[6:9], v[156:159], v[196:199], v[6:9]
	v_mfma_f32_16x16x32_bf16 v[2:5], v[164:167], v[196:199], v[2:5]
	v_mfma_f32_16x16x32_bf16 v[46:49], v[160:163], v[176:179], v[46:49]
	v_mfma_f32_16x16x32_bf16 v[42:45], v[168:171], v[176:179], v[42:45]
	v_mfma_f32_16x16x32_bf16 v[30:33], v[160:163], v[184:187], v[30:33]
	v_mfma_f32_16x16x32_bf16 v[26:29], v[168:171], v[184:187], v[26:29]
	v_mfma_f32_16x16x32_bf16 v[14:17], v[160:163], v[192:195], v[14:17]
	v_mfma_f32_16x16x32_bf16 v[10:13], v[168:171], v[192:195], v[10:13]
	v_mfma_f32_16x16x32_bf16 v[6:9], v[160:163], v[208:211], v[6:9]
	v_mfma_f32_16x16x32_bf16 v[2:5], v[168:171], v[208:211], v[2:5]
	s_barrier
	s_setprio 0
	s_add_i32 s59, s59, 2
	s_add_u32 s49, s49, 0x100
	s_addc_u32 s58, s58, 0
	s_cmp_gt_u32 s59, 5
	s_mov_b64 s[2:3], s[4:5]
	s_cbranch_scc0 .LBB0_990
	s_and_b64 vcc, exec, s[10:11]
	s_cbranch_vccz .LBB0_993
	s_barrier

.LBB0_1115:
	s_add_u32 s0, s22, 0xfff80080
	s_addc_u32 s1, s23, -1
	s_add_i32 s33, 0, 0x10000
	s_cmp_eq_u32 s58, 28
	s_cselect_b32 s5, s17, s1
	s_cselect_b32 s4, s39, s0
	s_cselect_b32 s3, s15, s49
	s_cselect_b32 s2, s40, s41
	s_add_i32 s55, 0, 0x14000
	ds_read_b128 v[148:151], v145
	ds_read_b128 v[152:155], v145 offset:1024
	ds_read_b128 v[156:159], v145 offset:2048
	ds_read_b128 v[160:163], v145 offset:3072
	ds_read_b128 v[164:167], v145 offset:16384
	ds_read_b128 v[168:171], v145 offset:17408
	ds_read_b128 v[172:175], v145 offset:18432
	ds_read_b128 v[176:179], v145 offset:19456
	s_add_i32 m0, s27, 0xc000
	ds_read_b128 v[180:183], v147
	ds_read_b128 v[184:187], v147 offset:1024
	ds_read_b128 v[188:191], v147 offset:2048
	ds_read_b128 v[192:195], v147 offset:3072
	ds_read_b128 v[196:199], v147 offset:4096
	ds_read_b128 v[208:211], v147 offset:5120
	ds_read_b128 v[212:215], v147 offset:6144
	ds_read_b128 v[216:219], v147 offset:7168
	global_load_lds_dwordx4 v138, s[22:23]
	s_add_i32 m0, s27, 0xe000
	s_nop 0
	global_load_lds_dwordx4 v140, s[22:23]
	s_setprio 1
	s_waitcnt vmcnt(8) lgkmcnt(0)
	s_barrier
	v_mfma_f32_16x16x32_bf16 v[126:129], v[148:151], v[180:183], v[126:129]
	v_mfma_f32_16x16x32_bf16 v[122:125], v[156:159], v[180:183], v[122:125]
	v_mfma_f32_16x16x32_bf16 v[110:113], v[148:151], v[188:191], v[110:113]
	v_mfma_f32_16x16x32_bf16 v[106:109], v[156:159], v[188:191], v[106:109]
	v_mfma_f32_16x16x32_bf16 v[94:97], v[148:151], v[196:199], v[94:97]
	v_mfma_f32_16x16x32_bf16 v[90:93], v[156:159], v[196:199], v[90:93]
	v_mfma_f32_16x16x32_bf16 v[78:81], v[148:151], v[212:215], v[78:81]
	v_mfma_f32_16x16x32_bf16 v[74:77], v[156:159], v[212:215], v[74:77]
	v_mfma_f32_16x16x32_bf16 v[126:129], v[152:155], v[184:187], v[126:129]
	v_mfma_f32_16x16x32_bf16 v[122:125], v[160:163], v[184:187], v[122:125]
	v_mfma_f32_16x16x32_bf16 v[110:113], v[152:155], v[192:195], v[110:113]
	v_mfma_f32_16x16x32_bf16 v[106:109], v[160:163], v[192:195], v[106:109]
	v_mfma_f32_16x16x32_bf16 v[94:97], v[152:155], v[208:211], v[94:97]
	v_mfma_f32_16x16x32_bf16 v[90:93], v[160:163], v[208:211], v[90:93]
	v_mfma_f32_16x16x32_bf16 v[78:81], v[152:155], v[216:219], v[78:81]
	v_mfma_f32_16x16x32_bf16 v[74:77], v[160:163], v[216:219], v[74:77]
	v_mfma_f32_16x16x32_bf16 v[118:121], v[164:167], v[180:183], v[118:121]
	v_mfma_f32_16x16x32_bf16 v[114:117], v[172:175], v[180:183], v[114:117]
	v_mfma_f32_16x16x32_bf16 v[102:105], v[164:167], v[188:191], v[102:105]
	v_mfma_f32_16x16x32_bf16 v[98:101], v[172:175], v[188:191], v[98:101]
	v_mfma_f32_16x16x32_bf16 v[86:89], v[164:167], v[196:199], v[86:89]
	v_mfma_f32_16x16x32_bf16 v[82:85], v[172:175], v[196:199], v[82:85]
	v_mfma_f32_16x16x32_bf16 v[70:73], v[164:167], v[212:215], v[70:73]
	v_mfma_f32_16x16x32_bf16 v[66:69], v[172:175], v[212:215], v[66:69]
	v_mfma_f32_16x16x32_bf16 v[118:121], v[168:171], v[184:187], v[118:121]
	v_mfma_f32_16x16x32_bf16 v[114:117], v[176:179], v[184:187], v[114:117]
	v_mfma_f32_16x16x32_bf16 v[102:105], v[168:171], v[192:195], v[102:105]
	v_mfma_f32_16x16x32_bf16 v[98:101], v[176:179], v[192:195], v[98:101]
	v_mfma_f32_16x16x32_bf16 v[86:89], v[168:171], v[208:211], v[86:89]
	v_mfma_f32_16x16x32_bf16 v[82:85], v[176:179], v[208:211], v[82:85]
	v_mfma_f32_16x16x32_bf16 v[70:73], v[168:171], v[216:219], v[70:73]
	v_mfma_f32_16x16x32_bf16 v[66:69], v[176:179], v[216:219], v[66:69]
	s_barrier
	s_setprio 0
	s_add_i32 s0, s33, s26
	s_mov_b32 m0, s0
	ds_read_b128 v[180:183], v147 offset:16384
	ds_read_b128 v[184:187], v147 offset:17408
	ds_read_b128 v[188:191], v147 offset:18432
	ds_read_b128 v[192:195], v147 offset:19456
	ds_read_b128 v[196:199], v147 offset:20480
	ds_read_b128 v[208:211], v147 offset:21504
	ds_read_b128 v[212:215], v147 offset:22528
	ds_read_b128 v[216:219], v147 offset:23552
	global_load_lds_dwordx4 v134, s[2:3]
	s_add_i32 m0, s0, 0x2000
	s_add_u32 s0, s2, 0x80000
	s_addc_u32 s1, s3, 0
	s_add_i32 s33, s55, s26
	global_load_lds_dwordx4 v130, s[2:3]
	s_mov_b32 m0, s33
	s_nop 0
	global_load_lds_dwordx4 v134, s[0:1]
	s_add_i32 m0, s33, 0x2000
	s_nop 0
	global_load_lds_dwordx4 v130, s[0:1]
	s_mov_b32 m0, s27
	s_nop 0
	global_load_lds_dwordx4 v136, s[4:5]
	s_mov_b32 m0, s28
	s_nop 0
	global_load_lds_dwordx4 v132, s[4:5]
	s_setprio 1
	s_waitcnt vmcnt(8) lgkmcnt(0)
	s_barrier
	v_mfma_f32_16x16x32_bf16 v[62:65], v[148:151], v[180:183], v[62:65]
	v_mfma_f32_16x16x32_bf16 v[58:61], v[156:159], v[180:183], v[58:61]
	v_mfma_f32_16x16x32_bf16 v[46:49], v[148:151], v[188:191], v[46:49]
	v_mfma_f32_16x16x32_bf16 v[42:45], v[156:159], v[188:191], v[42:45]
	v_mfma_f32_16x16x32_bf16 v[30:33], v[148:151], v[196:199], v[30:33]
	v_mfma_f32_16x16x32_bf16 v[26:29], v[156:159], v[196:199], v[26:29]
	v_mfma_f32_16x16x32_bf16 v[14:17], v[148:151], v[212:215], v[14:17]
	v_mfma_f32_16x16x32_bf16 v[10:13], v[156:159], v[212:215], v[10:13]
	v_mfma_f32_16x16x32_bf16 v[62:65], v[152:155], v[184:187], v[62:65]
	v_mfma_f32_16x16x32_bf16 v[58:61], v[160:163], v[184:187], v[58:61]
	v_mfma_f32_16x16x32_bf16 v[46:49], v[152:155], v[192:195], v[46:49]
	v_mfma_f32_16x16x32_bf16 v[42:45], v[160:163], v[192:195], v[42:45]
	v_mfma_f32_16x16x32_bf16 v[30:33], v[152:155], v[208:211], v[30:33]
	v_mfma_f32_16x16x32_bf16 v[26:29], v[160:163], v[208:211], v[26:29]
	v_mfma_f32_16x16x32_bf16 v[14:17], v[152:155], v[216:219], v[14:17]
	v_mfma_f32_16x16x32_bf16 v[10:13], v[160:163], v[216:219], v[10:13]
	v_mfma_f32_16x16x32_bf16 v[54:57], v[164:167], v[180:183], v[54:57]
	v_mfma_f32_16x16x32_bf16 v[50:53], v[172:175], v[180:183], v[50:53]
	v_mfma_f32_16x16x32_bf16 v[38:41], v[164:167], v[188:191], v[38:41]
	v_mfma_f32_16x16x32_bf16 v[34:37], v[172:175], v[188:191], v[34:37]
	v_mfma_f32_16x16x32_bf16 v[22:25], v[164:167], v[196:199], v[22:25]
	v_mfma_f32_16x16x32_bf16 v[18:21], v[172:175], v[196:199], v[18:21]
	v_mfma_f32_16x16x32_bf16 v[6:9], v[164:167], v[212:215], v[6:9]
	v_mfma_f32_16x16x32_bf16 v[2:5], v[172:175], v[212:215], v[2:5]
	v_mfma_f32_16x16x32_bf16 v[54:57], v[168:171], v[184:187], v[54:57]
	v_mfma_f32_16x16x32_bf16 v[50:53], v[176:179], v[184:187], v[50:53]
	v_mfma_f32_16x16x32_bf16 v[38:41], v[168:171], v[192:195], v[38:41]
	v_mfma_f32_16x16x32_bf16 v[34:37], v[176:179], v[192:195], v[34:37]
	v_mfma_f32_16x16x32_bf16 v[22:25], v[168:171], v[208:211], v[22:25]
	v_mfma_f32_16x16x32_bf16 v[18:21], v[176:179], v[208:211], v[18:21]
	v_mfma_f32_16x16x32_bf16 v[6:9], v[168:171], v[216:219], v[6:9]
	v_mfma_f32_16x16x32_bf16 v[2:5], v[176:179], v[216:219], v[2:5]
	s_barrier
	s_setprio 0
	s_add_i32 s33, 0, 0x18000
	s_add_i32 s55, 0, 0x1c000
	ds_read_b128 v[148:151], v145 offset:32768
	ds_read_b128 v[152:155], v145 offset:33792
	ds_read_b128 v[156:159], v145 offset:34816
	ds_read_b128 v[160:163], v145 offset:35840
	ds_read_b128 v[164:167], v145 offset:49152
	ds_read_b128 v[168:171], v145 offset:50176
	ds_read_b128 v[172:175], v145 offset:51200
	ds_read_b128 v[176:179], v145 offset:52224
	s_add_u32 s0, s4, 0x80000
	s_addc_u32 s1, s5, 0
	s_mov_b32 m0, s29
	ds_read_b128 v[180:183], v147 offset:32768
	ds_read_b128 v[184:187], v147 offset:33792
	ds_read_b128 v[188:191], v147 offset:34816
	ds_read_b128 v[192:195], v147 offset:35840
	ds_read_b128 v[196:199], v147 offset:36864
	ds_read_b128 v[208:211], v147 offset:37888
	ds_read_b128 v[212:215], v147 offset:38912
	ds_read_b128 v[216:219], v147 offset:39936
	global_load_lds_dwordx4 v136, s[0:1]
	s_mov_b32 m0, s30
	s_nop 0
	global_load_lds_dwordx4 v132, s[0:1]
	s_setprio 1
	s_waitcnt vmcnt(8) lgkmcnt(0)
	s_barrier
	v_mfma_f32_16x16x32_bf16 v[126:129], v[148:151], v[180:183], v[126:129]
	v_mfma_f32_16x16x32_bf16 v[122:125], v[156:159], v[180:183], v[122:125]
	v_mfma_f32_16x16x32_bf16 v[110:113], v[148:151], v[188:191], v[110:113]
	v_mfma_f32_16x16x32_bf16 v[106:109], v[156:159], v[188:191], v[106:109]
	v_mfma_f32_16x16x32_bf16 v[94:97], v[148:151], v[196:199], v[94:97]
	v_mfma_f32_16x16x32_bf16 v[90:93], v[156:159], v[196:199], v[90:93]
	v_mfma_f32_16x16x32_bf16 v[78:81], v[148:151], v[212:215], v[78:81]
	v_mfma_f32_16x16x32_bf16 v[74:77], v[156:159], v[212:215], v[74:77]
	v_mfma_f32_16x16x32_bf16 v[126:129], v[152:155], v[184:187], v[126:129]
	v_mfma_f32_16x16x32_bf16 v[122:125], v[160:163], v[184:187], v[122:125]
	v_mfma_f32_16x16x32_bf16 v[110:113], v[152:155], v[192:195], v[110:113]
	v_mfma_f32_16x16x32_bf16 v[106:109], v[160:163], v[192:195], v[106:109]
	v_mfma_f32_16x16x32_bf16 v[94:97], v[152:155], v[208:211], v[94:97]
	v_mfma_f32_16x16x32_bf16 v[90:93], v[160:163], v[208:211], v[90:93]
	v_mfma_f32_16x16x32_bf16 v[78:81], v[152:155], v[216:219], v[78:81]
	v_mfma_f32_16x16x32_bf16 v[74:77], v[160:163], v[216:219], v[74:77]
	v_mfma_f32_16x16x32_bf16 v[118:121], v[164:167], v[180:183], v[118:121]
	v_mfma_f32_16x16x32_bf16 v[114:117], v[172:175], v[180:183], v[114:117]
	v_mfma_f32_16x16x32_bf16 v[102:105], v[164:167], v[188:191], v[102:105]
	v_mfma_f32_16x16x32_bf16 v[98:101], v[172:175], v[188:191], v[98:101]
	v_mfma_f32_16x16x32_bf16 v[86:89], v[164:167], v[196:199], v[86:89]
	v_mfma_f32_16x16x32_bf16 v[82:85], v[172:175], v[196:199], v[82:85]
	v_mfma_f32_16x16x32_bf16 v[70:73], v[164:167], v[212:215], v[70:73]
	v_mfma_f32_16x16x32_bf16 v[66:69], v[172:175], v[212:215], v[66:69]
	v_mfma_f32_16x16x32_bf16 v[118:121], v[168:171], v[184:187], v[118:121]
	v_mfma_f32_16x16x32_bf16 v[114:117], v[176:179], v[184:187], v[114:117]
	v_mfma_f32_16x16x32_bf16 v[102:105], v[168:171], v[192:195], v[102:105]
	v_mfma_f32_16x16x32_bf16 v[98:101], v[176:179], v[192:195], v[98:101]
	v_mfma_f32_16x16x32_bf16 v[86:89], v[168:171], v[208:211], v[86:89]
	v_mfma_f32_16x16x32_bf16 v[82:85], v[176:179], v[208:211], v[82:85]
	v_mfma_f32_16x16x32_bf16 v[70:73], v[168:171], v[216:219], v[70:73]
	v_mfma_f32_16x16x32_bf16 v[66:69], v[176:179], v[216:219], v[66:69]
	s_barrier
	s_setprio 0
	s_add_i32 s0, s33, s26
	s_add_u32 s100, s2, 0x80
	s_addc_u32 s101, s3, 0
	s_mov_b32 m0, s0
	ds_read_b128 v[180:183], v147 offset:49152
	ds_read_b128 v[184:187], v147 offset:50176
	ds_read_b128 v[188:191], v147 offset:51200
	ds_read_b128 v[192:195], v147 offset:52224
	ds_read_b128 v[196:199], v147 offset:53248
	ds_read_b128 v[208:211], v147 offset:54272
	ds_read_b128 v[212:215], v147 offset:55296
	ds_read_b128 v[216:219], v147 offset:56320
	global_load_lds_dwordx4 v134, s[100:101]
	s_add_i32 m0, s0, 0x2000
	s_add_u32 s100, s2, 0x80
	s_addc_u32 s101, s3, 0
	s_add_u32 s0, s2, 0x80080
	s_addc_u32 s1, s3, 0
	s_add_i32 s2, s55, s26
	global_load_lds_dwordx4 v130, s[100:101]
	s_mov_b32 m0, s2
	s_nop 0
	global_load_lds_dwordx4 v134, s[0:1]
	s_add_i32 m0, s2, 0x2000
	s_nop 0
	global_load_lds_dwordx4 v130, s[0:1]
	s_add_u32 s100, s4, 0x80
	s_addc_u32 s101, s5, 0
	s_mov_b32 m0, s34
	s_nop 0
	global_load_lds_dwordx4 v136, s[100:101]
	s_add_u32 s100, s4, 0x80
	s_addc_u32 s101, s5, 0
	s_mov_b32 m0, s35
	s_nop 0
	global_load_lds_dwordx4 v132, s[100:101]
	s_setprio 1
	s_waitcnt vmcnt(8) lgkmcnt(0)
	s_barrier
	v_mfma_f32_16x16x32_bf16 v[62:65], v[148:151], v[180:183], v[62:65]
	v_mfma_f32_16x16x32_bf16 v[58:61], v[156:159], v[180:183], v[58:61]
	v_mfma_f32_16x16x32_bf16 v[46:49], v[148:151], v[188:191], v[46:49]
	v_mfma_f32_16x16x32_bf16 v[42:45], v[156:159], v[188:191], v[42:45]
	v_mfma_f32_16x16x32_bf16 v[30:33], v[148:151], v[196:199], v[30:33]
	v_mfma_f32_16x16x32_bf16 v[26:29], v[156:159], v[196:199], v[26:29]
	v_mfma_f32_16x16x32_bf16 v[14:17], v[148:151], v[212:215], v[14:17]
	v_mfma_f32_16x16x32_bf16 v[10:13], v[156:159], v[212:215], v[10:13]
	v_mfma_f32_16x16x32_bf16 v[62:65], v[152:155], v[184:187], v[62:65]
	v_mfma_f32_16x16x32_bf16 v[58:61], v[160:163], v[184:187], v[58:61]
	v_mfma_f32_16x16x32_bf16 v[46:49], v[152:155], v[192:195], v[46:49]
	v_mfma_f32_16x16x32_bf16 v[42:45], v[160:163], v[192:195], v[42:45]
	v_mfma_f32_16x16x32_bf16 v[30:33], v[152:155], v[208:211], v[30:33]
	v_mfma_f32_16x16x32_bf16 v[26:29], v[160:163], v[208:211], v[26:29]
	v_mfma_f32_16x16x32_bf16 v[14:17], v[152:155], v[216:219], v[14:17]
	v_mfma_f32_16x16x32_bf16 v[10:13], v[160:163], v[216:219], v[10:13]
	v_mfma_f32_16x16x32_bf16 v[54:57], v[164:167], v[180:183], v[54:57]
	v_mfma_f32_16x16x32_bf16 v[50:53], v[172:175], v[180:183], v[50:53]
	v_mfma_f32_16x16x32_bf16 v[38:41], v[164:167], v[188:191], v[38:41]
	v_mfma_f32_16x16x32_bf16 v[34:37], v[172:175], v[188:191], v[34:37]
	v_mfma_f32_16x16x32_bf16 v[22:25], v[164:167], v[196:199], v[22:25]
	v_mfma_f32_16x16x32_bf16 v[18:21], v[172:175], v[196:199], v[18:21]
	v_mfma_f32_16x16x32_bf16 v[6:9], v[164:167], v[212:215], v[6:9]
	v_mfma_f32_16x16x32_bf16 v[2:5], v[172:175], v[212:215], v[2:5]
	v_mfma_f32_16x16x32_bf16 v[54:57], v[168:171], v[184:187], v[54:57]
	v_mfma_f32_16x16x32_bf16 v[50:53], v[176:179], v[184:187], v[50:53]
	v_mfma_f32_16x16x32_bf16 v[38:41], v[168:171], v[192:195], v[38:41]
	v_mfma_f32_16x16x32_bf16 v[34:37], v[176:179], v[192:195], v[34:37]
	v_mfma_f32_16x16x32_bf16 v[22:25], v[168:171], v[208:211], v[22:25]
	v_mfma_f32_16x16x32_bf16 v[18:21], v[176:179], v[208:211], v[18:21]
	v_mfma_f32_16x16x32_bf16 v[6:9], v[168:171], v[216:219], v[6:9]
	v_mfma_f32_16x16x32_bf16 v[2:5], v[176:179], v[216:219], v[2:5]
	s_barrier
	s_setprio 0
	s_add_i32 s58, s58, 2
	s_add_u32 s22, s22, 0x100
	s_addc_u32 s23, s23, 0
	s_add_u32 s41, s41, 0x100
	s_addc_u32 s49, s49, 0
	s_cmp_gt_u32 s58, 29
	s_cbranch_scc0 .LBB0_1115
	s_and_b64 vcc, exec, s[10:11]
	s_cbranch_vccz .LBB0_1118
	s_barrier

.LBB0_1242:
	s_add_u32 s28, s18, s4
	s_addc_u32 s29, s19, s5
	s_add_u32 s24, s28, 0x100
	s_addc_u32 s25, s29, 0
	s_and_b64 s[0:1], s[2:3], exec
	s_cselect_b32 s25, s49, s25
	s_cselect_b32 s24, s58, s24
	s_add_u32 s0, s20, s4
	s_addc_u32 s1, s21, s5
	s_add_u32 s4, s0, 0x100
	s_addc_u32 s5, s1, 0
	s_add_i32 s55, 0, 0x10000
	s_and_b64 s[0:1], s[2:3], exec
	s_cselect_b32 s27, s59, s5
	s_cselect_b32 s26, s60, s4
	s_add_i32 s0, 0, 0x14000
	s_add_u32 s30, s28, 0x20080
	s_addc_u32 s31, s29, 0
	s_add_i32 s57, s55, s36
	s_add_i32 m0, s37, 0xc000
	s_add_i32 s1, s37, 0xe000
	s_add_i32 s63, s57, 0x2000
	v_add_u32_e32 v138, s55, v141
	s_add_u32 s28, s26, 0x10000
	ds_read_b128 v[144:147], v138
	ds_read_b128 v[148:151], v138 offset:1024
	ds_read_b128 v[152:155], v138 offset:2048
	ds_read_b128 v[156:159], v138 offset:3072
	v_add_u32_e32 v138, s0, v141
	s_addc_u32 s29, s27, 0
	s_add_i32 s33, s0, s36
	ds_read_b128 v[160:163], v138
	ds_read_b128 v[164:167], v138 offset:1024
	ds_read_b128 v[168:171], v138 offset:2048
	ds_read_b128 v[172:175], v138 offset:3072
	s_add_i32 s56, s33, 0x2000
	s_add_i32 vcc_lo, 0, 0x18000
	s_add_i32 vcc_hi, 0, 0x1c000
	s_add_u32 s4, s24, 0x20000
	s_addc_u32 s5, s25, 0
	s_add_i32 s61, vcc_lo, s36
	s_add_i32 s62, s61, 0x2000
	s_add_u32 s2, s26, 0x10080
	s_addc_u32 s3, s27, 0
	s_add_i32 s55, vcc_hi, s36
	s_add_i32 s0, s55, 0x2000
	ds_read_b128 v[176:179], v142
	ds_read_b128 v[180:183], v142 offset:1024
	ds_read_b128 v[184:187], v142 offset:2048
	ds_read_b128 v[188:191], v142 offset:3072
	ds_read_b128 v[192:195], v142 offset:4096
	ds_read_b128 v[196:199], v142 offset:5120
	ds_read_b128 v[208:211], v142 offset:6144
	ds_read_b128 v[212:215], v142 offset:7168
	global_load_lds_dwordx4 v134, s[30:31]
	s_mov_b32 m0, s1
	s_nop 0
	global_load_lds_dwordx4 v132, s[30:31]
	s_setprio 1
	s_waitcnt vmcnt(8) lgkmcnt(0)
	s_barrier
	v_mfma_f32_16x16x32_bf16 v[126:129], v[144:147], v[176:179], v[126:129]
	v_mfma_f32_16x16x32_bf16 v[122:125], v[152:155], v[176:179], v[122:125]
	v_mfma_f32_16x16x32_bf16 v[118:121], v[144:147], v[184:187], v[118:121]
	v_mfma_f32_16x16x32_bf16 v[110:113], v[152:155], v[184:187], v[110:113]
	v_mfma_f32_16x16x32_bf16 v[102:105], v[144:147], v[192:195], v[102:105]
	v_mfma_f32_16x16x32_bf16 v[94:97], v[152:155], v[192:195], v[94:97]
	v_mfma_f32_16x16x32_bf16 v[86:89], v[144:147], v[208:211], v[86:89]
	v_mfma_f32_16x16x32_bf16 v[78:81], v[152:155], v[208:211], v[78:81]
	v_mfma_f32_16x16x32_bf16 v[126:129], v[148:151], v[180:183], v[126:129]
	v_mfma_f32_16x16x32_bf16 v[122:125], v[156:159], v[180:183], v[122:125]
	v_mfma_f32_16x16x32_bf16 v[118:121], v[148:151], v[188:191], v[118:121]
	v_mfma_f32_16x16x32_bf16 v[110:113], v[156:159], v[188:191], v[110:113]
	v_mfma_f32_16x16x32_bf16 v[102:105], v[148:151], v[196:199], v[102:105]
	v_mfma_f32_16x16x32_bf16 v[94:97], v[156:159], v[196:199], v[94:97]
	v_mfma_f32_16x16x32_bf16 v[86:89], v[148:151], v[212:215], v[86:89]
	v_mfma_f32_16x16x32_bf16 v[78:81], v[156:159], v[212:215], v[78:81]
	v_mfma_f32_16x16x32_bf16 v[114:117], v[160:163], v[176:179], v[114:117]
	v_mfma_f32_16x16x32_bf16 v[106:109], v[168:171], v[176:179], v[106:109]
	v_mfma_f32_16x16x32_bf16 v[98:101], v[160:163], v[184:187], v[98:101]
	v_mfma_f32_16x16x32_bf16 v[90:93], v[168:171], v[184:187], v[90:93]
	v_mfma_f32_16x16x32_bf16 v[82:85], v[160:163], v[192:195], v[82:85]
	v_mfma_f32_16x16x32_bf16 v[74:77], v[168:171], v[192:195], v[74:77]
	v_mfma_f32_16x16x32_bf16 v[70:73], v[160:163], v[208:211], v[70:73]
	v_mfma_f32_16x16x32_bf16 v[66:69], v[168:171], v[208:211], v[66:69]
	v_mfma_f32_16x16x32_bf16 v[114:117], v[164:167], v[180:183], v[114:117]
	v_mfma_f32_16x16x32_bf16 v[106:109], v[172:175], v[180:183], v[106:109]
	v_mfma_f32_16x16x32_bf16 v[98:101], v[164:167], v[188:191], v[98:101]
	v_mfma_f32_16x16x32_bf16 v[90:93], v[172:175], v[188:191], v[90:93]
	v_mfma_f32_16x16x32_bf16 v[82:85], v[164:167], v[196:199], v[82:85]
	v_mfma_f32_16x16x32_bf16 v[74:77], v[172:175], v[196:199], v[74:77]
	v_mfma_f32_16x16x32_bf16 v[70:73], v[164:167], v[212:215], v[70:73]
	v_mfma_f32_16x16x32_bf16 v[66:69], v[172:175], v[212:215], v[66:69]
	s_barrier
	s_setprio 0
	s_mov_b32 m0, s57
	ds_read_b128 v[176:179], v142 offset:16384
	ds_read_b128 v[180:183], v142 offset:17408
	ds_read_b128 v[184:187], v142 offset:18432
	ds_read_b128 v[188:191], v142 offset:19456
	ds_read_b128 v[192:195], v142 offset:20480
	ds_read_b128 v[196:199], v142 offset:21504
	ds_read_b128 v[208:211], v142 offset:22528
	ds_read_b128 v[212:215], v142 offset:23552
	global_load_lds_dwordx4 v202, s[26:27]
	s_mov_b32 m0, s63
	s_nop 0
	global_load_lds_dwordx4 v130, s[26:27]
	s_mov_b32 m0, s33
	s_nop 0
	global_load_lds_dwordx4 v202, s[28:29]
	s_mov_b32 m0, s56
	s_nop 0
	global_load_lds_dwordx4 v130, s[28:29]
	s_mov_b32 m0, s37
	s_nop 0
	global_load_lds_dwordx4 v134, s[24:25]
	s_mov_b32 m0, s38
	s_nop 0
	global_load_lds_dwordx4 v132, s[24:25]
	s_setprio 1
	s_waitcnt vmcnt(8) lgkmcnt(0)
	s_barrier
	v_mfma_f32_16x16x32_bf16 v[62:65], v[144:147], v[176:179], v[62:65]
	v_mfma_f32_16x16x32_bf16 v[58:61], v[152:155], v[176:179], v[58:61]
	v_mfma_f32_16x16x32_bf16 v[54:57], v[144:147], v[184:187], v[54:57]
	v_mfma_f32_16x16x32_bf16 v[46:49], v[152:155], v[184:187], v[46:49]
	v_mfma_f32_16x16x32_bf16 v[38:41], v[144:147], v[192:195], v[38:41]
	v_mfma_f32_16x16x32_bf16 v[30:33], v[152:155], v[192:195], v[30:33]
	v_mfma_f32_16x16x32_bf16 v[22:25], v[144:147], v[208:211], v[22:25]
	v_mfma_f32_16x16x32_bf16 v[14:17], v[152:155], v[208:211], v[14:17]
	v_mfma_f32_16x16x32_bf16 v[62:65], v[148:151], v[180:183], v[62:65]
	v_mfma_f32_16x16x32_bf16 v[58:61], v[156:159], v[180:183], v[58:61]
	v_mfma_f32_16x16x32_bf16 v[54:57], v[148:151], v[188:191], v[54:57]
	v_mfma_f32_16x16x32_bf16 v[46:49], v[156:159], v[188:191], v[46:49]
	v_mfma_f32_16x16x32_bf16 v[38:41], v[148:151], v[196:199], v[38:41]
	v_mfma_f32_16x16x32_bf16 v[30:33], v[156:159], v[196:199], v[30:33]
	v_mfma_f32_16x16x32_bf16 v[22:25], v[148:151], v[212:215], v[22:25]
	v_mfma_f32_16x16x32_bf16 v[14:17], v[156:159], v[212:215], v[14:17]
	v_mfma_f32_16x16x32_bf16 v[50:53], v[160:163], v[176:179], v[50:53]
	v_mfma_f32_16x16x32_bf16 v[42:45], v[168:171], v[176:179], v[42:45]
	v_mfma_f32_16x16x32_bf16 v[34:37], v[160:163], v[184:187], v[34:37]
	v_mfma_f32_16x16x32_bf16 v[26:29], v[168:171], v[184:187], v[26:29]
	v_mfma_f32_16x16x32_bf16 v[18:21], v[160:163], v[192:195], v[18:21]
	v_mfma_f32_16x16x32_bf16 v[10:13], v[168:171], v[192:195], v[10:13]
	v_mfma_f32_16x16x32_bf16 v[6:9], v[160:163], v[208:211], v[6:9]
	v_mfma_f32_16x16x32_bf16 v[2:5], v[168:171], v[208:211], v[2:5]
	v_mfma_f32_16x16x32_bf16 v[50:53], v[164:167], v[180:183], v[50:53]
	v_mfma_f32_16x16x32_bf16 v[42:45], v[172:175], v[180:183], v[42:45]
	v_mfma_f32_16x16x32_bf16 v[34:37], v[164:167], v[188:191], v[34:37]
	v_mfma_f32_16x16x32_bf16 v[26:29], v[172:175], v[188:191], v[26:29]
	v_mfma_f32_16x16x32_bf16 v[18:21], v[164:167], v[196:199], v[18:21]
	v_mfma_f32_16x16x32_bf16 v[10:13], v[172:175], v[196:199], v[10:13]
	v_mfma_f32_16x16x32_bf16 v[6:9], v[164:167], v[212:215], v[6:9]
	v_mfma_f32_16x16x32_bf16 v[2:5], v[172:175], v[212:215], v[2:5]
	s_barrier
	s_setprio 0
	v_add_u32_e32 v143, vcc_lo, v141
	ds_read_b128 v[144:147], v143
	ds_read_b128 v[148:151], v143 offset:1024
	ds_read_b128 v[152:155], v143 offset:2048
	ds_read_b128 v[156:159], v143 offset:3072
	v_add_u32_e32 v143, vcc_hi, v141
	ds_read_b128 v[160:163], v143
	ds_read_b128 v[164:167], v143 offset:1024
	ds_read_b128 v[168:171], v143 offset:2048
	ds_read_b128 v[172:175], v143 offset:3072
	s_mov_b32 m0, s39
	ds_read_b128 v[176:179], v142 offset:32768
	ds_read_b128 v[180:183], v142 offset:33792
	ds_read_b128 v[184:187], v142 offset:34816
	ds_read_b128 v[188:191], v142 offset:35840
	ds_read_b128 v[192:195], v142 offset:36864
	ds_read_b128 v[196:199], v142 offset:37888
	ds_read_b128 v[208:211], v142 offset:38912
	ds_read_b128 v[212:215], v142 offset:39936
	global_load_lds_dwordx4 v134, s[4:5]
	s_mov_b32 m0, s40
	s_nop 0
	global_load_lds_dwordx4 v132, s[4:5]
	s_setprio 1
	s_waitcnt vmcnt(8) lgkmcnt(0)
	s_barrier
	v_mfma_f32_16x16x32_bf16 v[126:129], v[144:147], v[176:179], v[126:129]
	v_mfma_f32_16x16x32_bf16 v[122:125], v[152:155], v[176:179], v[122:125]
	v_mfma_f32_16x16x32_bf16 v[118:121], v[144:147], v[184:187], v[118:121]
	v_mfma_f32_16x16x32_bf16 v[110:113], v[152:155], v[184:187], v[110:113]
	v_mfma_f32_16x16x32_bf16 v[102:105], v[144:147], v[192:195], v[102:105]
	v_mfma_f32_16x16x32_bf16 v[94:97], v[152:155], v[192:195], v[94:97]
	v_mfma_f32_16x16x32_bf16 v[86:89], v[144:147], v[208:211], v[86:89]
	v_mfma_f32_16x16x32_bf16 v[78:81], v[152:155], v[208:211], v[78:81]
	v_mfma_f32_16x16x32_bf16 v[126:129], v[148:151], v[180:183], v[126:129]
	v_mfma_f32_16x16x32_bf16 v[122:125], v[156:159], v[180:183], v[122:125]
	v_mfma_f32_16x16x32_bf16 v[118:121], v[148:151], v[188:191], v[118:121]
	v_mfma_f32_16x16x32_bf16 v[110:113], v[156:159], v[188:191], v[110:113]
	v_mfma_f32_16x16x32_bf16 v[102:105], v[148:151], v[196:199], v[102:105]
	v_mfma_f32_16x16x32_bf16 v[94:97], v[156:159], v[196:199], v[94:97]
	v_mfma_f32_16x16x32_bf16 v[86:89], v[148:151], v[212:215], v[86:89]
	v_mfma_f32_16x16x32_bf16 v[78:81], v[156:159], v[212:215], v[78:81]
	v_mfma_f32_16x16x32_bf16 v[114:117], v[160:163], v[176:179], v[114:117]
	v_mfma_f32_16x16x32_bf16 v[106:109], v[168:171], v[176:179], v[106:109]
	v_mfma_f32_16x16x32_bf16 v[98:101], v[160:163], v[184:187], v[98:101]
	v_mfma_f32_16x16x32_bf16 v[90:93], v[168:171], v[184:187], v[90:93]
	v_mfma_f32_16x16x32_bf16 v[82:85], v[160:163], v[192:195], v[82:85]
	v_mfma_f32_16x16x32_bf16 v[74:77], v[168:171], v[192:195], v[74:77]
	v_mfma_f32_16x16x32_bf16 v[70:73], v[160:163], v[208:211], v[70:73]
	v_mfma_f32_16x16x32_bf16 v[66:69], v[168:171], v[208:211], v[66:69]
	v_mfma_f32_16x16x32_bf16 v[114:117], v[164:167], v[180:183], v[114:117]
	v_mfma_f32_16x16x32_bf16 v[106:109], v[172:175], v[180:183], v[106:109]
	v_mfma_f32_16x16x32_bf16 v[98:101], v[164:167], v[188:191], v[98:101]
	v_mfma_f32_16x16x32_bf16 v[90:93], v[172:175], v[188:191], v[90:93]
	v_mfma_f32_16x16x32_bf16 v[82:85], v[164:167], v[196:199], v[82:85]
	v_mfma_f32_16x16x32_bf16 v[74:77], v[172:175], v[196:199], v[74:77]
	v_mfma_f32_16x16x32_bf16 v[70:73], v[164:167], v[212:215], v[70:73]
	v_mfma_f32_16x16x32_bf16 v[66:69], v[172:175], v[212:215], v[66:69]
	s_barrier
	s_setprio 0
	s_mov_b32 m0, s61
	s_add_u32 s100, s26, 0x80
	s_addc_u32 s101, s27, 0
	ds_read_b128 v[176:179], v142 offset:49152
	ds_read_b128 v[180:183], v142 offset:50176
	ds_read_b128 v[184:187], v142 offset:51200
	ds_read_b128 v[188:191], v142 offset:52224
	ds_read_b128 v[192:195], v142 offset:53248
	ds_read_b128 v[196:199], v142 offset:54272
	ds_read_b128 v[208:211], v142 offset:55296
	ds_read_b128 v[212:215], v142 offset:56320
	global_load_lds_dwordx4 v202, s[100:101]
	s_add_u32 s100, s26, 0x80
	s_addc_u32 s101, s27, 0
	s_mov_b32 m0, s62
	s_nop 0
	global_load_lds_dwordx4 v130, s[100:101]
	s_mov_b32 m0, s55
	s_nop 0
	global_load_lds_dwordx4 v202, s[2:3]
	s_mov_b32 m0, s0
	s_nop 0
	global_load_lds_dwordx4 v130, s[2:3]
	s_add_u32 s100, s24, 0x80
	s_addc_u32 s101, s25, 0
	s_mov_b32 m0, s41
	s_nop 0
	global_load_lds_dwordx4 v134, s[100:101]
	s_add_u32 s100, s24, 0x80
	s_addc_u32 s101, s25, 0
	s_mov_b32 m0, s86
	s_nop 0
	global_load_lds_dwordx4 v132, s[100:101]
	s_setprio 1
	s_waitcnt vmcnt(8) lgkmcnt(0)
	s_barrier
	v_mfma_f32_16x16x32_bf16 v[62:65], v[144:147], v[176:179], v[62:65]
	v_mfma_f32_16x16x32_bf16 v[58:61], v[152:155], v[176:179], v[58:61]
	v_mfma_f32_16x16x32_bf16 v[54:57], v[144:147], v[184:187], v[54:57]
	v_mfma_f32_16x16x32_bf16 v[46:49], v[152:155], v[184:187], v[46:49]
	v_mfma_f32_16x16x32_bf16 v[38:41], v[144:147], v[192:195], v[38:41]
	v_mfma_f32_16x16x32_bf16 v[30:33], v[152:155], v[192:195], v[30:33]
	v_mfma_f32_16x16x32_bf16 v[22:25], v[144:147], v[208:211], v[22:25]
	v_mfma_f32_16x16x32_bf16 v[14:17], v[152:155], v[208:211], v[14:17]
	v_mfma_f32_16x16x32_bf16 v[62:65], v[148:151], v[180:183], v[62:65]
	v_mfma_f32_16x16x32_bf16 v[58:61], v[156:159], v[180:183], v[58:61]
	v_mfma_f32_16x16x32_bf16 v[54:57], v[148:151], v[188:191], v[54:57]
	v_mfma_f32_16x16x32_bf16 v[46:49], v[156:159], v[188:191], v[46:49]
	v_mfma_f32_16x16x32_bf16 v[38:41], v[148:151], v[196:199], v[38:41]
	v_mfma_f32_16x16x32_bf16 v[30:33], v[156:159], v[196:199], v[30:33]
	v_mfma_f32_16x16x32_bf16 v[22:25], v[148:151], v[212:215], v[22:25]
	v_mfma_f32_16x16x32_bf16 v[14:17], v[156:159], v[212:215], v[14:17]
	v_mfma_f32_16x16x32_bf16 v[50:53], v[160:163], v[176:179], v[50:53]
	v_mfma_f32_16x16x32_bf16 v[42:45], v[168:171], v[176:179], v[42:45]
	v_mfma_f32_16x16x32_bf16 v[34:37], v[160:163], v[184:187], v[34:37]
	v_mfma_f32_16x16x32_bf16 v[26:29], v[168:171], v[184:187], v[26:29]
	v_mfma_f32_16x16x32_bf16 v[18:21], v[160:163], v[192:195], v[18:21]
	v_mfma_f32_16x16x32_bf16 v[10:13], v[168:171], v[192:195], v[10:13]
	v_mfma_f32_16x16x32_bf16 v[6:9], v[160:163], v[208:211], v[6:9]
	v_mfma_f32_16x16x32_bf16 v[2:5], v[168:171], v[208:211], v[2:5]
	v_mfma_f32_16x16x32_bf16 v[50:53], v[164:167], v[180:183], v[50:53]
	v_mfma_f32_16x16x32_bf16 v[42:45], v[172:175], v[180:183], v[42:45]
	v_mfma_f32_16x16x32_bf16 v[34:37], v[164:167], v[188:191], v[34:37]
	v_mfma_f32_16x16x32_bf16 v[26:29], v[172:175], v[188:191], v[26:29]
	v_mfma_f32_16x16x32_bf16 v[18:21], v[164:167], v[196:199], v[18:21]
	v_mfma_f32_16x16x32_bf16 v[10:13], v[172:175], v[196:199], v[10:13]
	v_mfma_f32_16x16x32_bf16 v[6:9], v[164:167], v[212:215], v[6:9]
	v_mfma_f32_16x16x32_bf16 v[2:5], v[172:175], v[212:215], v[2:5]
	s_barrier
	s_setprio 0
	s_andn2_b64 vcc, exec, s[22:23]
	s_mov_b64 s[2:3], -1
	s_mov_b64 s[22:23], 0
	s_mov_b64 s[4:5], 0x100
	s_cbranch_vccz .LBB0_1242
	s_and_b64 vcc, exec, s[10:11]
	s_cbranch_vccz .LBB0_1245
	s_barrier

.LBB0_1363:
	s_add_u32 s0, s20, 0xfffe0080
	s_addc_u32 s1, s21, -1
	s_add_i32 s33, 0, 0x10000
	s_cmp_eq_u32 s59, 4
	s_cselect_b32 s5, s38, s1
	s_cselect_b32 s4, s39, s0
	s_cselect_b32 s3, s40, s58
	s_cselect_b32 s2, s41, s49
	s_add_i32 s55, 0, 0x14000
	ds_read_b128 v[148:151], v143
	ds_read_b128 v[152:155], v143 offset:1024
	ds_read_b128 v[156:159], v143 offset:2048
	ds_read_b128 v[160:163], v143 offset:3072
	ds_read_b128 v[164:167], v143 offset:16384
	ds_read_b128 v[168:171], v143 offset:17408
	ds_read_b128 v[172:175], v143 offset:18432
	ds_read_b128 v[176:179], v143 offset:19456
	s_add_i32 m0, s25, 0xc000
	ds_read_b128 v[180:183], v146
	ds_read_b128 v[184:187], v146 offset:1024
	ds_read_b128 v[188:191], v146 offset:2048
	ds_read_b128 v[192:195], v146 offset:3072
	ds_read_b128 v[196:199], v146 offset:4096
	ds_read_b128 v[208:211], v146 offset:5120
	ds_read_b128 v[212:215], v146 offset:6144
	ds_read_b128 v[216:219], v146 offset:7168
	global_load_lds_dwordx4 v138, s[20:21]
	s_add_i32 m0, s25, 0xe000
	s_nop 0
	global_load_lds_dwordx4 v140, s[20:21]
	s_setprio 1
	s_waitcnt vmcnt(8) lgkmcnt(0)
	s_barrier
	v_mfma_f32_16x16x32_bf16 v[126:129], v[148:151], v[180:183], v[126:129]
	v_mfma_f32_16x16x32_bf16 v[122:125], v[156:159], v[180:183], v[122:125]
	v_mfma_f32_16x16x32_bf16 v[110:113], v[148:151], v[188:191], v[110:113]
	v_mfma_f32_16x16x32_bf16 v[106:109], v[156:159], v[188:191], v[106:109]
	v_mfma_f32_16x16x32_bf16 v[94:97], v[148:151], v[196:199], v[94:97]
	v_mfma_f32_16x16x32_bf16 v[90:93], v[156:159], v[196:199], v[90:93]
	v_mfma_f32_16x16x32_bf16 v[78:81], v[148:151], v[212:215], v[78:81]
	v_mfma_f32_16x16x32_bf16 v[74:77], v[156:159], v[212:215], v[74:77]
	v_mfma_f32_16x16x32_bf16 v[126:129], v[152:155], v[184:187], v[126:129]
	v_mfma_f32_16x16x32_bf16 v[122:125], v[160:163], v[184:187], v[122:125]
	v_mfma_f32_16x16x32_bf16 v[110:113], v[152:155], v[192:195], v[110:113]
	v_mfma_f32_16x16x32_bf16 v[106:109], v[160:163], v[192:195], v[106:109]
	v_mfma_f32_16x16x32_bf16 v[94:97], v[152:155], v[208:211], v[94:97]
	v_mfma_f32_16x16x32_bf16 v[90:93], v[160:163], v[208:211], v[90:93]
	v_mfma_f32_16x16x32_bf16 v[78:81], v[152:155], v[216:219], v[78:81]
	v_mfma_f32_16x16x32_bf16 v[74:77], v[160:163], v[216:219], v[74:77]
	v_mfma_f32_16x16x32_bf16 v[118:121], v[164:167], v[180:183], v[118:121]
	v_mfma_f32_16x16x32_bf16 v[114:117], v[172:175], v[180:183], v[114:117]
	v_mfma_f32_16x16x32_bf16 v[102:105], v[164:167], v[188:191], v[102:105]
	v_mfma_f32_16x16x32_bf16 v[98:101], v[172:175], v[188:191], v[98:101]
	v_mfma_f32_16x16x32_bf16 v[86:89], v[164:167], v[196:199], v[86:89]
	v_mfma_f32_16x16x32_bf16 v[82:85], v[172:175], v[196:199], v[82:85]
	v_mfma_f32_16x16x32_bf16 v[70:73], v[164:167], v[212:215], v[70:73]
	v_mfma_f32_16x16x32_bf16 v[66:69], v[172:175], v[212:215], v[66:69]
	v_mfma_f32_16x16x32_bf16 v[118:121], v[168:171], v[184:187], v[118:121]
	v_mfma_f32_16x16x32_bf16 v[114:117], v[176:179], v[184:187], v[114:117]
	v_mfma_f32_16x16x32_bf16 v[102:105], v[168:171], v[192:195], v[102:105]
	v_mfma_f32_16x16x32_bf16 v[98:101], v[176:179], v[192:195], v[98:101]
	v_mfma_f32_16x16x32_bf16 v[86:89], v[168:171], v[208:211], v[86:89]
	v_mfma_f32_16x16x32_bf16 v[82:85], v[176:179], v[208:211], v[82:85]
	v_mfma_f32_16x16x32_bf16 v[70:73], v[168:171], v[216:219], v[70:73]
	v_mfma_f32_16x16x32_bf16 v[66:69], v[176:179], v[216:219], v[66:69]
	s_barrier
	s_setprio 0
	s_add_i32 s0, s33, s24
	s_mov_b32 m0, s0
	ds_read_b128 v[180:183], v146 offset:16384
	ds_read_b128 v[184:187], v146 offset:17408
	ds_read_b128 v[188:191], v146 offset:18432
	ds_read_b128 v[192:195], v146 offset:19456
	ds_read_b128 v[196:199], v146 offset:20480
	ds_read_b128 v[208:211], v146 offset:21504
	ds_read_b128 v[212:215], v146 offset:22528
	ds_read_b128 v[216:219], v146 offset:23552
	global_load_lds_dwordx4 v134, s[2:3]
	s_add_i32 m0, s0, 0x2000
	s_add_u32 s0, s2, 0x20000
	s_addc_u32 s1, s3, 0
	s_add_i32 s33, s55, s24
	global_load_lds_dwordx4 v130, s[2:3]
	s_mov_b32 m0, s33
	s_nop 0
	global_load_lds_dwordx4 v134, s[0:1]
	s_add_i32 m0, s33, 0x2000
	s_nop 0
	global_load_lds_dwordx4 v130, s[0:1]
	s_mov_b32 m0, s25
	s_nop 0
	global_load_lds_dwordx4 v136, s[4:5]
	s_mov_b32 m0, s26
	s_nop 0
	global_load_lds_dwordx4 v132, s[4:5]
	s_setprio 1
	s_waitcnt vmcnt(8) lgkmcnt(0)
	s_barrier
	v_mfma_f32_16x16x32_bf16 v[62:65], v[148:151], v[180:183], v[62:65]
	v_mfma_f32_16x16x32_bf16 v[58:61], v[156:159], v[180:183], v[58:61]
	v_mfma_f32_16x16x32_bf16 v[46:49], v[148:151], v[188:191], v[46:49]
	v_mfma_f32_16x16x32_bf16 v[42:45], v[156:159], v[188:191], v[42:45]
	v_mfma_f32_16x16x32_bf16 v[30:33], v[148:151], v[196:199], v[30:33]
	v_mfma_f32_16x16x32_bf16 v[26:29], v[156:159], v[196:199], v[26:29]
	v_mfma_f32_16x16x32_bf16 v[14:17], v[148:151], v[212:215], v[14:17]
	v_mfma_f32_16x16x32_bf16 v[10:13], v[156:159], v[212:215], v[10:13]
	v_mfma_f32_16x16x32_bf16 v[62:65], v[152:155], v[184:187], v[62:65]
	v_mfma_f32_16x16x32_bf16 v[58:61], v[160:163], v[184:187], v[58:61]
	v_mfma_f32_16x16x32_bf16 v[46:49], v[152:155], v[192:195], v[46:49]
	v_mfma_f32_16x16x32_bf16 v[42:45], v[160:163], v[192:195], v[42:45]
	v_mfma_f32_16x16x32_bf16 v[30:33], v[152:155], v[208:211], v[30:33]
	v_mfma_f32_16x16x32_bf16 v[26:29], v[160:163], v[208:211], v[26:29]
	v_mfma_f32_16x16x32_bf16 v[14:17], v[152:155], v[216:219], v[14:17]
	v_mfma_f32_16x16x32_bf16 v[10:13], v[160:163], v[216:219], v[10:13]
	v_mfma_f32_16x16x32_bf16 v[54:57], v[164:167], v[180:183], v[54:57]
	v_mfma_f32_16x16x32_bf16 v[50:53], v[172:175], v[180:183], v[50:53]
	v_mfma_f32_16x16x32_bf16 v[38:41], v[164:167], v[188:191], v[38:41]
	v_mfma_f32_16x16x32_bf16 v[34:37], v[172:175], v[188:191], v[34:37]
	v_mfma_f32_16x16x32_bf16 v[22:25], v[164:167], v[196:199], v[22:25]
	v_mfma_f32_16x16x32_bf16 v[18:21], v[172:175], v[196:199], v[18:21]
	v_mfma_f32_16x16x32_bf16 v[6:9], v[164:167], v[212:215], v[6:9]
	v_mfma_f32_16x16x32_bf16 v[2:5], v[172:175], v[212:215], v[2:5]
	v_mfma_f32_16x16x32_bf16 v[54:57], v[168:171], v[184:187], v[54:57]
	v_mfma_f32_16x16x32_bf16 v[50:53], v[176:179], v[184:187], v[50:53]
	v_mfma_f32_16x16x32_bf16 v[38:41], v[168:171], v[192:195], v[38:41]
	v_mfma_f32_16x16x32_bf16 v[34:37], v[176:179], v[192:195], v[34:37]
	v_mfma_f32_16x16x32_bf16 v[22:25], v[168:171], v[208:211], v[22:25]
	v_mfma_f32_16x16x32_bf16 v[18:21], v[176:179], v[208:211], v[18:21]
	v_mfma_f32_16x16x32_bf16 v[6:9], v[168:171], v[216:219], v[6:9]
	v_mfma_f32_16x16x32_bf16 v[2:5], v[176:179], v[216:219], v[2:5]
	s_barrier
	s_setprio 0
	s_add_i32 s33, 0, 0x18000
	s_add_i32 s55, 0, 0x1c000
	ds_read_b128 v[148:151], v143 offset:32768
	ds_read_b128 v[152:155], v143 offset:33792
	ds_read_b128 v[156:159], v143 offset:34816
	ds_read_b128 v[160:163], v143 offset:35840
	ds_read_b128 v[164:167], v143 offset:49152
	ds_read_b128 v[168:171], v143 offset:50176
	ds_read_b128 v[172:175], v143 offset:51200
	ds_read_b128 v[176:179], v143 offset:52224
	s_add_u32 s0, s4, 0x20000
	s_addc_u32 s1, s5, 0
	s_mov_b32 m0, s27
	ds_read_b128 v[180:183], v146 offset:32768
	ds_read_b128 v[184:187], v146 offset:33792
	ds_read_b128 v[188:191], v146 offset:34816
	ds_read_b128 v[192:195], v146 offset:35840
	ds_read_b128 v[196:199], v146 offset:36864
	ds_read_b128 v[208:211], v146 offset:37888
	ds_read_b128 v[212:215], v146 offset:38912
	ds_read_b128 v[216:219], v146 offset:39936
	global_load_lds_dwordx4 v136, s[0:1]
	s_mov_b32 m0, s28
	s_nop 0
	global_load_lds_dwordx4 v132, s[0:1]
	s_setprio 1
	s_waitcnt vmcnt(8) lgkmcnt(0)
	s_barrier
	v_mfma_f32_16x16x32_bf16 v[126:129], v[148:151], v[180:183], v[126:129]
	v_mfma_f32_16x16x32_bf16 v[122:125], v[156:159], v[180:183], v[122:125]
	v_mfma_f32_16x16x32_bf16 v[110:113], v[148:151], v[188:191], v[110:113]
	v_mfma_f32_16x16x32_bf16 v[106:109], v[156:159], v[188:191], v[106:109]
	v_mfma_f32_16x16x32_bf16 v[94:97], v[148:151], v[196:199], v[94:97]
	v_mfma_f32_16x16x32_bf16 v[90:93], v[156:159], v[196:199], v[90:93]
	v_mfma_f32_16x16x32_bf16 v[78:81], v[148:151], v[212:215], v[78:81]
	v_mfma_f32_16x16x32_bf16 v[74:77], v[156:159], v[212:215], v[74:77]
	v_mfma_f32_16x16x32_bf16 v[126:129], v[152:155], v[184:187], v[126:129]
	v_mfma_f32_16x16x32_bf16 v[122:125], v[160:163], v[184:187], v[122:125]
	v_mfma_f32_16x16x32_bf16 v[110:113], v[152:155], v[192:195], v[110:113]
	v_mfma_f32_16x16x32_bf16 v[106:109], v[160:163], v[192:195], v[106:109]
	v_mfma_f32_16x16x32_bf16 v[94:97], v[152:155], v[208:211], v[94:97]
	v_mfma_f32_16x16x32_bf16 v[90:93], v[160:163], v[208:211], v[90:93]
	v_mfma_f32_16x16x32_bf16 v[78:81], v[152:155], v[216:219], v[78:81]
	v_mfma_f32_16x16x32_bf16 v[74:77], v[160:163], v[216:219], v[74:77]
	v_mfma_f32_16x16x32_bf16 v[118:121], v[164:167], v[180:183], v[118:121]
	v_mfma_f32_16x16x32_bf16 v[114:117], v[172:175], v[180:183], v[114:117]
	v_mfma_f32_16x16x32_bf16 v[102:105], v[164:167], v[188:191], v[102:105]
	v_mfma_f32_16x16x32_bf16 v[98:101], v[172:175], v[188:191], v[98:101]
	v_mfma_f32_16x16x32_bf16 v[86:89], v[164:167], v[196:199], v[86:89]
	v_mfma_f32_16x16x32_bf16 v[82:85], v[172:175], v[196:199], v[82:85]
	v_mfma_f32_16x16x32_bf16 v[70:73], v[164:167], v[212:215], v[70:73]
	v_mfma_f32_16x16x32_bf16 v[66:69], v[172:175], v[212:215], v[66:69]
	v_mfma_f32_16x16x32_bf16 v[118:121], v[168:171], v[184:187], v[118:121]
	v_mfma_f32_16x16x32_bf16 v[114:117], v[176:179], v[184:187], v[114:117]
	v_mfma_f32_16x16x32_bf16 v[102:105], v[168:171], v[192:195], v[102:105]
	v_mfma_f32_16x16x32_bf16 v[98:101], v[176:179], v[192:195], v[98:101]
	v_mfma_f32_16x16x32_bf16 v[86:89], v[168:171], v[208:211], v[86:89]
	v_mfma_f32_16x16x32_bf16 v[82:85], v[176:179], v[208:211], v[82:85]
	v_mfma_f32_16x16x32_bf16 v[70:73], v[168:171], v[216:219], v[70:73]
	v_mfma_f32_16x16x32_bf16 v[66:69], v[176:179], v[216:219], v[66:69]
	s_barrier
	s_setprio 0
	s_add_i32 s0, s33, s24
	s_add_u32 s100, s2, 0x80
	s_addc_u32 s101, s3, 0
	s_mov_b32 m0, s0
	ds_read_b128 v[180:183], v146 offset:49152
	ds_read_b128 v[184:187], v146 offset:50176
	ds_read_b128 v[188:191], v146 offset:51200
	ds_read_b128 v[192:195], v146 offset:52224
	ds_read_b128 v[196:199], v146 offset:53248
	ds_read_b128 v[208:211], v146 offset:54272
	ds_read_b128 v[212:215], v146 offset:55296
	ds_read_b128 v[216:219], v146 offset:56320
	global_load_lds_dwordx4 v134, s[100:101]
	s_add_i32 m0, s0, 0x2000
	s_add_u32 s100, s2, 0x80
	s_addc_u32 s101, s3, 0
	s_add_u32 s0, s2, 0x20080
	s_addc_u32 s1, s3, 0
	s_add_i32 s2, s55, s24
	global_load_lds_dwordx4 v130, s[100:101]
	s_mov_b32 m0, s2
	s_nop 0
	global_load_lds_dwordx4 v134, s[0:1]
	s_add_i32 m0, s2, 0x2000
	s_nop 0
	global_load_lds_dwordx4 v130, s[0:1]
	s_add_u32 s100, s4, 0x80
	s_addc_u32 s101, s5, 0
	s_mov_b32 m0, s29
	s_nop 0
	global_load_lds_dwordx4 v136, s[100:101]
	s_add_u32 s100, s4, 0x80
	s_addc_u32 s101, s5, 0
	s_mov_b32 m0, s30
	s_nop 0
	global_load_lds_dwordx4 v132, s[100:101]
	s_setprio 1
	s_waitcnt vmcnt(8) lgkmcnt(0)
	s_barrier
	v_mfma_f32_16x16x32_bf16 v[62:65], v[148:151], v[180:183], v[62:65]
	v_mfma_f32_16x16x32_bf16 v[58:61], v[156:159], v[180:183], v[58:61]
	v_mfma_f32_16x16x32_bf16 v[46:49], v[148:151], v[188:191], v[46:49]
	v_mfma_f32_16x16x32_bf16 v[42:45], v[156:159], v[188:191], v[42:45]
	v_mfma_f32_16x16x32_bf16 v[30:33], v[148:151], v[196:199], v[30:33]
	v_mfma_f32_16x16x32_bf16 v[26:29], v[156:159], v[196:199], v[26:29]
	v_mfma_f32_16x16x32_bf16 v[14:17], v[148:151], v[212:215], v[14:17]
	v_mfma_f32_16x16x32_bf16 v[10:13], v[156:159], v[212:215], v[10:13]
	v_mfma_f32_16x16x32_bf16 v[62:65], v[152:155], v[184:187], v[62:65]
	v_mfma_f32_16x16x32_bf16 v[58:61], v[160:163], v[184:187], v[58:61]
	v_mfma_f32_16x16x32_bf16 v[46:49], v[152:155], v[192:195], v[46:49]
	v_mfma_f32_16x16x32_bf16 v[42:45], v[160:163], v[192:195], v[42:45]
	v_mfma_f32_16x16x32_bf16 v[30:33], v[152:155], v[208:211], v[30:33]
	v_mfma_f32_16x16x32_bf16 v[26:29], v[160:163], v[208:211], v[26:29]
	v_mfma_f32_16x16x32_bf16 v[14:17], v[152:155], v[216:219], v[14:17]
	v_mfma_f32_16x16x32_bf16 v[10:13], v[160:163], v[216:219], v[10:13]
	v_mfma_f32_16x16x32_bf16 v[54:57], v[164:167], v[180:183], v[54:57]
	v_mfma_f32_16x16x32_bf16 v[50:53], v[172:175], v[180:183], v[50:53]
	v_mfma_f32_16x16x32_bf16 v[38:41], v[164:167], v[188:191], v[38:41]
	v_mfma_f32_16x16x32_bf16 v[34:37], v[172:175], v[188:191], v[34:37]
	v_mfma_f32_16x16x32_bf16 v[22:25], v[164:167], v[196:199], v[22:25]
	v_mfma_f32_16x16x32_bf16 v[18:21], v[172:175], v[196:199], v[18:21]
	v_mfma_f32_16x16x32_bf16 v[6:9], v[164:167], v[212:215], v[6:9]
	v_mfma_f32_16x16x32_bf16 v[2:5], v[172:175], v[212:215], v[2:5]
	v_mfma_f32_16x16x32_bf16 v[54:57], v[168:171], v[184:187], v[54:57]
	v_mfma_f32_16x16x32_bf16 v[50:53], v[176:179], v[184:187], v[50:53]
	v_mfma_f32_16x16x32_bf16 v[38:41], v[168:171], v[192:195], v[38:41]
	v_mfma_f32_16x16x32_bf16 v[34:37], v[176:179], v[192:195], v[34:37]
	v_mfma_f32_16x16x32_bf16 v[22:25], v[168:171], v[208:211], v[22:25]
	v_mfma_f32_16x16x32_bf16 v[18:21], v[176:179], v[208:211], v[18:21]
	v_mfma_f32_16x16x32_bf16 v[6:9], v[168:171], v[216:219], v[6:9]
	v_mfma_f32_16x16x32_bf16 v[2:5], v[176:179], v[216:219], v[2:5]
	s_barrier
	s_setprio 0
	s_add_i32 s59, s59, 2
	s_add_u32 s20, s20, 0x100
	s_addc_u32 s21, s21, 0
	s_add_u32 s49, s49, 0x100
	s_addc_u32 s58, s58, 0
	s_cmp_gt_u32 s59, 5
	s_cbranch_scc0 .LBB0_1363
	s_and_b64 vcc, exec, s[14:15]
	s_cbranch_vccz .LBB0_1366
	s_barrier

.LBB0_1428:
	s_add_u32 s0, s26, 0xfff80080
	s_addc_u32 s1, s27, -1
	s_add_i32 s33, 0, 0x10000
	s_cmp_eq_u32 s61, 28
	s_cselect_b32 s5, s17, s1
	s_cselect_b32 s4, s49, s0
	s_cselect_b32 s3, s15, s60
	s_cselect_b32 s2, s58, s59
	s_add_i32 s55, 0, 0x14000
	ds_read_b128 v[126:129], v187
	ds_read_b128 v[134:137], v187 offset:1024
	ds_read_b128 v[138:141], v187 offset:2048
	ds_read_b128 v[142:145], v187 offset:3072
	ds_read_b128 v[146:149], v187 offset:16384
	ds_read_b128 v[150:153], v187 offset:17408
	ds_read_b128 v[154:157], v187 offset:18432
	ds_read_b128 v[158:161], v187 offset:19456
	s_add_i32 m0, s23, 0xc000
	ds_read_b128 v[172:175], v189
	ds_read_b128 v[176:179], v189 offset:1024
	ds_read_b128 v[180:183], v189 offset:2048
	ds_read_b128 v[190:193], v189 offset:3072
	ds_read_b128 v[194:197], v189 offset:4096
	ds_read_b128 v[198:201], v189 offset:5120
	ds_read_b128 v[208:211], v189 offset:6144
	ds_read_b128 v[212:215], v189 offset:7168
	global_load_lds_dwordx4 v168, s[26:27]
	s_add_i32 m0, s23, 0xe000
	s_nop 0
	global_load_lds_dwordx4 v170, s[26:27]
	s_setprio 1
	s_waitcnt vmcnt(8) lgkmcnt(0)
	s_barrier
	v_mfma_f32_16x16x32_bf16 v[130:133], v[126:129], v[172:175], v[130:133]
	v_mfma_f32_16x16x32_bf16 v[118:121], v[138:141], v[172:175], v[118:121]
	v_mfma_f32_16x16x32_bf16 v[110:113], v[126:129], v[180:183], v[110:113]
	v_mfma_f32_16x16x32_bf16 v[102:105], v[138:141], v[180:183], v[102:105]
	v_mfma_f32_16x16x32_bf16 v[94:97], v[126:129], v[194:197], v[94:97]
	v_mfma_f32_16x16x32_bf16 v[86:89], v[138:141], v[194:197], v[86:89]
	v_mfma_f32_16x16x32_bf16 v[78:81], v[126:129], v[208:211], v[78:81]
	v_mfma_f32_16x16x32_bf16 v[70:73], v[138:141], v[208:211], v[70:73]
	v_mfma_f32_16x16x32_bf16 v[130:133], v[134:137], v[176:179], v[130:133]
	v_mfma_f32_16x16x32_bf16 v[118:121], v[142:145], v[176:179], v[118:121]
	v_mfma_f32_16x16x32_bf16 v[110:113], v[134:137], v[190:193], v[110:113]
	v_mfma_f32_16x16x32_bf16 v[102:105], v[142:145], v[190:193], v[102:105]
	v_mfma_f32_16x16x32_bf16 v[94:97], v[134:137], v[198:201], v[94:97]
	v_mfma_f32_16x16x32_bf16 v[86:89], v[142:145], v[198:201], v[86:89]
	v_mfma_f32_16x16x32_bf16 v[78:81], v[134:137], v[212:215], v[78:81]
	v_mfma_f32_16x16x32_bf16 v[70:73], v[142:145], v[212:215], v[70:73]
	v_mfma_f32_16x16x32_bf16 v[122:125], v[146:149], v[172:175], v[122:125]
	v_mfma_f32_16x16x32_bf16 v[114:117], v[154:157], v[172:175], v[114:117]
	v_mfma_f32_16x16x32_bf16 v[106:109], v[146:149], v[180:183], v[106:109]
	v_mfma_f32_16x16x32_bf16 v[98:101], v[154:157], v[180:183], v[98:101]
	v_mfma_f32_16x16x32_bf16 v[90:93], v[146:149], v[194:197], v[90:93]
	v_mfma_f32_16x16x32_bf16 v[82:85], v[154:157], v[194:197], v[82:85]
	v_mfma_f32_16x16x32_bf16 v[74:77], v[146:149], v[208:211], v[74:77]
	v_mfma_f32_16x16x32_bf16 v[66:69], v[154:157], v[208:211], v[66:69]
	v_mfma_f32_16x16x32_bf16 v[122:125], v[150:153], v[176:179], v[122:125]
	v_mfma_f32_16x16x32_bf16 v[114:117], v[158:161], v[176:179], v[114:117]
	v_mfma_f32_16x16x32_bf16 v[106:109], v[150:153], v[190:193], v[106:109]
	v_mfma_f32_16x16x32_bf16 v[98:101], v[158:161], v[190:193], v[98:101]
	v_mfma_f32_16x16x32_bf16 v[90:93], v[150:153], v[198:201], v[90:93]
	v_mfma_f32_16x16x32_bf16 v[82:85], v[158:161], v[198:201], v[82:85]
	v_mfma_f32_16x16x32_bf16 v[74:77], v[150:153], v[212:215], v[74:77]
	v_mfma_f32_16x16x32_bf16 v[66:69], v[158:161], v[212:215], v[66:69]
	s_barrier
	s_setprio 0
	s_add_i32 s0, s33, s34
	s_mov_b32 m0, s0
	ds_read_b128 v[172:175], v189 offset:16384
	ds_read_b128 v[176:179], v189 offset:17408
	ds_read_b128 v[180:183], v189 offset:18432
	ds_read_b128 v[190:193], v189 offset:19456
	ds_read_b128 v[194:197], v189 offset:20480
	ds_read_b128 v[198:201], v189 offset:21504
	ds_read_b128 v[208:211], v189 offset:22528
	ds_read_b128 v[212:215], v189 offset:23552
	global_load_lds_dwordx4 v202, s[2:3]
	s_add_i32 m0, s0, 0x2000
	s_add_u32 s0, s2, 0x80000
	s_addc_u32 s1, s3, 0
	s_add_i32 s33, s55, s34
	global_load_lds_dwordx4 v162, s[2:3]
	s_mov_b32 m0, s33
	s_nop 0
	global_load_lds_dwordx4 v202, s[0:1]
	s_add_i32 m0, s33, 0x2000
	s_nop 0
	global_load_lds_dwordx4 v162, s[0:1]
	s_mov_b32 m0, s23
	s_nop 0
	global_load_lds_dwordx4 v166, s[4:5]
	s_mov_b32 m0, s25
	s_nop 0
	global_load_lds_dwordx4 v164, s[4:5]
	s_setprio 1
	s_waitcnt vmcnt(8) lgkmcnt(0)
	s_barrier
	v_mfma_f32_16x16x32_bf16 v[62:65], v[126:129], v[172:175], v[62:65]
	v_mfma_f32_16x16x32_bf16 v[54:57], v[138:141], v[172:175], v[54:57]
	v_mfma_f32_16x16x32_bf16 v[46:49], v[126:129], v[180:183], v[46:49]
	v_mfma_f32_16x16x32_bf16 v[38:41], v[138:141], v[180:183], v[38:41]
	v_mfma_f32_16x16x32_bf16 v[30:33], v[126:129], v[194:197], v[30:33]
	v_mfma_f32_16x16x32_bf16 v[22:25], v[138:141], v[194:197], v[22:25]
	v_mfma_f32_16x16x32_bf16 v[14:17], v[126:129], v[208:211], v[14:17]
	v_mfma_f32_16x16x32_bf16 v[6:9], v[138:141], v[208:211], v[6:9]
	v_mfma_f32_16x16x32_bf16 v[62:65], v[134:137], v[176:179], v[62:65]
	v_mfma_f32_16x16x32_bf16 v[54:57], v[142:145], v[176:179], v[54:57]
	v_mfma_f32_16x16x32_bf16 v[46:49], v[134:137], v[190:193], v[46:49]
	v_mfma_f32_16x16x32_bf16 v[38:41], v[142:145], v[190:193], v[38:41]
	v_mfma_f32_16x16x32_bf16 v[30:33], v[134:137], v[198:201], v[30:33]
	v_mfma_f32_16x16x32_bf16 v[22:25], v[142:145], v[198:201], v[22:25]
	v_mfma_f32_16x16x32_bf16 v[14:17], v[134:137], v[212:215], v[14:17]
	v_mfma_f32_16x16x32_bf16 v[6:9], v[142:145], v[212:215], v[6:9]
	v_mfma_f32_16x16x32_bf16 v[58:61], v[146:149], v[172:175], v[58:61]
	v_mfma_f32_16x16x32_bf16 v[50:53], v[154:157], v[172:175], v[50:53]
	v_mfma_f32_16x16x32_bf16 v[42:45], v[146:149], v[180:183], v[42:45]
	v_mfma_f32_16x16x32_bf16 v[34:37], v[154:157], v[180:183], v[34:37]
	v_mfma_f32_16x16x32_bf16 v[26:29], v[146:149], v[194:197], v[26:29]
	v_mfma_f32_16x16x32_bf16 v[18:21], v[154:157], v[194:197], v[18:21]
	v_mfma_f32_16x16x32_bf16 v[10:13], v[146:149], v[208:211], v[10:13]
	v_mfma_f32_16x16x32_bf16 v[2:5], v[154:157], v[208:211], v[2:5]
	v_mfma_f32_16x16x32_bf16 v[58:61], v[150:153], v[176:179], v[58:61]
	v_mfma_f32_16x16x32_bf16 v[50:53], v[158:161], v[176:179], v[50:53]
	v_mfma_f32_16x16x32_bf16 v[42:45], v[150:153], v[190:193], v[42:45]
	v_mfma_f32_16x16x32_bf16 v[34:37], v[158:161], v[190:193], v[34:37]
	v_mfma_f32_16x16x32_bf16 v[26:29], v[150:153], v[198:201], v[26:29]
	v_mfma_f32_16x16x32_bf16 v[18:21], v[158:161], v[198:201], v[18:21]
	v_mfma_f32_16x16x32_bf16 v[10:13], v[150:153], v[212:215], v[10:13]
	v_mfma_f32_16x16x32_bf16 v[2:5], v[158:161], v[212:215], v[2:5]
	s_barrier
	s_setprio 0
	s_add_i32 s33, 0, 0x18000
	s_add_i32 s55, 0, 0x1c000
	ds_read_b128 v[126:129], v187 offset:32768
	ds_read_b128 v[134:137], v187 offset:33792
	ds_read_b128 v[138:141], v187 offset:34816
	ds_read_b128 v[142:145], v187 offset:35840
	ds_read_b128 v[146:149], v187 offset:49152
	ds_read_b128 v[150:153], v187 offset:50176
	ds_read_b128 v[154:157], v187 offset:51200
	ds_read_b128 v[158:161], v187 offset:52224
	s_add_u32 s0, s4, 0x80000
	s_addc_u32 s1, s5, 0
	s_mov_b32 m0, s35
	ds_read_b128 v[172:175], v189 offset:32768
	ds_read_b128 v[176:179], v189 offset:33792
	ds_read_b128 v[180:183], v189 offset:34816
	ds_read_b128 v[190:193], v189 offset:35840
	ds_read_b128 v[194:197], v189 offset:36864
	ds_read_b128 v[198:201], v189 offset:37888
	ds_read_b128 v[208:211], v189 offset:38912
	ds_read_b128 v[212:215], v189 offset:39936
	global_load_lds_dwordx4 v166, s[0:1]
	s_mov_b32 m0, s36
	s_nop 0
	global_load_lds_dwordx4 v164, s[0:1]
	s_setprio 1
	s_waitcnt vmcnt(8) lgkmcnt(0)
	s_barrier
	v_mfma_f32_16x16x32_bf16 v[130:133], v[126:129], v[172:175], v[130:133]
	v_mfma_f32_16x16x32_bf16 v[118:121], v[138:141], v[172:175], v[118:121]
	v_mfma_f32_16x16x32_bf16 v[110:113], v[126:129], v[180:183], v[110:113]
	v_mfma_f32_16x16x32_bf16 v[102:105], v[138:141], v[180:183], v[102:105]
	v_mfma_f32_16x16x32_bf16 v[94:97], v[126:129], v[194:197], v[94:97]
	v_mfma_f32_16x16x32_bf16 v[86:89], v[138:141], v[194:197], v[86:89]
	v_mfma_f32_16x16x32_bf16 v[78:81], v[126:129], v[208:211], v[78:81]
	v_mfma_f32_16x16x32_bf16 v[70:73], v[138:141], v[208:211], v[70:73]
	v_mfma_f32_16x16x32_bf16 v[130:133], v[134:137], v[176:179], v[130:133]
	v_mfma_f32_16x16x32_bf16 v[118:121], v[142:145], v[176:179], v[118:121]
	v_mfma_f32_16x16x32_bf16 v[110:113], v[134:137], v[190:193], v[110:113]
	v_mfma_f32_16x16x32_bf16 v[102:105], v[142:145], v[190:193], v[102:105]
	v_mfma_f32_16x16x32_bf16 v[94:97], v[134:137], v[198:201], v[94:97]
	v_mfma_f32_16x16x32_bf16 v[86:89], v[142:145], v[198:201], v[86:89]
	v_mfma_f32_16x16x32_bf16 v[78:81], v[134:137], v[212:215], v[78:81]
	v_mfma_f32_16x16x32_bf16 v[70:73], v[142:145], v[212:215], v[70:73]
	v_mfma_f32_16x16x32_bf16 v[122:125], v[146:149], v[172:175], v[122:125]
	v_mfma_f32_16x16x32_bf16 v[114:117], v[154:157], v[172:175], v[114:117]
	v_mfma_f32_16x16x32_bf16 v[106:109], v[146:149], v[180:183], v[106:109]
	v_mfma_f32_16x16x32_bf16 v[98:101], v[154:157], v[180:183], v[98:101]
	v_mfma_f32_16x16x32_bf16 v[90:93], v[146:149], v[194:197], v[90:93]
	v_mfma_f32_16x16x32_bf16 v[82:85], v[154:157], v[194:197], v[82:85]
	v_mfma_f32_16x16x32_bf16 v[74:77], v[146:149], v[208:211], v[74:77]
	v_mfma_f32_16x16x32_bf16 v[66:69], v[154:157], v[208:211], v[66:69]
	v_mfma_f32_16x16x32_bf16 v[122:125], v[150:153], v[176:179], v[122:125]
	v_mfma_f32_16x16x32_bf16 v[114:117], v[158:161], v[176:179], v[114:117]
	v_mfma_f32_16x16x32_bf16 v[106:109], v[150:153], v[190:193], v[106:109]
	v_mfma_f32_16x16x32_bf16 v[98:101], v[158:161], v[190:193], v[98:101]
	v_mfma_f32_16x16x32_bf16 v[90:93], v[150:153], v[198:201], v[90:93]
	v_mfma_f32_16x16x32_bf16 v[82:85], v[158:161], v[198:201], v[82:85]
	v_mfma_f32_16x16x32_bf16 v[74:77], v[150:153], v[212:215], v[74:77]
	v_mfma_f32_16x16x32_bf16 v[66:69], v[158:161], v[212:215], v[66:69]
	s_barrier
	s_setprio 0
	s_add_i32 s0, s33, s34
	s_add_u32 s100, s2, 0x80
	s_addc_u32 s101, s3, 0
	s_mov_b32 m0, s0
	ds_read_b128 v[172:175], v189 offset:49152
	ds_read_b128 v[176:179], v189 offset:50176
	ds_read_b128 v[180:183], v189 offset:51200
	ds_read_b128 v[190:193], v189 offset:52224
	ds_read_b128 v[194:197], v189 offset:53248
	ds_read_b128 v[198:201], v189 offset:54272
	ds_read_b128 v[208:211], v189 offset:55296
	ds_read_b128 v[212:215], v189 offset:56320
	global_load_lds_dwordx4 v202, s[100:101]
	s_add_i32 m0, s0, 0x2000
	s_add_u32 s100, s2, 0x80
	s_addc_u32 s101, s3, 0
	s_add_u32 s0, s2, 0x80080
	s_addc_u32 s1, s3, 0
	s_add_i32 s2, s55, s34
	global_load_lds_dwordx4 v162, s[100:101]
	s_mov_b32 m0, s2
	s_nop 0
	global_load_lds_dwordx4 v202, s[0:1]
	s_add_i32 m0, s2, 0x2000
	s_nop 0
	global_load_lds_dwordx4 v162, s[0:1]
	s_add_u32 s100, s4, 0x80
	s_addc_u32 s101, s5, 0
	s_mov_b32 m0, s39
	s_nop 0
	global_load_lds_dwordx4 v166, s[100:101]
	s_add_u32 s100, s4, 0x80
	s_addc_u32 s101, s5, 0
	s_mov_b32 m0, s40
	s_nop 0
	global_load_lds_dwordx4 v164, s[100:101]
	s_setprio 1
	s_waitcnt vmcnt(8) lgkmcnt(0)
	s_barrier
	v_mfma_f32_16x16x32_bf16 v[62:65], v[126:129], v[172:175], v[62:65]
	v_mfma_f32_16x16x32_bf16 v[54:57], v[138:141], v[172:175], v[54:57]
	v_mfma_f32_16x16x32_bf16 v[46:49], v[126:129], v[180:183], v[46:49]
	v_mfma_f32_16x16x32_bf16 v[38:41], v[138:141], v[180:183], v[38:41]
	v_mfma_f32_16x16x32_bf16 v[30:33], v[126:129], v[194:197], v[30:33]
	v_mfma_f32_16x16x32_bf16 v[22:25], v[138:141], v[194:197], v[22:25]
	v_mfma_f32_16x16x32_bf16 v[14:17], v[126:129], v[208:211], v[14:17]
	v_mfma_f32_16x16x32_bf16 v[6:9], v[138:141], v[208:211], v[6:9]
	v_mfma_f32_16x16x32_bf16 v[62:65], v[134:137], v[176:179], v[62:65]
	v_mfma_f32_16x16x32_bf16 v[54:57], v[142:145], v[176:179], v[54:57]
	v_mfma_f32_16x16x32_bf16 v[46:49], v[134:137], v[190:193], v[46:49]
	v_mfma_f32_16x16x32_bf16 v[38:41], v[142:145], v[190:193], v[38:41]
	v_mfma_f32_16x16x32_bf16 v[30:33], v[134:137], v[198:201], v[30:33]
	v_mfma_f32_16x16x32_bf16 v[22:25], v[142:145], v[198:201], v[22:25]
	v_mfma_f32_16x16x32_bf16 v[14:17], v[134:137], v[212:215], v[14:17]
	v_mfma_f32_16x16x32_bf16 v[6:9], v[142:145], v[212:215], v[6:9]
	v_mfma_f32_16x16x32_bf16 v[58:61], v[146:149], v[172:175], v[58:61]
	v_mfma_f32_16x16x32_bf16 v[50:53], v[154:157], v[172:175], v[50:53]
	v_mfma_f32_16x16x32_bf16 v[42:45], v[146:149], v[180:183], v[42:45]
	v_mfma_f32_16x16x32_bf16 v[34:37], v[154:157], v[180:183], v[34:37]
	v_mfma_f32_16x16x32_bf16 v[26:29], v[146:149], v[194:197], v[26:29]
	v_mfma_f32_16x16x32_bf16 v[18:21], v[154:157], v[194:197], v[18:21]
	v_mfma_f32_16x16x32_bf16 v[10:13], v[146:149], v[208:211], v[10:13]
	v_mfma_f32_16x16x32_bf16 v[2:5], v[154:157], v[208:211], v[2:5]
	v_mfma_f32_16x16x32_bf16 v[58:61], v[150:153], v[176:179], v[58:61]
	v_mfma_f32_16x16x32_bf16 v[50:53], v[158:161], v[176:179], v[50:53]
	v_mfma_f32_16x16x32_bf16 v[42:45], v[150:153], v[190:193], v[42:45]
	v_mfma_f32_16x16x32_bf16 v[34:37], v[158:161], v[190:193], v[34:37]
	v_mfma_f32_16x16x32_bf16 v[26:29], v[150:153], v[198:201], v[26:29]
	v_mfma_f32_16x16x32_bf16 v[18:21], v[158:161], v[198:201], v[18:21]
	v_mfma_f32_16x16x32_bf16 v[10:13], v[150:153], v[212:215], v[10:13]
	v_mfma_f32_16x16x32_bf16 v[2:5], v[158:161], v[212:215], v[2:5]
	s_barrier
	s_setprio 0
	s_add_i32 s61, s61, 2
	s_add_u32 s26, s26, 0x100
	s_addc_u32 s27, s27, 0
	s_add_u32 s59, s59, 0x100
	s_addc_u32 s60, s60, 0
	s_cmp_gt_u32 s61, 29
	s_cbranch_scc0 .LBB0_1428
	s_and_b64 vcc, exec, s[10:11]
	s_cbranch_vccz .LBB0_1431
	s_barrier

.LBB0_1593:
	s_ashr_i32 s19, s18, 31
	s_lshl_b64 s[0:1], s[18:19], 20
	s_add_u32 s20, s42, s0
	s_addc_u32 s21, s43, s1
	s_and_b64 s[0:1], s[8:9], exec
	s_cselect_b32 s19, s21, s5
	s_cselect_b32 s49, s20, s4
	s_ashr_i32 s17, s16, 31
	s_lshl_b64 s[0:1], s[16:17], 20
	s_add_u32 s22, s30, s0
	s_addc_u32 s23, s31, s1
	s_and_b64 s[0:1], s[8:9], exec
	s_cselect_b32 s17, s23, s3
	s_cselect_b32 s58, s22, s2
	s_add_u32 s28, s4, 0x80080
	s_addc_u32 s29, s5, 0
	s_add_u32 s59, s2, 0x100
	v_mov_b32_e32 v2, 0
	s_addc_u32 s60, s3, 0
	s_mov_b32 s61, -2
	v_mov_b32_e32 v3, v2
	v_pk_mov_b32 v[4:5], v[2:3], v[2:3] op_sel:[0,1]
	v_pk_mov_b32 v[10:11], v[2:3], v[2:3] op_sel:[0,1]
	v_pk_mov_b32 v[12:13], v[2:3], v[2:3] op_sel:[0,1]
	v_pk_mov_b32 v[18:19], v[2:3], v[2:3] op_sel:[0,1]
	v_pk_mov_b32 v[20:21], v[2:3], v[2:3] op_sel:[0,1]
	v_pk_mov_b32 v[26:27], v[2:3], v[2:3] op_sel:[0,1]
	v_pk_mov_b32 v[28:29], v[2:3], v[2:3] op_sel:[0,1]
	v_pk_mov_b32 v[34:35], v[2:3], v[2:3] op_sel:[0,1]
	v_pk_mov_b32 v[36:37], v[2:3], v[2:3] op_sel:[0,1]
	v_pk_mov_b32 v[42:43], v[2:3], v[2:3] op_sel:[0,1]
	v_pk_mov_b32 v[44:45], v[2:3], v[2:3] op_sel:[0,1]
	v_pk_mov_b32 v[50:51], v[2:3], v[2:3] op_sel:[0,1]
	v_pk_mov_b32 v[52:53], v[2:3], v[2:3] op_sel:[0,1]
	v_pk_mov_b32 v[58:59], v[2:3], v[2:3] op_sel:[0,1]
	v_pk_mov_b32 v[60:61], v[2:3], v[2:3] op_sel:[0,1]
	v_pk_mov_b32 v[6:7], v[2:3], v[2:3] op_sel:[0,1]
	v_pk_mov_b32 v[8:9], v[2:3], v[2:3] op_sel:[0,1]
	v_pk_mov_b32 v[14:15], v[2:3], v[2:3] op_sel:[0,1]
	v_pk_mov_b32 v[16:17], v[2:3], v[2:3] op_sel:[0,1]
	v_pk_mov_b32 v[22:23], v[2:3], v[2:3] op_sel:[0,1]
	v_pk_mov_b32 v[24:25], v[2:3], v[2:3] op_sel:[0,1]
	v_pk_mov_b32 v[30:31], v[2:3], v[2:3] op_sel:[0,1]
	v_pk_mov_b32 v[32:33], v[2:3], v[2:3] op_sel:[0,1]
	v_pk_mov_b32 v[38:39], v[2:3], v[2:3] op_sel:[0,1]
	v_pk_mov_b32 v[40:41], v[2:3], v[2:3] op_sel:[0,1]
	v_pk_mov_b32 v[46:47], v[2:3], v[2:3] op_sel:[0,1]
	v_pk_mov_b32 v[48:49], v[2:3], v[2:3] op_sel:[0,1]
	v_pk_mov_b32 v[54:55], v[2:3], v[2:3] op_sel:[0,1]
	v_pk_mov_b32 v[56:57], v[2:3], v[2:3] op_sel:[0,1]
	v_pk_mov_b32 v[62:63], v[2:3], v[2:3] op_sel:[0,1]
	v_pk_mov_b32 v[64:65], v[2:3], v[2:3] op_sel:[0,1]
	v_pk_mov_b32 v[66:67], v[2:3], v[2:3] op_sel:[0,1]
	v_pk_mov_b32 v[68:69], v[2:3], v[2:3] op_sel:[0,1]
	v_pk_mov_b32 v[74:75], v[2:3], v[2:3] op_sel:[0,1]
	v_pk_mov_b32 v[76:77], v[2:3], v[2:3] op_sel:[0,1]
	v_pk_mov_b32 v[82:83], v[2:3], v[2:3] op_sel:[0,1]
	v_pk_mov_b32 v[84:85], v[2:3], v[2:3] op_sel:[0,1]
	v_pk_mov_b32 v[90:91], v[2:3], v[2:3] op_sel:[0,1]
	v_pk_mov_b32 v[92:93], v[2:3], v[2:3] op_sel:[0,1]
	v_pk_mov_b32 v[98:99], v[2:3], v[2:3] op_sel:[0,1]
	v_pk_mov_b32 v[100:101], v[2:3], v[2:3] op_sel:[0,1]
	v_pk_mov_b32 v[106:107], v[2:3], v[2:3] op_sel:[0,1]
	v_pk_mov_b32 v[108:109], v[2:3], v[2:3] op_sel:[0,1]
	v_pk_mov_b32 v[114:115], v[2:3], v[2:3] op_sel:[0,1]
	v_pk_mov_b32 v[116:117], v[2:3], v[2:3] op_sel:[0,1]
	v_pk_mov_b32 v[122:123], v[2:3], v[2:3] op_sel:[0,1]
	v_pk_mov_b32 v[124:125], v[2:3], v[2:3] op_sel:[0,1]
	v_pk_mov_b32 v[70:71], v[2:3], v[2:3] op_sel:[0,1]
	v_pk_mov_b32 v[72:73], v[2:3], v[2:3] op_sel:[0,1]
	v_pk_mov_b32 v[78:79], v[2:3], v[2:3] op_sel:[0,1]
	v_pk_mov_b32 v[80:81], v[2:3], v[2:3] op_sel:[0,1]
	v_pk_mov_b32 v[86:87], v[2:3], v[2:3] op_sel:[0,1]
	v_pk_mov_b32 v[88:89], v[2:3], v[2:3] op_sel:[0,1]
	v_pk_mov_b32 v[94:95], v[2:3], v[2:3] op_sel:[0,1]
	v_pk_mov_b32 v[96:97], v[2:3], v[2:3] op_sel:[0,1]
	v_pk_mov_b32 v[102:103], v[2:3], v[2:3] op_sel:[0,1]
	v_pk_mov_b32 v[104:105], v[2:3], v[2:3] op_sel:[0,1]
	v_pk_mov_b32 v[110:111], v[2:3], v[2:3] op_sel:[0,1]
	v_pk_mov_b32 v[112:113], v[2:3], v[2:3] op_sel:[0,1]
	v_pk_mov_b32 v[118:119], v[2:3], v[2:3] op_sel:[0,1]
	v_pk_mov_b32 v[120:121], v[2:3], v[2:3] op_sel:[0,1]
	v_pk_mov_b32 v[126:127], v[2:3], v[2:3] op_sel:[0,1]
	v_pk_mov_b32 v[128:129], v[2:3], v[2:3] op_sel:[0,1]
	s_cmp_eq_u32 s101, 0x80000001
	s_cbranch_scc0 .LBB0_1594
	s_add_u32 s0, s28, 0xfff80080
	s_addc_u32 s1, s29, -1
	s_add_i32 s33, 0, 0x10000
	s_cmp_eq_u32 s61, 28
	s_cselect_b32 s5, s19, s1
	s_cselect_b32 s4, s49, s0
	s_cselect_b32 s3, s17, s60
	s_cselect_b32 s2, s58, s59
	s_add_i32 s55, 0, 0x14000
	ds_read_b128 v[146:149], v143
	ds_read_b128 v[150:153], v143 offset:1024
	ds_read_b128 v[154:157], v143 offset:2048
	ds_read_b128 v[158:161], v143 offset:3072
	ds_read_b128 v[162:165], v143 offset:16384
	ds_read_b128 v[166:169], v143 offset:17408
	ds_read_b128 v[170:173], v143 offset:18432
	ds_read_b128 v[174:177], v143 offset:19456
	s_add_i32 m0, s25, 0xc000
	ds_read_b128 v[178:181], v145
	ds_read_b128 v[182:185], v145 offset:1024
	ds_read_b128 v[186:189], v145 offset:2048
	ds_read_b128 v[190:193], v145 offset:3072
	ds_read_b128 v[194:197], v145 offset:4096
	ds_read_b128 v[198:201], v145 offset:5120
	ds_read_b128 v[208:211], v145 offset:6144
	ds_read_b128 v[212:215], v145 offset:7168
	global_load_lds_dwordx4 v136, s[28:29]
	s_add_i32 m0, s25, 0xe000
	s_nop 0
	global_load_lds_dwordx4 v138, s[28:29]
	s_setprio 1
	s_waitcnt vmcnt(16) lgkmcnt(0)
	s_barrier
	v_mfma_f32_16x16x32_bf16 v[126:129], v[146:149], v[178:181], v[126:129]
	v_mfma_f32_16x16x32_bf16 v[118:121], v[154:157], v[178:181], v[118:121]
	v_mfma_f32_16x16x32_bf16 v[110:113], v[146:149], v[186:189], v[110:113]
	v_mfma_f32_16x16x32_bf16 v[102:105], v[154:157], v[186:189], v[102:105]
	v_mfma_f32_16x16x32_bf16 v[94:97], v[146:149], v[194:197], v[94:97]
	v_mfma_f32_16x16x32_bf16 v[86:89], v[154:157], v[194:197], v[86:89]
	v_mfma_f32_16x16x32_bf16 v[78:81], v[146:149], v[208:211], v[78:81]
	v_mfma_f32_16x16x32_bf16 v[70:73], v[154:157], v[208:211], v[70:73]
	v_mfma_f32_16x16x32_bf16 v[126:129], v[150:153], v[182:185], v[126:129]
	v_mfma_f32_16x16x32_bf16 v[118:121], v[158:161], v[182:185], v[118:121]
	v_mfma_f32_16x16x32_bf16 v[110:113], v[150:153], v[190:193], v[110:113]
	v_mfma_f32_16x16x32_bf16 v[102:105], v[158:161], v[190:193], v[102:105]
	v_mfma_f32_16x16x32_bf16 v[94:97], v[150:153], v[198:201], v[94:97]
	v_mfma_f32_16x16x32_bf16 v[86:89], v[158:161], v[198:201], v[86:89]
	v_mfma_f32_16x16x32_bf16 v[78:81], v[150:153], v[212:215], v[78:81]
	v_mfma_f32_16x16x32_bf16 v[70:73], v[158:161], v[212:215], v[70:73]
	v_mfma_f32_16x16x32_bf16 v[122:125], v[162:165], v[178:181], v[122:125]
	v_mfma_f32_16x16x32_bf16 v[114:117], v[170:173], v[178:181], v[114:117]
	v_mfma_f32_16x16x32_bf16 v[106:109], v[162:165], v[186:189], v[106:109]
	v_mfma_f32_16x16x32_bf16 v[98:101], v[170:173], v[186:189], v[98:101]
	v_mfma_f32_16x16x32_bf16 v[90:93], v[162:165], v[194:197], v[90:93]
	v_mfma_f32_16x16x32_bf16 v[82:85], v[170:173], v[194:197], v[82:85]
	v_mfma_f32_16x16x32_bf16 v[74:77], v[162:165], v[208:211], v[74:77]
	v_mfma_f32_16x16x32_bf16 v[66:69], v[170:173], v[208:211], v[66:69]
	v_mfma_f32_16x16x32_bf16 v[122:125], v[166:169], v[182:185], v[122:125]
	v_mfma_f32_16x16x32_bf16 v[114:117], v[174:177], v[182:185], v[114:117]
	v_mfma_f32_16x16x32_bf16 v[106:109], v[166:169], v[190:193], v[106:109]
	v_mfma_f32_16x16x32_bf16 v[98:101], v[174:177], v[190:193], v[98:101]
	v_mfma_f32_16x16x32_bf16 v[90:93], v[166:169], v[198:201], v[90:93]
	v_mfma_f32_16x16x32_bf16 v[82:85], v[174:177], v[198:201], v[82:85]
	v_mfma_f32_16x16x32_bf16 v[74:77], v[166:169], v[212:215], v[74:77]
	v_mfma_f32_16x16x32_bf16 v[66:69], v[174:177], v[212:215], v[66:69]
	s_barrier
	s_setprio 0
	s_add_i32 s0, s33, s36
	s_mov_b32 m0, s0
	ds_read_b128 v[178:181], v145 offset:16384
	ds_read_b128 v[182:185], v145 offset:17408
	ds_read_b128 v[186:189], v145 offset:18432
	ds_read_b128 v[190:193], v145 offset:19456
	ds_read_b128 v[194:197], v145 offset:20480
	ds_read_b128 v[198:201], v145 offset:21504
	ds_read_b128 v[208:211], v145 offset:22528
	ds_read_b128 v[212:215], v145 offset:23552
	global_load_lds_dwordx4 v202, s[2:3]
	s_add_i32 m0, s0, 0x2000
	s_add_u32 s0, s2, 0x80000
	s_addc_u32 s1, s3, 0
	s_add_i32 s33, s55, s36
	global_load_lds_dwordx4 v130, s[2:3]
	s_mov_b32 m0, s33
	s_nop 0
	global_load_lds_dwordx4 v202, s[0:1]
	s_add_i32 m0, s33, 0x2000
	s_nop 0
	global_load_lds_dwordx4 v130, s[0:1]
	s_mov_b32 m0, s25
	s_nop 0
	global_load_lds_dwordx4 v134, s[4:5]
	s_mov_b32 m0, s27
	s_nop 0
	global_load_lds_dwordx4 v132, s[4:5]
	s_setprio 1
	s_waitcnt vmcnt(16) lgkmcnt(0)
	s_barrier
	v_mfma_f32_16x16x32_bf16 v[62:65], v[146:149], v[178:181], v[62:65]
	v_mfma_f32_16x16x32_bf16 v[54:57], v[154:157], v[178:181], v[54:57]
	v_mfma_f32_16x16x32_bf16 v[46:49], v[146:149], v[186:189], v[46:49]
	v_mfma_f32_16x16x32_bf16 v[38:41], v[154:157], v[186:189], v[38:41]
	v_mfma_f32_16x16x32_bf16 v[30:33], v[146:149], v[194:197], v[30:33]
	v_mfma_f32_16x16x32_bf16 v[22:25], v[154:157], v[194:197], v[22:25]
	v_mfma_f32_16x16x32_bf16 v[14:17], v[146:149], v[208:211], v[14:17]
	v_mfma_f32_16x16x32_bf16 v[6:9], v[154:157], v[208:211], v[6:9]
	v_mfma_f32_16x16x32_bf16 v[62:65], v[150:153], v[182:185], v[62:65]
	v_mfma_f32_16x16x32_bf16 v[54:57], v[158:161], v[182:185], v[54:57]
	v_mfma_f32_16x16x32_bf16 v[46:49], v[150:153], v[190:193], v[46:49]
	v_mfma_f32_16x16x32_bf16 v[38:41], v[158:161], v[190:193], v[38:41]
	v_mfma_f32_16x16x32_bf16 v[30:33], v[150:153], v[198:201], v[30:33]
	v_mfma_f32_16x16x32_bf16 v[22:25], v[158:161], v[198:201], v[22:25]
	v_mfma_f32_16x16x32_bf16 v[14:17], v[150:153], v[212:215], v[14:17]
	v_mfma_f32_16x16x32_bf16 v[6:9], v[158:161], v[212:215], v[6:9]
	v_mfma_f32_16x16x32_bf16 v[58:61], v[162:165], v[178:181], v[58:61]
	v_mfma_f32_16x16x32_bf16 v[50:53], v[170:173], v[178:181], v[50:53]
	v_mfma_f32_16x16x32_bf16 v[42:45], v[162:165], v[186:189], v[42:45]
	v_mfma_f32_16x16x32_bf16 v[34:37], v[170:173], v[186:189], v[34:37]
	v_mfma_f32_16x16x32_bf16 v[26:29], v[162:165], v[194:197], v[26:29]
	v_mfma_f32_16x16x32_bf16 v[18:21], v[170:173], v[194:197], v[18:21]
	v_mfma_f32_16x16x32_bf16 v[10:13], v[162:165], v[208:211], v[10:13]
	v_mfma_f32_16x16x32_bf16 v[2:5], v[170:173], v[208:211], v[2:5]
	v_mfma_f32_16x16x32_bf16 v[58:61], v[166:169], v[182:185], v[58:61]
	v_mfma_f32_16x16x32_bf16 v[50:53], v[174:177], v[182:185], v[50:53]
	v_mfma_f32_16x16x32_bf16 v[42:45], v[166:169], v[190:193], v[42:45]
	v_mfma_f32_16x16x32_bf16 v[34:37], v[174:177], v[190:193], v[34:37]
	v_mfma_f32_16x16x32_bf16 v[26:29], v[166:169], v[198:201], v[26:29]
	v_mfma_f32_16x16x32_bf16 v[18:21], v[174:177], v[198:201], v[18:21]
	v_mfma_f32_16x16x32_bf16 v[10:13], v[166:169], v[212:215], v[10:13]
	v_mfma_f32_16x16x32_bf16 v[2:5], v[174:177], v[212:215], v[2:5]
	s_barrier
	s_setprio 0
	s_branch .Lpeel_mid_10
.LBB0_1594:
	s_add_u32 s0, s28, 0xfff80080
	s_addc_u32 s1, s29, -1
	s_add_i32 s33, 0, 0x10000
	s_cmp_eq_u32 s61, 28
	s_cselect_b32 s5, s19, s1
	s_cselect_b32 s4, s49, s0
	s_cselect_b32 s3, s17, s60
	s_cselect_b32 s2, s58, s59
	s_add_i32 s55, 0, 0x14000
	ds_read_b128 v[146:149], v143
	ds_read_b128 v[150:153], v143 offset:1024
	ds_read_b128 v[154:157], v143 offset:2048
	ds_read_b128 v[158:161], v143 offset:3072
	ds_read_b128 v[162:165], v143 offset:16384
	ds_read_b128 v[166:169], v143 offset:17408
	ds_read_b128 v[170:173], v143 offset:18432
	ds_read_b128 v[174:177], v143 offset:19456
	s_add_i32 m0, s25, 0xc000
	ds_read_b128 v[178:181], v145
	ds_read_b128 v[182:185], v145 offset:1024
	ds_read_b128 v[186:189], v145 offset:2048
	ds_read_b128 v[190:193], v145 offset:3072
	ds_read_b128 v[194:197], v145 offset:4096
	ds_read_b128 v[198:201], v145 offset:5120
	ds_read_b128 v[208:211], v145 offset:6144
	ds_read_b128 v[212:215], v145 offset:7168
	global_load_lds_dwordx4 v136, s[28:29]
	s_add_i32 m0, s25, 0xe000
	s_nop 0
	global_load_lds_dwordx4 v138, s[28:29]
	s_setprio 1
	s_waitcnt vmcnt(8) lgkmcnt(0)
	s_barrier
	v_mfma_f32_16x16x32_bf16 v[126:129], v[146:149], v[178:181], v[126:129]
	v_mfma_f32_16x16x32_bf16 v[118:121], v[154:157], v[178:181], v[118:121]
	v_mfma_f32_16x16x32_bf16 v[110:113], v[146:149], v[186:189], v[110:113]
	v_mfma_f32_16x16x32_bf16 v[102:105], v[154:157], v[186:189], v[102:105]
	v_mfma_f32_16x16x32_bf16 v[94:97], v[146:149], v[194:197], v[94:97]
	v_mfma_f32_16x16x32_bf16 v[86:89], v[154:157], v[194:197], v[86:89]
	v_mfma_f32_16x16x32_bf16 v[78:81], v[146:149], v[208:211], v[78:81]
	v_mfma_f32_16x16x32_bf16 v[70:73], v[154:157], v[208:211], v[70:73]
	v_mfma_f32_16x16x32_bf16 v[126:129], v[150:153], v[182:185], v[126:129]
	v_mfma_f32_16x16x32_bf16 v[118:121], v[158:161], v[182:185], v[118:121]
	v_mfma_f32_16x16x32_bf16 v[110:113], v[150:153], v[190:193], v[110:113]
	v_mfma_f32_16x16x32_bf16 v[102:105], v[158:161], v[190:193], v[102:105]
	v_mfma_f32_16x16x32_bf16 v[94:97], v[150:153], v[198:201], v[94:97]
	v_mfma_f32_16x16x32_bf16 v[86:89], v[158:161], v[198:201], v[86:89]
	v_mfma_f32_16x16x32_bf16 v[78:81], v[150:153], v[212:215], v[78:81]
	v_mfma_f32_16x16x32_bf16 v[70:73], v[158:161], v[212:215], v[70:73]
	v_mfma_f32_16x16x32_bf16 v[122:125], v[162:165], v[178:181], v[122:125]
	v_mfma_f32_16x16x32_bf16 v[114:117], v[170:173], v[178:181], v[114:117]
	v_mfma_f32_16x16x32_bf16 v[106:109], v[162:165], v[186:189], v[106:109]
	v_mfma_f32_16x16x32_bf16 v[98:101], v[170:173], v[186:189], v[98:101]
	v_mfma_f32_16x16x32_bf16 v[90:93], v[162:165], v[194:197], v[90:93]
	v_mfma_f32_16x16x32_bf16 v[82:85], v[170:173], v[194:197], v[82:85]
	v_mfma_f32_16x16x32_bf16 v[74:77], v[162:165], v[208:211], v[74:77]
	v_mfma_f32_16x16x32_bf16 v[66:69], v[170:173], v[208:211], v[66:69]
	v_mfma_f32_16x16x32_bf16 v[122:125], v[166:169], v[182:185], v[122:125]
	v_mfma_f32_16x16x32_bf16 v[114:117], v[174:177], v[182:185], v[114:117]
	v_mfma_f32_16x16x32_bf16 v[106:109], v[166:169], v[190:193], v[106:109]
	v_mfma_f32_16x16x32_bf16 v[98:101], v[174:177], v[190:193], v[98:101]
	v_mfma_f32_16x16x32_bf16 v[90:93], v[166:169], v[198:201], v[90:93]
	v_mfma_f32_16x16x32_bf16 v[82:85], v[174:177], v[198:201], v[82:85]
	v_mfma_f32_16x16x32_bf16 v[74:77], v[166:169], v[212:215], v[74:77]
	v_mfma_f32_16x16x32_bf16 v[66:69], v[174:177], v[212:215], v[66:69]
	s_barrier
	s_setprio 0
	s_add_i32 s0, s33, s36
	s_mov_b32 m0, s0
	ds_read_b128 v[178:181], v145 offset:16384
	ds_read_b128 v[182:185], v145 offset:17408
	ds_read_b128 v[186:189], v145 offset:18432
	ds_read_b128 v[190:193], v145 offset:19456
	ds_read_b128 v[194:197], v145 offset:20480
	ds_read_b128 v[198:201], v145 offset:21504
	ds_read_b128 v[208:211], v145 offset:22528
	ds_read_b128 v[212:215], v145 offset:23552
	global_load_lds_dwordx4 v202, s[2:3]
	s_add_i32 m0, s0, 0x2000
	s_add_u32 s0, s2, 0x80000
	s_addc_u32 s1, s3, 0
	s_add_i32 s33, s55, s36
	global_load_lds_dwordx4 v130, s[2:3]
	s_mov_b32 m0, s33
	s_nop 0
	global_load_lds_dwordx4 v202, s[0:1]
	s_add_i32 m0, s33, 0x2000
	s_nop 0
	global_load_lds_dwordx4 v130, s[0:1]
	s_mov_b32 m0, s25
	s_nop 0
	global_load_lds_dwordx4 v134, s[4:5]
	s_mov_b32 m0, s27
	s_nop 0
	global_load_lds_dwordx4 v132, s[4:5]
	s_setprio 1
	s_waitcnt vmcnt(8) lgkmcnt(0)
	s_barrier
	v_mfma_f32_16x16x32_bf16 v[62:65], v[146:149], v[178:181], v[62:65]
	v_mfma_f32_16x16x32_bf16 v[54:57], v[154:157], v[178:181], v[54:57]
	v_mfma_f32_16x16x32_bf16 v[46:49], v[146:149], v[186:189], v[46:49]
	v_mfma_f32_16x16x32_bf16 v[38:41], v[154:157], v[186:189], v[38:41]
	v_mfma_f32_16x16x32_bf16 v[30:33], v[146:149], v[194:197], v[30:33]
	v_mfma_f32_16x16x32_bf16 v[22:25], v[154:157], v[194:197], v[22:25]
	v_mfma_f32_16x16x32_bf16 v[14:17], v[146:149], v[208:211], v[14:17]
	v_mfma_f32_16x16x32_bf16 v[6:9], v[154:157], v[208:211], v[6:9]
	v_mfma_f32_16x16x32_bf16 v[62:65], v[150:153], v[182:185], v[62:65]
	v_mfma_f32_16x16x32_bf16 v[54:57], v[158:161], v[182:185], v[54:57]
	v_mfma_f32_16x16x32_bf16 v[46:49], v[150:153], v[190:193], v[46:49]
	v_mfma_f32_16x16x32_bf16 v[38:41], v[158:161], v[190:193], v[38:41]
	v_mfma_f32_16x16x32_bf16 v[30:33], v[150:153], v[198:201], v[30:33]
	v_mfma_f32_16x16x32_bf16 v[22:25], v[158:161], v[198:201], v[22:25]
	v_mfma_f32_16x16x32_bf16 v[14:17], v[150:153], v[212:215], v[14:17]
	v_mfma_f32_16x16x32_bf16 v[6:9], v[158:161], v[212:215], v[6:9]
	v_mfma_f32_16x16x32_bf16 v[58:61], v[162:165], v[178:181], v[58:61]
	v_mfma_f32_16x16x32_bf16 v[50:53], v[170:173], v[178:181], v[50:53]
	v_mfma_f32_16x16x32_bf16 v[42:45], v[162:165], v[186:189], v[42:45]
	v_mfma_f32_16x16x32_bf16 v[34:37], v[170:173], v[186:189], v[34:37]
	v_mfma_f32_16x16x32_bf16 v[26:29], v[162:165], v[194:197], v[26:29]
	v_mfma_f32_16x16x32_bf16 v[18:21], v[170:173], v[194:197], v[18:21]
	v_mfma_f32_16x16x32_bf16 v[10:13], v[162:165], v[208:211], v[10:13]
	v_mfma_f32_16x16x32_bf16 v[2:5], v[170:173], v[208:211], v[2:5]
	v_mfma_f32_16x16x32_bf16 v[58:61], v[166:169], v[182:185], v[58:61]
	v_mfma_f32_16x16x32_bf16 v[50:53], v[174:177], v[182:185], v[50:53]
	v_mfma_f32_16x16x32_bf16 v[42:45], v[166:169], v[190:193], v[42:45]
	v_mfma_f32_16x16x32_bf16 v[34:37], v[174:177], v[190:193], v[34:37]
	v_mfma_f32_16x16x32_bf16 v[26:29], v[166:169], v[198:201], v[26:29]
	v_mfma_f32_16x16x32_bf16 v[18:21], v[174:177], v[198:201], v[18:21]
	v_mfma_f32_16x16x32_bf16 v[10:13], v[166:169], v[212:215], v[10:13]
	v_mfma_f32_16x16x32_bf16 v[2:5], v[174:177], v[212:215], v[2:5]
	s_barrier
	s_setprio 0
.Lpeel_mid_10:
	s_add_i32 s33, 0, 0x18000
	s_add_i32 s55, 0, 0x1c000
	ds_read_b128 v[146:149], v143 offset:32768
	ds_read_b128 v[150:153], v143 offset:33792
	ds_read_b128 v[154:157], v143 offset:34816
	ds_read_b128 v[158:161], v143 offset:35840
	ds_read_b128 v[162:165], v143 offset:49152
	ds_read_b128 v[166:169], v143 offset:50176
	ds_read_b128 v[170:173], v143 offset:51200
	ds_read_b128 v[174:177], v143 offset:52224
	s_add_u32 s0, s4, 0x80000
	s_addc_u32 s1, s5, 0
	s_mov_b32 m0, s37
	ds_read_b128 v[178:181], v145 offset:32768
	ds_read_b128 v[182:185], v145 offset:33792
	ds_read_b128 v[186:189], v145 offset:34816
	ds_read_b128 v[190:193], v145 offset:35840
	ds_read_b128 v[194:197], v145 offset:36864
	ds_read_b128 v[198:201], v145 offset:37888
	ds_read_b128 v[208:211], v145 offset:38912
	ds_read_b128 v[212:215], v145 offset:39936
	global_load_lds_dwordx4 v134, s[0:1]
	s_mov_b32 m0, s38
	s_nop 0
	global_load_lds_dwordx4 v132, s[0:1]
	s_setprio 1
	s_waitcnt vmcnt(8) lgkmcnt(0)
	s_barrier
	v_mfma_f32_16x16x32_bf16 v[126:129], v[146:149], v[178:181], v[126:129]
	v_mfma_f32_16x16x32_bf16 v[118:121], v[154:157], v[178:181], v[118:121]
	v_mfma_f32_16x16x32_bf16 v[110:113], v[146:149], v[186:189], v[110:113]
	v_mfma_f32_16x16x32_bf16 v[102:105], v[154:157], v[186:189], v[102:105]
	v_mfma_f32_16x16x32_bf16 v[94:97], v[146:149], v[194:197], v[94:97]
	v_mfma_f32_16x16x32_bf16 v[86:89], v[154:157], v[194:197], v[86:89]
	v_mfma_f32_16x16x32_bf16 v[78:81], v[146:149], v[208:211], v[78:81]
	v_mfma_f32_16x16x32_bf16 v[70:73], v[154:157], v[208:211], v[70:73]
	v_mfma_f32_16x16x32_bf16 v[126:129], v[150:153], v[182:185], v[126:129]
	v_mfma_f32_16x16x32_bf16 v[118:121], v[158:161], v[182:185], v[118:121]
	v_mfma_f32_16x16x32_bf16 v[110:113], v[150:153], v[190:193], v[110:113]
	v_mfma_f32_16x16x32_bf16 v[102:105], v[158:161], v[190:193], v[102:105]
	v_mfma_f32_16x16x32_bf16 v[94:97], v[150:153], v[198:201], v[94:97]
	v_mfma_f32_16x16x32_bf16 v[86:89], v[158:161], v[198:201], v[86:89]
	v_mfma_f32_16x16x32_bf16 v[78:81], v[150:153], v[212:215], v[78:81]
	v_mfma_f32_16x16x32_bf16 v[70:73], v[158:161], v[212:215], v[70:73]
	v_mfma_f32_16x16x32_bf16 v[122:125], v[162:165], v[178:181], v[122:125]
	v_mfma_f32_16x16x32_bf16 v[114:117], v[170:173], v[178:181], v[114:117]
	v_mfma_f32_16x16x32_bf16 v[106:109], v[162:165], v[186:189], v[106:109]
	v_mfma_f32_16x16x32_bf16 v[98:101], v[170:173], v[186:189], v[98:101]
	v_mfma_f32_16x16x32_bf16 v[90:93], v[162:165], v[194:197], v[90:93]
	v_mfma_f32_16x16x32_bf16 v[82:85], v[170:173], v[194:197], v[82:85]
	v_mfma_f32_16x16x32_bf16 v[74:77], v[162:165], v[208:211], v[74:77]
	v_mfma_f32_16x16x32_bf16 v[66:69], v[170:173], v[208:211], v[66:69]
	v_mfma_f32_16x16x32_bf16 v[122:125], v[166:169], v[182:185], v[122:125]
	v_mfma_f32_16x16x32_bf16 v[114:117], v[174:177], v[182:185], v[114:117]
	v_mfma_f32_16x16x32_bf16 v[106:109], v[166:169], v[190:193], v[106:109]
	v_mfma_f32_16x16x32_bf16 v[98:101], v[174:177], v[190:193], v[98:101]
	v_mfma_f32_16x16x32_bf16 v[90:93], v[166:169], v[198:201], v[90:93]
	v_mfma_f32_16x16x32_bf16 v[82:85], v[174:177], v[198:201], v[82:85]
	v_mfma_f32_16x16x32_bf16 v[74:77], v[166:169], v[212:215], v[74:77]
	v_mfma_f32_16x16x32_bf16 v[66:69], v[174:177], v[212:215], v[66:69]
	s_barrier
	s_setprio 0
	s_add_i32 s0, s33, s36
	s_add_u32 s100, s2, 0x80
	s_addc_u32 s101, s3, 0
	s_mov_b32 m0, s0
	ds_read_b128 v[178:181], v145 offset:49152
	ds_read_b128 v[182:185], v145 offset:50176
	ds_read_b128 v[186:189], v145 offset:51200
	ds_read_b128 v[190:193], v145 offset:52224
	ds_read_b128 v[194:197], v145 offset:53248
	ds_read_b128 v[198:201], v145 offset:54272
	ds_read_b128 v[208:211], v145 offset:55296
	ds_read_b128 v[212:215], v145 offset:56320
	global_load_lds_dwordx4 v202, s[100:101]
	s_add_i32 m0, s0, 0x2000
	s_add_u32 s100, s2, 0x80
	s_addc_u32 s101, s3, 0
	s_add_u32 s0, s2, 0x80080
	s_addc_u32 s1, s3, 0
	s_add_i32 s2, s55, s36
	global_load_lds_dwordx4 v130, s[100:101]
	s_mov_b32 m0, s2
	s_nop 0
	global_load_lds_dwordx4 v202, s[0:1]
	s_add_i32 m0, s2, 0x2000
	s_nop 0
	global_load_lds_dwordx4 v130, s[0:1]
	s_add_u32 s100, s4, 0x80
	s_addc_u32 s101, s5, 0
	s_mov_b32 m0, s39
	s_nop 0
	global_load_lds_dwordx4 v134, s[100:101]
	s_add_u32 s100, s4, 0x80
	s_addc_u32 s101, s5, 0
	s_mov_b32 m0, s40
	s_nop 0
	global_load_lds_dwordx4 v132, s[100:101]
	s_setprio 1
	s_waitcnt vmcnt(8) lgkmcnt(0)
	s_barrier
	v_mfma_f32_16x16x32_bf16 v[62:65], v[146:149], v[178:181], v[62:65]
	v_mfma_f32_16x16x32_bf16 v[54:57], v[154:157], v[178:181], v[54:57]
	v_mfma_f32_16x16x32_bf16 v[46:49], v[146:149], v[186:189], v[46:49]
	v_mfma_f32_16x16x32_bf16 v[38:41], v[154:157], v[186:189], v[38:41]
	v_mfma_f32_16x16x32_bf16 v[30:33], v[146:149], v[194:197], v[30:33]
	v_mfma_f32_16x16x32_bf16 v[22:25], v[154:157], v[194:197], v[22:25]
	v_mfma_f32_16x16x32_bf16 v[14:17], v[146:149], v[208:211], v[14:17]
	v_mfma_f32_16x16x32_bf16 v[6:9], v[154:157], v[208:211], v[6:9]
	v_mfma_f32_16x16x32_bf16 v[62:65], v[150:153], v[182:185], v[62:65]
	v_mfma_f32_16x16x32_bf16 v[54:57], v[158:161], v[182:185], v[54:57]
	v_mfma_f32_16x16x32_bf16 v[46:49], v[150:153], v[190:193], v[46:49]
	v_mfma_f32_16x16x32_bf16 v[38:41], v[158:161], v[190:193], v[38:41]
	v_mfma_f32_16x16x32_bf16 v[30:33], v[150:153], v[198:201], v[30:33]
	v_mfma_f32_16x16x32_bf16 v[22:25], v[158:161], v[198:201], v[22:25]
	v_mfma_f32_16x16x32_bf16 v[14:17], v[150:153], v[212:215], v[14:17]
	v_mfma_f32_16x16x32_bf16 v[6:9], v[158:161], v[212:215], v[6:9]
	v_mfma_f32_16x16x32_bf16 v[58:61], v[162:165], v[178:181], v[58:61]
	v_mfma_f32_16x16x32_bf16 v[50:53], v[170:173], v[178:181], v[50:53]
	v_mfma_f32_16x16x32_bf16 v[42:45], v[162:165], v[186:189], v[42:45]
	v_mfma_f32_16x16x32_bf16 v[34:37], v[170:173], v[186:189], v[34:37]
	v_mfma_f32_16x16x32_bf16 v[26:29], v[162:165], v[194:197], v[26:29]
	v_mfma_f32_16x16x32_bf16 v[18:21], v[170:173], v[194:197], v[18:21]
	v_mfma_f32_16x16x32_bf16 v[10:13], v[162:165], v[208:211], v[10:13]
	v_mfma_f32_16x16x32_bf16 v[2:5], v[170:173], v[208:211], v[2:5]
	v_mfma_f32_16x16x32_bf16 v[58:61], v[166:169], v[182:185], v[58:61]
	v_mfma_f32_16x16x32_bf16 v[50:53], v[174:177], v[182:185], v[50:53]
	v_mfma_f32_16x16x32_bf16 v[42:45], v[166:169], v[190:193], v[42:45]
	v_mfma_f32_16x16x32_bf16 v[34:37], v[174:177], v[190:193], v[34:37]
	v_mfma_f32_16x16x32_bf16 v[26:29], v[166:169], v[198:201], v[26:29]
	v_mfma_f32_16x16x32_bf16 v[18:21], v[174:177], v[198:201], v[18:21]
	v_mfma_f32_16x16x32_bf16 v[10:13], v[166:169], v[212:215], v[10:13]
	v_mfma_f32_16x16x32_bf16 v[2:5], v[174:177], v[212:215], v[2:5]
	s_barrier
	s_setprio 0
	s_add_i32 s61, s61, 2
	s_add_u32 s28, s28, 0x100
	s_addc_u32 s29, s29, 0
	s_add_u32 s59, s59, 0x100
	s_addc_u32 s60, s60, 0
	s_cmp_gt_u32 s61, 29
	s_cbranch_scc0 .LBB0_1594
	s_mov_b32 s101, 0x80000001
	s_and_b64 vcc, exec, s[14:15]
	s_cbranch_vccz .LBB0_1597
	s_barrier

.LBB0_1718:
	s_add_u32 s18, s4, 0x100
	s_addc_u32 s19, s5, 0
	s_add_i32 s0, 0, 0x10000
	s_cmpk_eq_i32 s59, 0x54
	s_cselect_b32 s23, s9, s19
	s_cselect_b32 s22, s8, s18
	s_cselect_b32 s21, s17, s58
	s_cselect_b32 s20, s16, s49
	s_add_i32 s33, 0, 0x14000
	ds_read_b128 v[78:81], v205
	ds_read_b128 v[82:85], v205 offset:1024
	ds_read_b128 v[94:97], v205 offset:2048
	ds_read_b128 v[98:101], v205 offset:3072
	ds_read_b128 v[106:109], v205 offset:16384
	ds_read_b128 v[110:113], v205 offset:17408
	ds_read_b128 v[126:129], v205 offset:18432
	ds_read_b128 v[134:137], v205 offset:19456
	s_add_i32 m0, s27, 0xc000
	ds_read_b128 v[146:149], v239
	ds_read_b128 v[158:161], v239 offset:1024
	ds_read_b128 v[166:169], v239 offset:2048
	ds_read_b128 v[174:177], v239 offset:3072
	ds_read_b128 v[178:181], v239 offset:4096
	ds_read_b128 v[182:185], v239 offset:5120
	ds_read_b128 v[186:189], v239 offset:6144
	ds_read_b128 v[190:193], v239 offset:7168
	global_load_lds_dwordx4 v214, s[4:5]
	s_add_i32 m0, s27, 0xe000
	s_nop 0
	global_load_lds_dwordx4 v216, s[4:5]
	s_setprio 1
	s_waitcnt vmcnt(8) lgkmcnt(0)
	s_barrier
	v_mfma_f32_16x16x32_bf16 v[170:173], v[78:81], v[146:149], v[170:173]
	v_mfma_f32_16x16x32_bf16 v[162:165], v[94:97], v[146:149], v[162:165]
	v_mfma_f32_16x16x32_bf16 v[142:145], v[78:81], v[166:169], v[142:145]
	v_mfma_f32_16x16x32_bf16 v[138:141], v[94:97], v[166:169], v[138:141]
	v_mfma_f32_16x16x32_bf16 v[118:121], v[78:81], v[178:181], v[118:121]
	v_mfma_f32_16x16x32_bf16 v[114:117], v[94:97], v[178:181], v[114:117]
	v_mfma_f32_16x16x32_bf16 v[86:89], v[78:81], v[186:189], v[86:89]
	v_mfma_f32_16x16x32_bf16 v[74:77], v[94:97], v[186:189], v[74:77]
	v_mfma_f32_16x16x32_bf16 v[170:173], v[82:85], v[158:161], v[170:173]
	v_mfma_f32_16x16x32_bf16 v[162:165], v[98:101], v[158:161], v[162:165]
	v_mfma_f32_16x16x32_bf16 v[142:145], v[82:85], v[174:177], v[142:145]
	v_mfma_f32_16x16x32_bf16 v[138:141], v[98:101], v[174:177], v[138:141]
	v_mfma_f32_16x16x32_bf16 v[118:121], v[82:85], v[182:185], v[118:121]
	v_mfma_f32_16x16x32_bf16 v[114:117], v[98:101], v[182:185], v[114:117]
	v_mfma_f32_16x16x32_bf16 v[86:89], v[82:85], v[190:193], v[86:89]
	v_mfma_f32_16x16x32_bf16 v[74:77], v[98:101], v[190:193], v[74:77]
	v_mfma_f32_16x16x32_bf16 v[154:157], v[106:109], v[146:149], v[154:157]
	v_mfma_f32_16x16x32_bf16 v[130:133], v[106:109], v[166:169], v[130:133]
	v_mfma_f32_16x16x32_bf16 v[122:125], v[126:129], v[166:169], v[122:125]
	v_mfma_f32_16x16x32_bf16 v[102:105], v[106:109], v[178:181], v[102:105]
	v_mfma_f32_16x16x32_bf16 v[90:93], v[126:129], v[178:181], v[90:93]
	v_mfma_f32_16x16x32_bf16 v[70:73], v[106:109], v[186:189], v[70:73]
	v_mfma_f32_16x16x32_bf16 v[66:69], v[126:129], v[186:189], v[66:69]
	v_mfma_f32_16x16x32_bf16 v[154:157], v[110:113], v[158:161], v[154:157]
	v_mfma_f32_16x16x32_bf16 v[146:149], v[126:129], v[146:149], v[150:153]
	v_mfma_f32_16x16x32_bf16 v[130:133], v[110:113], v[174:177], v[130:133]
	v_mfma_f32_16x16x32_bf16 v[122:125], v[134:137], v[174:177], v[122:125]
	v_mfma_f32_16x16x32_bf16 v[102:105], v[110:113], v[182:185], v[102:105]
	v_mfma_f32_16x16x32_bf16 v[90:93], v[134:137], v[182:185], v[90:93]
	v_mfma_f32_16x16x32_bf16 v[70:73], v[110:113], v[190:193], v[70:73]
	v_mfma_f32_16x16x32_bf16 v[66:69], v[134:137], v[190:193], v[66:69]
	v_mfma_f32_16x16x32_bf16 v[146:149], v[134:137], v[158:161], v[146:149]
	s_barrier
	s_setprio 0
	s_add_i32 s0, s0, s26
	s_mov_b32 m0, s0
	ds_read_b128 v[150:153], v239 offset:16384
	ds_read_b128 v[158:161], v239 offset:17408
	ds_read_b128 v[166:169], v239 offset:18432
	ds_read_b128 v[174:177], v239 offset:19456
	ds_read_b128 v[178:181], v239 offset:20480
	ds_read_b128 v[182:185], v239 offset:21504
	ds_read_b128 v[186:189], v239 offset:22528
	ds_read_b128 v[190:193], v239 offset:23552
	global_load_lds_dwordx4 v202, s[20:21]
	s_add_i32 m0, s0, 0x2000
	s_add_u32 s0, s20, 0x160000
	s_addc_u32 s1, s21, 0
	s_add_i32 s4, s33, s26
	global_load_lds_dwordx4 v208, s[20:21]
	s_mov_b32 m0, s4
	s_nop 0
	global_load_lds_dwordx4 v202, s[0:1]
	s_add_i32 m0, s4, 0x2000
	s_nop 0
	global_load_lds_dwordx4 v208, s[0:1]
	s_mov_b32 m0, s27
	s_nop 0
	global_load_lds_dwordx4 v212, s[22:23]
	s_mov_b32 m0, s28
	s_nop 0
	global_load_lds_dwordx4 v210, s[22:23]
	s_setprio 1
	s_waitcnt vmcnt(8) lgkmcnt(0)
	s_barrier
	v_mfma_f32_16x16x32_bf16 v[62:65], v[78:81], v[150:153], v[62:65]
	v_mfma_f32_16x16x32_bf16 v[58:61], v[94:97], v[150:153], v[58:61]
	v_mfma_f32_16x16x32_bf16 v[46:49], v[78:81], v[166:169], v[46:49]
	v_mfma_f32_16x16x32_bf16 v[42:45], v[94:97], v[166:169], v[42:45]
	v_mfma_f32_16x16x32_bf16 v[30:33], v[78:81], v[178:181], v[30:33]
	v_mfma_f32_16x16x32_bf16 v[26:29], v[94:97], v[178:181], v[26:29]
	v_mfma_f32_16x16x32_bf16 v[14:17], v[78:81], v[186:189], v[14:17]
	v_mfma_f32_16x16x32_bf16 v[10:13], v[94:97], v[186:189], v[10:13]
	v_mfma_f32_16x16x32_bf16 v[62:65], v[82:85], v[158:161], v[62:65]
	v_mfma_f32_16x16x32_bf16 v[58:61], v[98:101], v[158:161], v[58:61]
	v_mfma_f32_16x16x32_bf16 v[46:49], v[82:85], v[174:177], v[46:49]
	v_mfma_f32_16x16x32_bf16 v[42:45], v[98:101], v[174:177], v[42:45]
	v_mfma_f32_16x16x32_bf16 v[30:33], v[82:85], v[182:185], v[30:33]
	v_mfma_f32_16x16x32_bf16 v[26:29], v[98:101], v[182:185], v[26:29]
	v_mfma_f32_16x16x32_bf16 v[14:17], v[82:85], v[190:193], v[14:17]
	v_mfma_f32_16x16x32_bf16 v[10:13], v[98:101], v[190:193], v[10:13]
	v_mfma_f32_16x16x32_bf16 v[54:57], v[106:109], v[150:153], v[54:57]
	v_mfma_f32_16x16x32_bf16 v[50:53], v[126:129], v[150:153], v[50:53]
	v_mfma_f32_16x16x32_bf16 v[38:41], v[106:109], v[166:169], v[38:41]
	v_mfma_f32_16x16x32_bf16 v[34:37], v[126:129], v[166:169], v[34:37]
	v_mfma_f32_16x16x32_bf16 v[22:25], v[106:109], v[178:181], v[22:25]
	v_mfma_f32_16x16x32_bf16 v[18:21], v[126:129], v[178:181], v[18:21]
	v_mfma_f32_16x16x32_bf16 v[6:9], v[106:109], v[186:189], v[6:9]
	v_mfma_f32_16x16x32_bf16 v[2:5], v[126:129], v[186:189], v[2:5]
	v_mfma_f32_16x16x32_bf16 v[54:57], v[110:113], v[158:161], v[54:57]
	v_mfma_f32_16x16x32_bf16 v[50:53], v[134:137], v[158:161], v[50:53]
	v_mfma_f32_16x16x32_bf16 v[38:41], v[110:113], v[174:177], v[38:41]
	v_mfma_f32_16x16x32_bf16 v[34:37], v[134:137], v[174:177], v[34:37]
	v_mfma_f32_16x16x32_bf16 v[22:25], v[110:113], v[182:185], v[22:25]
	v_mfma_f32_16x16x32_bf16 v[18:21], v[134:137], v[182:185], v[18:21]
	v_mfma_f32_16x16x32_bf16 v[6:9], v[110:113], v[190:193], v[6:9]
	v_mfma_f32_16x16x32_bf16 v[2:5], v[134:137], v[190:193], v[2:5]
	s_barrier
	s_setprio 0
	s_add_i32 s4, 0, 0x18000
	s_add_i32 s5, 0, 0x1c000
	ds_read_b128 v[78:81], v205 offset:32768
	ds_read_b128 v[82:85], v205 offset:33792
	ds_read_b128 v[94:97], v205 offset:34816
	ds_read_b128 v[98:101], v205 offset:35840
	ds_read_b128 v[106:109], v205 offset:49152
	ds_read_b128 v[110:113], v205 offset:50176
	ds_read_b128 v[126:129], v205 offset:51200
	ds_read_b128 v[134:137], v205 offset:52224
	s_add_u32 s0, s22, 0x160000
	s_addc_u32 s1, s23, 0
	s_mov_b32 m0, s29
	ds_read_b128 v[150:153], v239 offset:32768
	ds_read_b128 v[158:161], v239 offset:33792
	ds_read_b128 v[166:169], v239 offset:34816
	ds_read_b128 v[174:177], v239 offset:35840
	ds_read_b128 v[178:181], v239 offset:36864
	ds_read_b128 v[182:185], v239 offset:37888
	ds_read_b128 v[186:189], v239 offset:38912
	ds_read_b128 v[190:193], v239 offset:39936
	global_load_lds_dwordx4 v212, s[0:1]
	s_mov_b32 m0, s30
	s_nop 0
	global_load_lds_dwordx4 v210, s[0:1]
	s_setprio 1
	s_waitcnt vmcnt(8) lgkmcnt(0)
	s_barrier
	v_mfma_f32_16x16x32_bf16 v[170:173], v[78:81], v[150:153], v[170:173]
	v_mfma_f32_16x16x32_bf16 v[162:165], v[94:97], v[150:153], v[162:165]
	v_mfma_f32_16x16x32_bf16 v[142:145], v[78:81], v[166:169], v[142:145]
	v_mfma_f32_16x16x32_bf16 v[138:141], v[94:97], v[166:169], v[138:141]
	v_mfma_f32_16x16x32_bf16 v[118:121], v[78:81], v[178:181], v[118:121]
	v_mfma_f32_16x16x32_bf16 v[114:117], v[94:97], v[178:181], v[114:117]
	v_mfma_f32_16x16x32_bf16 v[86:89], v[78:81], v[186:189], v[86:89]
	v_mfma_f32_16x16x32_bf16 v[74:77], v[94:97], v[186:189], v[74:77]
	v_mfma_f32_16x16x32_bf16 v[170:173], v[82:85], v[158:161], v[170:173]
	v_mfma_f32_16x16x32_bf16 v[162:165], v[98:101], v[158:161], v[162:165]
	v_mfma_f32_16x16x32_bf16 v[142:145], v[82:85], v[174:177], v[142:145]
	v_mfma_f32_16x16x32_bf16 v[138:141], v[98:101], v[174:177], v[138:141]
	v_mfma_f32_16x16x32_bf16 v[118:121], v[82:85], v[182:185], v[118:121]
	v_mfma_f32_16x16x32_bf16 v[114:117], v[98:101], v[182:185], v[114:117]
	v_mfma_f32_16x16x32_bf16 v[86:89], v[82:85], v[190:193], v[86:89]
	v_mfma_f32_16x16x32_bf16 v[74:77], v[98:101], v[190:193], v[74:77]
	v_mfma_f32_16x16x32_bf16 v[154:157], v[106:109], v[150:153], v[154:157]
	v_mfma_f32_16x16x32_bf16 v[146:149], v[126:129], v[150:153], v[146:149]
	v_mfma_f32_16x16x32_bf16 v[130:133], v[106:109], v[166:169], v[130:133]
	v_mfma_f32_16x16x32_bf16 v[122:125], v[126:129], v[166:169], v[122:125]
	v_mfma_f32_16x16x32_bf16 v[102:105], v[106:109], v[178:181], v[102:105]
	v_mfma_f32_16x16x32_bf16 v[90:93], v[126:129], v[178:181], v[90:93]
	v_mfma_f32_16x16x32_bf16 v[70:73], v[106:109], v[186:189], v[70:73]
	v_mfma_f32_16x16x32_bf16 v[66:69], v[126:129], v[186:189], v[66:69]
	v_mfma_f32_16x16x32_bf16 v[154:157], v[110:113], v[158:161], v[154:157]
	v_mfma_f32_16x16x32_bf16 v[150:153], v[134:137], v[158:161], v[146:149]
	v_mfma_f32_16x16x32_bf16 v[130:133], v[110:113], v[174:177], v[130:133]
	v_mfma_f32_16x16x32_bf16 v[122:125], v[134:137], v[174:177], v[122:125]
	v_mfma_f32_16x16x32_bf16 v[102:105], v[110:113], v[182:185], v[102:105]
	v_mfma_f32_16x16x32_bf16 v[90:93], v[134:137], v[182:185], v[90:93]
	v_mfma_f32_16x16x32_bf16 v[70:73], v[110:113], v[190:193], v[70:73]
	v_mfma_f32_16x16x32_bf16 v[66:69], v[134:137], v[190:193], v[66:69]
	s_barrier
	s_setprio 0
	s_add_i32 s0, s4, s26
	s_add_u32 s100, s20, 0x80
	s_addc_u32 s101, s21, 0
	s_mov_b32 m0, s0
	ds_read_b128 v[146:149], v239 offset:49152
	ds_read_b128 v[158:161], v239 offset:50176
	ds_read_b128 v[166:169], v239 offset:51200
	ds_read_b128 v[174:177], v239 offset:52224
	ds_read_b128 v[178:181], v239 offset:53248
	ds_read_b128 v[182:185], v239 offset:54272
	ds_read_b128 v[186:189], v239 offset:55296
	ds_read_b128 v[190:193], v239 offset:56320
	global_load_lds_dwordx4 v202, s[100:101]
	s_add_i32 m0, s0, 0x2000
	s_add_u32 s100, s20, 0x80
	s_addc_u32 s101, s21, 0
	s_add_u32 s0, s20, 0x160080
	s_addc_u32 s1, s21, 0
	s_add_i32 s4, s5, s26
	global_load_lds_dwordx4 v208, s[100:101]
	s_mov_b32 m0, s4
	s_nop 0
	global_load_lds_dwordx4 v202, s[0:1]
	s_add_i32 m0, s4, 0x2000
	s_nop 0
	global_load_lds_dwordx4 v208, s[0:1]
	s_add_u32 s100, s22, 0x80
	s_addc_u32 s101, s23, 0
	s_mov_b32 m0, s35
	s_nop 0
	global_load_lds_dwordx4 v212, s[100:101]
	s_add_u32 s100, s22, 0x80
	s_addc_u32 s101, s23, 0
	s_mov_b32 m0, s36
	s_nop 0
	global_load_lds_dwordx4 v210, s[100:101]
	s_setprio 1
	s_waitcnt vmcnt(8) lgkmcnt(0)
	s_barrier
	v_mfma_f32_16x16x32_bf16 v[62:65], v[78:81], v[146:149], v[62:65]
	v_mfma_f32_16x16x32_bf16 v[58:61], v[94:97], v[146:149], v[58:61]
	v_mfma_f32_16x16x32_bf16 v[46:49], v[78:81], v[166:169], v[46:49]
	v_mfma_f32_16x16x32_bf16 v[42:45], v[94:97], v[166:169], v[42:45]
	v_mfma_f32_16x16x32_bf16 v[30:33], v[78:81], v[178:181], v[30:33]
	v_mfma_f32_16x16x32_bf16 v[26:29], v[94:97], v[178:181], v[26:29]
	v_mfma_f32_16x16x32_bf16 v[14:17], v[78:81], v[186:189], v[14:17]
	v_mfma_f32_16x16x32_bf16 v[10:13], v[94:97], v[186:189], v[10:13]
	v_mfma_f32_16x16x32_bf16 v[62:65], v[82:85], v[158:161], v[62:65]
	v_mfma_f32_16x16x32_bf16 v[58:61], v[98:101], v[158:161], v[58:61]
	v_mfma_f32_16x16x32_bf16 v[46:49], v[82:85], v[174:177], v[46:49]
	v_mfma_f32_16x16x32_bf16 v[42:45], v[98:101], v[174:177], v[42:45]
	v_mfma_f32_16x16x32_bf16 v[30:33], v[82:85], v[182:185], v[30:33]
	v_mfma_f32_16x16x32_bf16 v[26:29], v[98:101], v[182:185], v[26:29]
	v_mfma_f32_16x16x32_bf16 v[14:17], v[82:85], v[190:193], v[14:17]
	v_mfma_f32_16x16x32_bf16 v[10:13], v[98:101], v[190:193], v[10:13]
	v_mfma_f32_16x16x32_bf16 v[54:57], v[106:109], v[146:149], v[54:57]
	v_mfma_f32_16x16x32_bf16 v[50:53], v[126:129], v[146:149], v[50:53]
	v_mfma_f32_16x16x32_bf16 v[38:41], v[106:109], v[166:169], v[38:41]
	v_mfma_f32_16x16x32_bf16 v[34:37], v[126:129], v[166:169], v[34:37]
	v_mfma_f32_16x16x32_bf16 v[22:25], v[106:109], v[178:181], v[22:25]
	v_mfma_f32_16x16x32_bf16 v[18:21], v[126:129], v[178:181], v[18:21]
	v_mfma_f32_16x16x32_bf16 v[6:9], v[106:109], v[186:189], v[6:9]
	v_mfma_f32_16x16x32_bf16 v[2:5], v[126:129], v[186:189], v[2:5]
	v_mfma_f32_16x16x32_bf16 v[54:57], v[110:113], v[158:161], v[54:57]
	v_mfma_f32_16x16x32_bf16 v[50:53], v[134:137], v[158:161], v[50:53]
	v_mfma_f32_16x16x32_bf16 v[38:41], v[110:113], v[174:177], v[38:41]
	v_mfma_f32_16x16x32_bf16 v[34:37], v[134:137], v[174:177], v[34:37]
	v_mfma_f32_16x16x32_bf16 v[22:25], v[110:113], v[182:185], v[22:25]
	v_mfma_f32_16x16x32_bf16 v[18:21], v[134:137], v[182:185], v[18:21]
	v_mfma_f32_16x16x32_bf16 v[6:9], v[110:113], v[190:193], v[6:9]
	v_mfma_f32_16x16x32_bf16 v[2:5], v[134:137], v[190:193], v[2:5]
	s_barrier
	s_setprio 0
	s_add_i32 s59, s59, 2
	s_add_u32 s49, s49, 0x100
	s_addc_u32 s58, s58, 0
	s_cmpk_gt_u32 s59, 0x55
	s_mov_b64 s[4:5], s[18:19]
	s_cbranch_scc0 .LBB0_1718
	s_and_b64 vcc, exec, s[14:15]
	s_cbranch_vccz .LBB0_1721
	s_barrier

.LBB0_1739:
	s_add_u32 s16, s14, 0x100
	s_addc_u32 s17, s15, 0
	s_add_i32 s0, 0, 0x10000
	s_cmp_eq_u32 s49, 4
	s_cselect_b32 s21, s9, s17
	s_cselect_b32 s20, s8, s16
	s_cselect_b32 s19, s11, s41
	s_cselect_b32 s18, s10, s40
	s_add_i32 s33, 0, 0x14000
	ds_read_b128 v[140:143], v136
	ds_read_b128 v[144:147], v136 offset:1024
	ds_read_b128 v[148:151], v136 offset:2048
	ds_read_b128 v[152:155], v136 offset:3072
	ds_read_b128 v[156:159], v136 offset:16384
	ds_read_b128 v[160:163], v136 offset:17408
	ds_read_b128 v[164:167], v136 offset:18432
	ds_read_b128 v[168:171], v136 offset:19456
	s_add_i32 m0, s23, 0xc000
	ds_read_b128 v[172:175], v139
	ds_read_b128 v[176:179], v139 offset:1024
	ds_read_b128 v[180:183], v139 offset:2048
	ds_read_b128 v[184:187], v139 offset:3072
	ds_read_b128 v[188:191], v139 offset:4096
	ds_read_b128 v[192:195], v139 offset:5120
	ds_read_b128 v[196:199], v139 offset:6144
	ds_read_b128 v[208:211], v139 offset:7168
	global_load_lds_dwordx4 v132, s[14:15]
	s_add_i32 m0, s23, 0xe000
	s_nop 0
	global_load_lds_dwordx4 v134, s[14:15]
	s_setprio 1
	s_waitcnt vmcnt(8) lgkmcnt(0)
	s_barrier
	v_mfma_f32_16x16x32_bf16 v[126:129], v[140:143], v[172:175], v[126:129]
	v_mfma_f32_16x16x32_bf16 v[122:125], v[148:151], v[172:175], v[122:125]
	v_mfma_f32_16x16x32_bf16 v[118:121], v[140:143], v[180:183], v[118:121]
	v_mfma_f32_16x16x32_bf16 v[114:117], v[148:151], v[180:183], v[114:117]
	v_mfma_f32_16x16x32_bf16 v[106:109], v[140:143], v[188:191], v[106:109]
	v_mfma_f32_16x16x32_bf16 v[98:101], v[148:151], v[188:191], v[98:101]
	v_mfma_f32_16x16x32_bf16 v[90:93], v[140:143], v[196:199], v[90:93]
	v_mfma_f32_16x16x32_bf16 v[82:85], v[148:151], v[196:199], v[82:85]
	v_mfma_f32_16x16x32_bf16 v[126:129], v[144:147], v[176:179], v[126:129]
	v_mfma_f32_16x16x32_bf16 v[122:125], v[152:155], v[176:179], v[122:125]
	v_mfma_f32_16x16x32_bf16 v[118:121], v[144:147], v[184:187], v[118:121]
	v_mfma_f32_16x16x32_bf16 v[114:117], v[152:155], v[184:187], v[114:117]
	v_mfma_f32_16x16x32_bf16 v[106:109], v[144:147], v[192:195], v[106:109]
	v_mfma_f32_16x16x32_bf16 v[98:101], v[152:155], v[192:195], v[98:101]
	v_mfma_f32_16x16x32_bf16 v[90:93], v[144:147], v[208:211], v[90:93]
	v_mfma_f32_16x16x32_bf16 v[82:85], v[152:155], v[208:211], v[82:85]
	v_mfma_f32_16x16x32_bf16 v[110:113], v[156:159], v[172:175], v[110:113]
	v_mfma_f32_16x16x32_bf16 v[102:105], v[164:167], v[172:175], v[102:105]
	v_mfma_f32_16x16x32_bf16 v[94:97], v[156:159], v[180:183], v[94:97]
	v_mfma_f32_16x16x32_bf16 v[86:89], v[164:167], v[180:183], v[86:89]
	v_mfma_f32_16x16x32_bf16 v[78:81], v[156:159], v[188:191], v[78:81]
	v_mfma_f32_16x16x32_bf16 v[74:77], v[164:167], v[188:191], v[74:77]
	v_mfma_f32_16x16x32_bf16 v[70:73], v[156:159], v[196:199], v[70:73]
	v_mfma_f32_16x16x32_bf16 v[66:69], v[164:167], v[196:199], v[66:69]
	v_mfma_f32_16x16x32_bf16 v[110:113], v[160:163], v[176:179], v[110:113]
	v_mfma_f32_16x16x32_bf16 v[102:105], v[168:171], v[176:179], v[102:105]
	v_mfma_f32_16x16x32_bf16 v[94:97], v[160:163], v[184:187], v[94:97]
	v_mfma_f32_16x16x32_bf16 v[86:89], v[168:171], v[184:187], v[86:89]
	v_mfma_f32_16x16x32_bf16 v[78:81], v[160:163], v[192:195], v[78:81]
	v_mfma_f32_16x16x32_bf16 v[74:77], v[168:171], v[192:195], v[74:77]
	v_mfma_f32_16x16x32_bf16 v[70:73], v[160:163], v[208:211], v[70:73]
	v_mfma_f32_16x16x32_bf16 v[66:69], v[168:171], v[208:211], v[66:69]
	s_barrier
	s_setprio 0
	s_add_i32 s0, s0, s22
	s_mov_b32 m0, s0
	ds_read_b128 v[172:175], v139 offset:16384
	ds_read_b128 v[176:179], v139 offset:17408
	ds_read_b128 v[180:183], v139 offset:18432
	ds_read_b128 v[184:187], v139 offset:19456
	ds_read_b128 v[188:191], v139 offset:20480
	ds_read_b128 v[192:195], v139 offset:21504
	ds_read_b128 v[196:199], v139 offset:22528
	ds_read_b128 v[208:211], v139 offset:23552
	global_load_lds_dwordx4 v202, s[18:19]
	s_add_i32 m0, s0, 0x2000
	s_add_u32 s0, s18, 0x160000
	s_addc_u32 s1, s19, 0
	s_add_i32 s14, s33, s22
	global_load_lds_dwordx4 v130, s[18:19]
	s_mov_b32 m0, s14
	s_nop 0
	global_load_lds_dwordx4 v202, s[0:1]
	s_add_i32 m0, s14, 0x2000
	s_nop 0
	global_load_lds_dwordx4 v130, s[0:1]
	s_mov_b32 m0, s23
	s_nop 0
	global_load_lds_dwordx4 v202, s[20:21]
	s_mov_b32 m0, s26
	s_nop 0
	global_load_lds_dwordx4 v130, s[20:21]
	s_setprio 1
	s_waitcnt vmcnt(8) lgkmcnt(0)
	s_barrier
	v_mfma_f32_16x16x32_bf16 v[62:65], v[140:143], v[172:175], v[62:65]
	v_mfma_f32_16x16x32_bf16 v[58:61], v[148:151], v[172:175], v[58:61]
	v_mfma_f32_16x16x32_bf16 v[54:57], v[140:143], v[180:183], v[54:57]
	v_mfma_f32_16x16x32_bf16 v[50:53], v[148:151], v[180:183], v[50:53]
	v_mfma_f32_16x16x32_bf16 v[38:41], v[140:143], v[188:191], v[38:41]
	v_mfma_f32_16x16x32_bf16 v[34:37], v[148:151], v[188:191], v[34:37]
	v_mfma_f32_16x16x32_bf16 v[22:25], v[140:143], v[196:199], v[22:25]
	v_mfma_f32_16x16x32_bf16 v[18:21], v[148:151], v[196:199], v[18:21]
	v_mfma_f32_16x16x32_bf16 v[62:65], v[144:147], v[176:179], v[62:65]
	v_mfma_f32_16x16x32_bf16 v[58:61], v[152:155], v[176:179], v[58:61]
	v_mfma_f32_16x16x32_bf16 v[54:57], v[144:147], v[184:187], v[54:57]
	v_mfma_f32_16x16x32_bf16 v[50:53], v[152:155], v[184:187], v[50:53]
	v_mfma_f32_16x16x32_bf16 v[38:41], v[144:147], v[192:195], v[38:41]
	v_mfma_f32_16x16x32_bf16 v[34:37], v[152:155], v[192:195], v[34:37]
	v_mfma_f32_16x16x32_bf16 v[22:25], v[144:147], v[208:211], v[22:25]
	v_mfma_f32_16x16x32_bf16 v[18:21], v[152:155], v[208:211], v[18:21]
	v_mfma_f32_16x16x32_bf16 v[46:49], v[156:159], v[172:175], v[46:49]
	v_mfma_f32_16x16x32_bf16 v[42:45], v[164:167], v[172:175], v[42:45]
	v_mfma_f32_16x16x32_bf16 v[30:33], v[156:159], v[180:183], v[30:33]
	v_mfma_f32_16x16x32_bf16 v[26:29], v[164:167], v[180:183], v[26:29]
	v_mfma_f32_16x16x32_bf16 v[14:17], v[156:159], v[188:191], v[14:17]
	v_mfma_f32_16x16x32_bf16 v[10:13], v[164:167], v[188:191], v[10:13]
	v_mfma_f32_16x16x32_bf16 v[6:9], v[156:159], v[196:199], v[6:9]
	v_mfma_f32_16x16x32_bf16 v[2:5], v[164:167], v[196:199], v[2:5]
	v_mfma_f32_16x16x32_bf16 v[46:49], v[160:163], v[176:179], v[46:49]
	v_mfma_f32_16x16x32_bf16 v[42:45], v[168:171], v[176:179], v[42:45]
	v_mfma_f32_16x16x32_bf16 v[30:33], v[160:163], v[184:187], v[30:33]
	v_mfma_f32_16x16x32_bf16 v[26:29], v[168:171], v[184:187], v[26:29]
	v_mfma_f32_16x16x32_bf16 v[14:17], v[160:163], v[192:195], v[14:17]
	v_mfma_f32_16x16x32_bf16 v[10:13], v[168:171], v[192:195], v[10:13]
	v_mfma_f32_16x16x32_bf16 v[6:9], v[160:163], v[208:211], v[6:9]
	v_mfma_f32_16x16x32_bf16 v[2:5], v[168:171], v[208:211], v[2:5]
	s_barrier
	s_setprio 0
	s_add_i32 s14, 0, 0x18000
	s_add_i32 s15, 0, 0x1c000
	ds_read_b128 v[140:143], v136 offset:32768
	ds_read_b128 v[144:147], v136 offset:33792
	ds_read_b128 v[148:151], v136 offset:34816
	ds_read_b128 v[152:155], v136 offset:35840
	ds_read_b128 v[156:159], v136 offset:49152
	ds_read_b128 v[160:163], v136 offset:50176
	ds_read_b128 v[164:167], v136 offset:51200
	ds_read_b128 v[168:171], v136 offset:52224
	s_add_u32 s0, s20, 0x160000
	s_addc_u32 s1, s21, 0
	s_mov_b32 m0, s27
	ds_read_b128 v[172:175], v139 offset:32768
	ds_read_b128 v[176:179], v139 offset:33792
	ds_read_b128 v[180:183], v139 offset:34816
	ds_read_b128 v[184:187], v139 offset:35840
	ds_read_b128 v[188:191], v139 offset:36864
	ds_read_b128 v[192:195], v139 offset:37888
	ds_read_b128 v[196:199], v139 offset:38912
	ds_read_b128 v[208:211], v139 offset:39936
	global_load_lds_dwordx4 v202, s[0:1]
	s_mov_b32 m0, s28
	s_nop 0
	global_load_lds_dwordx4 v130, s[0:1]
	s_setprio 1
	s_waitcnt vmcnt(8) lgkmcnt(0)
	s_barrier
	v_mfma_f32_16x16x32_bf16 v[126:129], v[140:143], v[172:175], v[126:129]
	v_mfma_f32_16x16x32_bf16 v[122:125], v[148:151], v[172:175], v[122:125]
	v_mfma_f32_16x16x32_bf16 v[118:121], v[140:143], v[180:183], v[118:121]
	v_mfma_f32_16x16x32_bf16 v[114:117], v[148:151], v[180:183], v[114:117]
	v_mfma_f32_16x16x32_bf16 v[106:109], v[140:143], v[188:191], v[106:109]
	v_mfma_f32_16x16x32_bf16 v[98:101], v[148:151], v[188:191], v[98:101]
	v_mfma_f32_16x16x32_bf16 v[90:93], v[140:143], v[196:199], v[90:93]
	v_mfma_f32_16x16x32_bf16 v[82:85], v[148:151], v[196:199], v[82:85]
	v_mfma_f32_16x16x32_bf16 v[126:129], v[144:147], v[176:179], v[126:129]
	v_mfma_f32_16x16x32_bf16 v[122:125], v[152:155], v[176:179], v[122:125]
	v_mfma_f32_16x16x32_bf16 v[118:121], v[144:147], v[184:187], v[118:121]
	v_mfma_f32_16x16x32_bf16 v[114:117], v[152:155], v[184:187], v[114:117]
	v_mfma_f32_16x16x32_bf16 v[106:109], v[144:147], v[192:195], v[106:109]
	v_mfma_f32_16x16x32_bf16 v[98:101], v[152:155], v[192:195], v[98:101]
	v_mfma_f32_16x16x32_bf16 v[90:93], v[144:147], v[208:211], v[90:93]
	v_mfma_f32_16x16x32_bf16 v[82:85], v[152:155], v[208:211], v[82:85]
	v_mfma_f32_16x16x32_bf16 v[110:113], v[156:159], v[172:175], v[110:113]
	v_mfma_f32_16x16x32_bf16 v[102:105], v[164:167], v[172:175], v[102:105]
	v_mfma_f32_16x16x32_bf16 v[94:97], v[156:159], v[180:183], v[94:97]
	v_mfma_f32_16x16x32_bf16 v[86:89], v[164:167], v[180:183], v[86:89]
	v_mfma_f32_16x16x32_bf16 v[78:81], v[156:159], v[188:191], v[78:81]
	v_mfma_f32_16x16x32_bf16 v[74:77], v[164:167], v[188:191], v[74:77]
	v_mfma_f32_16x16x32_bf16 v[70:73], v[156:159], v[196:199], v[70:73]
	v_mfma_f32_16x16x32_bf16 v[66:69], v[164:167], v[196:199], v[66:69]
	v_mfma_f32_16x16x32_bf16 v[110:113], v[160:163], v[176:179], v[110:113]
	v_mfma_f32_16x16x32_bf16 v[102:105], v[168:171], v[176:179], v[102:105]
	v_mfma_f32_16x16x32_bf16 v[94:97], v[160:163], v[184:187], v[94:97]
	v_mfma_f32_16x16x32_bf16 v[86:89], v[168:171], v[184:187], v[86:89]
	v_mfma_f32_16x16x32_bf16 v[78:81], v[160:163], v[192:195], v[78:81]
	v_mfma_f32_16x16x32_bf16 v[74:77], v[168:171], v[192:195], v[74:77]
	v_mfma_f32_16x16x32_bf16 v[70:73], v[160:163], v[208:211], v[70:73]
	v_mfma_f32_16x16x32_bf16 v[66:69], v[168:171], v[208:211], v[66:69]
	s_barrier
	s_setprio 0
	s_add_i32 s0, s14, s22
	s_add_u32 s100, s18, 0x80
	s_addc_u32 s101, s19, 0
	s_mov_b32 m0, s0
	ds_read_b128 v[172:175], v139 offset:49152
	ds_read_b128 v[176:179], v139 offset:50176
	ds_read_b128 v[180:183], v139 offset:51200
	ds_read_b128 v[184:187], v139 offset:52224
	ds_read_b128 v[188:191], v139 offset:53248
	ds_read_b128 v[192:195], v139 offset:54272
	ds_read_b128 v[196:199], v139 offset:55296
	ds_read_b128 v[208:211], v139 offset:56320
	global_load_lds_dwordx4 v202, s[100:101]
	s_add_i32 m0, s0, 0x2000
	s_add_u32 s100, s18, 0x80
	s_addc_u32 s101, s19, 0
	s_add_u32 s0, s18, 0x160080
	s_addc_u32 s1, s19, 0
	s_add_i32 s14, s15, s22
	global_load_lds_dwordx4 v130, s[100:101]
	s_mov_b32 m0, s14
	s_nop 0
	global_load_lds_dwordx4 v202, s[0:1]
	s_add_i32 m0, s14, 0x2000
	s_nop 0
	global_load_lds_dwordx4 v130, s[0:1]
	s_add_u32 s100, s20, 0x80
	s_addc_u32 s101, s21, 0
	s_mov_b32 m0, s29
	s_nop 0
	global_load_lds_dwordx4 v202, s[100:101]
	s_add_u32 s100, s20, 0x80
	s_addc_u32 s101, s21, 0
	s_mov_b32 m0, s30
	s_nop 0
	global_load_lds_dwordx4 v130, s[100:101]
	s_setprio 1
	s_waitcnt vmcnt(8) lgkmcnt(0)
	s_barrier
	v_mfma_f32_16x16x32_bf16 v[62:65], v[140:143], v[172:175], v[62:65]
	v_mfma_f32_16x16x32_bf16 v[58:61], v[148:151], v[172:175], v[58:61]
	v_mfma_f32_16x16x32_bf16 v[54:57], v[140:143], v[180:183], v[54:57]
	v_mfma_f32_16x16x32_bf16 v[50:53], v[148:151], v[180:183], v[50:53]
	v_mfma_f32_16x16x32_bf16 v[38:41], v[140:143], v[188:191], v[38:41]
	v_mfma_f32_16x16x32_bf16 v[34:37], v[148:151], v[188:191], v[34:37]
	v_mfma_f32_16x16x32_bf16 v[22:25], v[140:143], v[196:199], v[22:25]
	v_mfma_f32_16x16x32_bf16 v[18:21], v[148:151], v[196:199], v[18:21]
	v_mfma_f32_16x16x32_bf16 v[62:65], v[144:147], v[176:179], v[62:65]
	v_mfma_f32_16x16x32_bf16 v[58:61], v[152:155], v[176:179], v[58:61]
	v_mfma_f32_16x16x32_bf16 v[54:57], v[144:147], v[184:187], v[54:57]
	v_mfma_f32_16x16x32_bf16 v[50:53], v[152:155], v[184:187], v[50:53]
	v_mfma_f32_16x16x32_bf16 v[38:41], v[144:147], v[192:195], v[38:41]
	v_mfma_f32_16x16x32_bf16 v[34:37], v[152:155], v[192:195], v[34:37]
	v_mfma_f32_16x16x32_bf16 v[22:25], v[144:147], v[208:211], v[22:25]
	v_mfma_f32_16x16x32_bf16 v[18:21], v[152:155], v[208:211], v[18:21]
	v_mfma_f32_16x16x32_bf16 v[46:49], v[156:159], v[172:175], v[46:49]
	v_mfma_f32_16x16x32_bf16 v[42:45], v[164:167], v[172:175], v[42:45]
	v_mfma_f32_16x16x32_bf16 v[30:33], v[156:159], v[180:183], v[30:33]
	v_mfma_f32_16x16x32_bf16 v[26:29], v[164:167], v[180:183], v[26:29]
	v_mfma_f32_16x16x32_bf16 v[14:17], v[156:159], v[188:191], v[14:17]
	v_mfma_f32_16x16x32_bf16 v[10:13], v[164:167], v[188:191], v[10:13]
	v_mfma_f32_16x16x32_bf16 v[6:9], v[156:159], v[196:199], v[6:9]
	v_mfma_f32_16x16x32_bf16 v[2:5], v[164:167], v[196:199], v[2:5]
	v_mfma_f32_16x16x32_bf16 v[46:49], v[160:163], v[176:179], v[46:49]
	v_mfma_f32_16x16x32_bf16 v[42:45], v[168:171], v[176:179], v[42:45]
	v_mfma_f32_16x16x32_bf16 v[30:33], v[160:163], v[184:187], v[30:33]
	v_mfma_f32_16x16x32_bf16 v[26:29], v[168:171], v[184:187], v[26:29]
	v_mfma_f32_16x16x32_bf16 v[14:17], v[160:163], v[192:195], v[14:17]
	v_mfma_f32_16x16x32_bf16 v[10:13], v[168:171], v[192:195], v[10:13]
	v_mfma_f32_16x16x32_bf16 v[6:9], v[160:163], v[208:211], v[6:9]
	v_mfma_f32_16x16x32_bf16 v[2:5], v[168:171], v[208:211], v[2:5]
	s_barrier
	s_setprio 0
	s_add_i32 s49, s49, 2
	s_add_u32 s40, s40, 0x100
	s_addc_u32 s41, s41, 0
	s_cmp_gt_u32 s49, 5
	s_mov_b64 s[14:15], s[16:17]
	s_cbranch_scc0 .LBB0_1739
	s_and_b64 vcc, exec, s[6:7]
	s_cbranch_vccz .LBB0_1742
	s_barrier
